# pair-B scratch reload issued during select A (after the compaction barrier), U[60..62] staged in v244-v246
# speedup vs baseline: 1.0138x; 1.0029x over previous
.LBB0_532:
	v_mov_b32_e32 v129, v194
	v_readfirstlane_b32 s83, v194
	v_and_b32_e32 v180, 31, v194
	v_bfe_u32 v131, v194, 5, 1
	v_and_b32_e32 v243, 63, v194
	s_ashr_i32 s84, s83, 6
	s_lshl_b32 s0, s84, 5
	v_or_b32_e32 v130, s0, v180
	v_lshlrev_b32_e32 v243, 2, v243
	s_lshl_b32 s0, s2, 17
	s_lshl_b32 s1, s84, 8
	s_add_u32 s0, s0, s1
	s_add_u32 s8, s28, s0
	s_addc_u32 s9, s29, 0
	s_lshl_b32 s21, s84, 12
	s_cmp_lg_u32 s82, 0
	s_cbranch_scc1 .Lix_reload
	s_mov_b32 s100, 0
	v_bfe_u32 v0, v194, 2, 1
	v_lshrrev_b32_e32 v1, 1, v194
	v_and_b32_e32 v1, 12, v1
	v_and_b32_e32 v228, 3, v194
	v_or_b32_e32 v1, v1, v228
	v_add_u32_e32 v0, s34, v0
	v_lshlrev_b32_e32 v0, 11, v0
	v_lshl_add_u32 v0, v1, 7, v0
	v_lshl_add_u32 v0, v131, 4, v0
	v_add_u32_e32 v1, 0x1000, v0
	global_load_dwordx4 v[70:73], v0, s[36:37]
	global_load_dwordx4 v[74:77], v0, s[36:37] offset:32
	global_load_dwordx4 v[78:81], v0, s[36:37] offset:64
	global_load_dwordx4 v[82:85], v0, s[36:37] offset:96
	global_load_dwordx4 v[86:89], v1, s[36:37]
	global_load_dwordx4 v[90:93], v1, s[36:37] offset:32
	global_load_dwordx4 v[94:97], v1, s[36:37] offset:64
	global_load_dwordx4 v[98:101], v1, s[36:37] offset:96
	v_add_u32_e32 v228, s34, v131
	v_lshlrev_b32_e32 v228, 6, v228
	global_load_dwordx4 v[22:25], v228, s[38:39]
	global_load_dwordx4 v[26:29], v228, s[38:39] offset:16
	global_load_dwordx4 v[30:33], v228, s[38:39] offset:32
	global_load_dwordx4 v[34:37], v228, s[38:39] offset:48
	global_load_dwordx2 v[244:245], v228, s[38:39] offset:128
	global_load_dwordx2 v[246:247], v228, s[38:39] offset:136
	global_load_dwordx2 v[248:249], v228, s[38:39] offset:144
	global_load_dwordx2 v[250:251], v228, s[38:39] offset:152
	global_load_dwordx2 v[252:253], v228, s[38:39] offset:160
	global_load_dwordx2 v[254:255], v228, s[38:39] offset:168
	global_load_dwordx2 v[200:201], v228, s[38:39] offset:176
	global_load_dwordx2 v[202:203], v228, s[38:39] offset:184
	v_lshrrev_b32_e32 v0, 2, v243
	v_lshrrev_b32_e32 v1, 3, v0
	v_lshrrev_b32_e32 v228, 4, v0
	v_and_b32_e32 v229, 7, v0
	v_xor_b32_e32 v228, v229, v228
	v_xor_b32_e32 v229, 4, v228
	s_lshl_b32 s0, s84, 12
	v_lshl_add_u32 v1, v1, 7, s0
	v_lshl_add_u32 v102, v228, 4, v1
	v_lshl_add_u32 v110, v229, 4, v1
	v_add_u32_e32 v110, 0x400, v110
	v_add_u32_e32 v112, 0x800, v102
	v_add_u32_e32 v193, 0x800, v110
	v_lshlrev_b32_e32 v0, 7, v130
	v_bfe_u32 v1, v180, 1, 3
	v_or_b32_e32 v228, 0, v131
	v_xor_b32_e32 v228, v228, v1
	v_lshl_add_u32 v5, v228, 4, v0
	v_or_b32_e32 v228, 2, v131
	v_xor_b32_e32 v228, v228, v1
	v_lshl_add_u32 v52, v228, 4, v0
	v_or_b32_e32 v228, 4, v131
	v_xor_b32_e32 v228, v228, v1
	v_lshl_add_u32 v55, v228, 4, v0
	v_or_b32_e32 v228, 6, v131
	v_xor_b32_e32 v228, v228, v1
	v_lshl_add_u32 v56, v228, 4, v0
	s_mov_b32 s6, s14
	s_mov_b32 s7, s15
	s_add_i32 s10, s0, 10496
	s_sub_i32 s11, s35, s84
	s_add_i32 m0, s10, 0
	s_nop 0
	global_load_lds_dwordx4 v102, s[6:7]
	s_add_i32 m0, s10, 1024
	s_nop 0
	global_load_lds_dwordx4 v110, s[6:7]
	s_add_i32 m0, s10, 2048
	s_nop 0
	global_load_lds_dwordx4 v112, s[6:7]
	s_add_i32 m0, s10, 3072
	s_nop 0
	global_load_lds_dwordx4 v193, s[6:7]
	s_add_u32 s6, s6, 0x8000
	s_addc_u32 s7, s7, 0
	s_add_i32 m0, s10, 32768
	s_nop 0
	global_load_lds_dwordx4 v102, s[6:7]
	s_add_i32 m0, s10, 33792
	s_nop 0
	global_load_lds_dwordx4 v110, s[6:7]
	s_add_i32 m0, s10, 34816
	s_nop 0
	global_load_lds_dwordx4 v112, s[6:7]
	s_add_i32 m0, s10, 35840
	s_nop 0
	global_load_lds_dwordx4 v193, s[6:7]
	s_add_u32 s6, s6, 0x8000
	s_addc_u32 s7, s7, 0
	s_add_i32 m0, s10, 65536
	s_nop 0
	global_load_lds_dwordx4 v102, s[6:7]
	s_add_i32 m0, s10, 66560
	s_nop 0
	global_load_lds_dwordx4 v110, s[6:7]
	s_add_i32 m0, s10, 67584
	s_nop 0
	global_load_lds_dwordx4 v112, s[6:7]
	s_add_i32 m0, s10, 68608
	s_nop 0
	global_load_lds_dwordx4 v193, s[6:7]
	s_add_u32 s6, s6, 0x8000
	s_addc_u32 s7, s7, 0
	s_waitcnt vmcnt(8)
	ds_read_b128 v[38:41], v5 offset:10496
	ds_read_b128 v[42:45], v52 offset:10496
	ds_read_b128 v[46:49], v55 offset:10496
	ds_read_b128 v[196:199], v56 offset:10496
	s_waitcnt lgkmcnt(3)
	v_mfma_f32_32x32x16_bf16 v[212:227], v[70:73], v[38:41], 0
	s_add_i32 m0, s10, 98304
	s_nop 0
	global_load_lds_dwordx4 v102, s[6:7]
	s_waitcnt lgkmcnt(2)
	v_mfma_f32_32x32x16_bf16 v[212:227], v[74:77], v[42:45], v[212:227]
	s_add_i32 m0, s10, 99328
	s_nop 0
	global_load_lds_dwordx4 v110, s[6:7]
	s_waitcnt lgkmcnt(1)
	v_mfma_f32_32x32x16_bf16 v[212:227], v[78:81], v[46:49], v[212:227]
	s_add_i32 m0, s10, 100352
	s_nop 0
	global_load_lds_dwordx4 v112, s[6:7]
	s_waitcnt lgkmcnt(0)
	v_mfma_f32_32x32x16_bf16 v[212:227], v[82:85], v[196:199], v[212:227]
	s_add_i32 m0, s10, 101376
	s_nop 0
	global_load_lds_dwordx4 v193, s[6:7]
	s_add_u32 s6, s6, 0x8000
	s_addc_u32 s7, s7, 0
	v_mfma_f32_32x32x16_bf16 v[6:21], v[86:89], v[38:41], 0
	s_nop 7
	s_nop 2
	v_max_f32_e32 v108, 0, v212
	v_max_f32_e32 v109, 0, v213
	v_pk_mul_f32 v[0:1], v[22:23], v[108:109]
	v_max_f32_e32 v210, 0, v214
	v_max_f32_e32 v211, 0, v215
	v_pk_fma_f32 v[0:1], v[24:25], v[210:211], v[0:1]
	v_max_f32_e32 v108, 0, v216
	v_max_f32_e32 v109, 0, v217
	v_pk_fma_f32 v[0:1], v[26:27], v[108:109], v[0:1]
	v_mfma_f32_32x32x16_bf16 v[6:21], v[90:93], v[42:45], v[6:21]
	v_max_f32_e32 v210, 0, v218
	v_max_f32_e32 v211, 0, v219
	v_pk_fma_f32 v[0:1], v[28:29], v[210:211], v[0:1]
	v_max_f32_e32 v108, 0, v220
	v_max_f32_e32 v109, 0, v221
	v_pk_fma_f32 v[0:1], v[30:31], v[108:109], v[0:1]
	v_max_f32_e32 v210, 0, v222
	v_max_f32_e32 v211, 0, v223
	v_pk_fma_f32 v[0:1], v[32:33], v[210:211], v[0:1]
	v_mfma_f32_32x32x16_bf16 v[6:21], v[94:97], v[46:49], v[6:21]
	v_max_f32_e32 v108, 0, v224
	v_max_f32_e32 v109, 0, v225
	v_pk_fma_f32 v[0:1], v[34:35], v[108:109], v[0:1]
	v_max_f32_e32 v210, 0, v226
	v_max_f32_e32 v211, 0, v227
	v_pk_fma_f32 v[0:1], v[36:37], v[210:211], v[0:1]
	v_add_f32_e32 v0, v0, v1
	v_ashrrev_i32_e32 v1, 31, v0
	v_mfma_f32_32x32x16_bf16 v[6:21], v[98:101], v[196:199], v[6:21]
	s_waitcnt vmcnt(8)
	ds_read_b128 v[38:41], v5 offset:43264
	ds_read_b128 v[42:45], v52 offset:43264
	ds_read_b128 v[46:49], v55 offset:43264
	ds_read_b128 v[196:199], v56 offset:43264
	v_or_b32_e32 v1, 0x80000000, v1
	s_cmpk_gt_i32 s11, 0
	s_cselect_b64 vcc, -1, 0
	v_xor_b32_e32 v0, v1, v0
	v_cndmask_b32_e32 v133, v123, v0, vcc
	s_nop 3
	s_waitcnt lgkmcnt(3)
	v_mfma_f32_32x32x16_bf16 v[212:227], v[70:73], v[38:41], 0
	v_max_f32_e32 v108, 0, v6
	v_max_f32_e32 v109, 0, v7
	v_pk_mul_f32 v[50:51], v[244:245], v[108:109]
	v_max_f32_e32 v210, 0, v8
	v_max_f32_e32 v211, 0, v9
	v_pk_fma_f32 v[50:51], v[246:247], v[210:211], v[50:51]
	v_max_f32_e32 v108, 0, v10
	v_max_f32_e32 v109, 0, v11
	v_pk_fma_f32 v[50:51], v[248:249], v[108:109], v[50:51]
	s_waitcnt lgkmcnt(2)
	v_mfma_f32_32x32x16_bf16 v[212:227], v[74:77], v[42:45], v[212:227]
	v_max_f32_e32 v210, 0, v12
	v_max_f32_e32 v211, 0, v13
	v_pk_fma_f32 v[50:51], v[250:251], v[210:211], v[50:51]
	v_max_f32_e32 v108, 0, v14
	v_max_f32_e32 v109, 0, v15
	v_pk_fma_f32 v[50:51], v[252:253], v[108:109], v[50:51]
	v_max_f32_e32 v210, 0, v16
	v_max_f32_e32 v211, 0, v17
	v_pk_fma_f32 v[50:51], v[254:255], v[210:211], v[50:51]
	s_waitcnt lgkmcnt(1)
	v_mfma_f32_32x32x16_bf16 v[212:227], v[78:81], v[46:49], v[212:227]
	v_max_f32_e32 v108, 0, v18
	v_max_f32_e32 v109, 0, v19
	v_pk_fma_f32 v[50:51], v[200:201], v[108:109], v[50:51]
	v_max_f32_e32 v210, 0, v20
	v_max_f32_e32 v211, 0, v21
	v_pk_fma_f32 v[50:51], v[202:203], v[210:211], v[50:51]
	v_add_f32_e32 v50, v50, v51
	v_ashrrev_i32_e32 v51, 31, v50
	s_waitcnt lgkmcnt(0)
	v_mfma_f32_32x32x16_bf16 v[212:227], v[82:85], v[196:199], v[212:227]
	v_or_b32_e32 v51, 0x80000000, v51
	s_cmpk_gt_i32 s11, 0
	s_cselect_b64 vcc, -1, 0
	v_xor_b32_e32 v50, v51, v50
	v_cndmask_b32_e32 v50, v123, v50, vcc
	global_store_dword v243, v50, s[8:9]
	v_mfma_f32_32x32x16_bf16 v[6:21], v[86:89], v[38:41], 0
	s_add_i32 m0, s10, 0
	s_nop 0
	global_load_lds_dwordx4 v102, s[6:7]
	s_add_i32 m0, s10, 1024
	s_nop 0
	global_load_lds_dwordx4 v110, s[6:7]
	s_add_i32 m0, s10, 2048
	s_nop 0
	global_load_lds_dwordx4 v112, s[6:7]
	s_add_i32 m0, s10, 3072
	s_nop 0
	global_load_lds_dwordx4 v193, s[6:7]
	s_add_u32 s6, s6, 0x8000
	s_addc_u32 s7, s7, 0
	v_max_f32_e32 v108, 0, v212
	v_max_f32_e32 v109, 0, v213
	v_pk_mul_f32 v[0:1], v[22:23], v[108:109]
	v_max_f32_e32 v210, 0, v214
	v_max_f32_e32 v211, 0, v215
	v_pk_fma_f32 v[0:1], v[24:25], v[210:211], v[0:1]
	v_max_f32_e32 v108, 0, v216
	v_max_f32_e32 v109, 0, v217
	v_pk_fma_f32 v[0:1], v[26:27], v[108:109], v[0:1]
	v_mfma_f32_32x32x16_bf16 v[6:21], v[90:93], v[42:45], v[6:21]
	v_max_f32_e32 v210, 0, v218
	v_max_f32_e32 v211, 0, v219
	v_pk_fma_f32 v[0:1], v[28:29], v[210:211], v[0:1]
	v_max_f32_e32 v108, 0, v220
	v_max_f32_e32 v109, 0, v221
	v_pk_fma_f32 v[0:1], v[30:31], v[108:109], v[0:1]
	v_max_f32_e32 v210, 0, v222
	v_max_f32_e32 v211, 0, v223
	v_pk_fma_f32 v[0:1], v[32:33], v[210:211], v[0:1]
	v_mfma_f32_32x32x16_bf16 v[6:21], v[94:97], v[46:49], v[6:21]
	v_max_f32_e32 v108, 0, v224
	v_max_f32_e32 v109, 0, v225
	v_pk_fma_f32 v[0:1], v[34:35], v[108:109], v[0:1]
	v_max_f32_e32 v210, 0, v226
	v_max_f32_e32 v211, 0, v227
	v_pk_fma_f32 v[0:1], v[36:37], v[210:211], v[0:1]
	v_add_f32_e32 v0, v0, v1
	v_ashrrev_i32_e32 v1, 31, v0
	v_mfma_f32_32x32x16_bf16 v[6:21], v[98:101], v[196:199], v[6:21]
	s_waitcnt vmcnt(9)
	v_add_u32_e32 v228, 0x10000, v5
	ds_read_b128 v[38:41], v228 offset:10496
	v_add_u32_e32 v228, 0x10000, v52
	ds_read_b128 v[42:45], v228 offset:10496
	v_add_u32_e32 v228, 0x10000, v55
	ds_read_b128 v[46:49], v228 offset:10496
	v_add_u32_e32 v228, 0x10000, v56
	ds_read_b128 v[196:199], v228 offset:10496
	v_or_b32_e32 v1, 0x80000000, v1
	s_cmpk_gt_i32 s11, 8
	s_cselect_b64 vcc, -1, 0
	v_xor_b32_e32 v0, v1, v0
	v_cndmask_b32_e32 v132, v123, v0, vcc
	s_nop 3
	s_waitcnt lgkmcnt(3)
	v_mfma_f32_32x32x16_bf16 v[212:227], v[70:73], v[38:41], 0
	v_max_f32_e32 v108, 0, v6
	v_max_f32_e32 v109, 0, v7
	v_pk_mul_f32 v[50:51], v[244:245], v[108:109]
	v_max_f32_e32 v210, 0, v8
	v_max_f32_e32 v211, 0, v9
	v_pk_fma_f32 v[50:51], v[246:247], v[210:211], v[50:51]
	v_max_f32_e32 v108, 0, v10
	v_max_f32_e32 v109, 0, v11
	v_pk_fma_f32 v[50:51], v[248:249], v[108:109], v[50:51]
	s_waitcnt lgkmcnt(2)
	v_mfma_f32_32x32x16_bf16 v[212:227], v[74:77], v[42:45], v[212:227]
	v_max_f32_e32 v210, 0, v12
	v_max_f32_e32 v211, 0, v13
	v_pk_fma_f32 v[50:51], v[250:251], v[210:211], v[50:51]
	v_max_f32_e32 v108, 0, v14
	v_max_f32_e32 v109, 0, v15
	v_pk_fma_f32 v[50:51], v[252:253], v[108:109], v[50:51]
	v_max_f32_e32 v210, 0, v16
	v_max_f32_e32 v211, 0, v17
	v_pk_fma_f32 v[50:51], v[254:255], v[210:211], v[50:51]
	s_waitcnt lgkmcnt(1)
	v_mfma_f32_32x32x16_bf16 v[212:227], v[78:81], v[46:49], v[212:227]
	v_max_f32_e32 v108, 0, v18
	v_max_f32_e32 v109, 0, v19
	v_pk_fma_f32 v[50:51], v[200:201], v[108:109], v[50:51]
	v_max_f32_e32 v210, 0, v20
	v_max_f32_e32 v211, 0, v21
	v_pk_fma_f32 v[50:51], v[202:203], v[210:211], v[50:51]
	v_add_f32_e32 v50, v50, v51
	v_ashrrev_i32_e32 v51, 31, v50
	s_waitcnt lgkmcnt(0)
	v_mfma_f32_32x32x16_bf16 v[212:227], v[82:85], v[196:199], v[212:227]
	v_or_b32_e32 v51, 0x80000000, v51
	s_cmpk_gt_i32 s11, 8
	s_cselect_b64 vcc, -1, 0
	v_xor_b32_e32 v50, v51, v50
	v_cndmask_b32_e32 v50, v123, v50, vcc
	global_store_dword v243, v50, s[8:9] offset:2048
	s_add_u32 s8, s8, 0x1000
	s_addc_u32 s9, s9, 0
	v_mfma_f32_32x32x16_bf16 v[6:21], v[86:89], v[38:41], 0
	s_add_i32 m0, s10, 32768
	s_nop 0
	global_load_lds_dwordx4 v102, s[6:7]
	s_add_i32 m0, s10, 33792
	s_nop 0
	global_load_lds_dwordx4 v110, s[6:7]
	s_add_i32 m0, s10, 34816
	s_nop 0
	global_load_lds_dwordx4 v112, s[6:7]
	s_add_i32 m0, s10, 35840
	s_nop 0
	global_load_lds_dwordx4 v193, s[6:7]
	s_add_u32 s6, s6, 0x8000
	s_addc_u32 s7, s7, 0
	v_max_f32_e32 v108, 0, v212
	v_max_f32_e32 v109, 0, v213
	v_pk_mul_f32 v[0:1], v[22:23], v[108:109]
	v_max_f32_e32 v210, 0, v214
	v_max_f32_e32 v211, 0, v215
	v_pk_fma_f32 v[0:1], v[24:25], v[210:211], v[0:1]
	v_max_f32_e32 v108, 0, v216
	v_max_f32_e32 v109, 0, v217
	v_pk_fma_f32 v[0:1], v[26:27], v[108:109], v[0:1]
	v_mfma_f32_32x32x16_bf16 v[6:21], v[90:93], v[42:45], v[6:21]
	v_max_f32_e32 v210, 0, v218
	v_max_f32_e32 v211, 0, v219
	v_pk_fma_f32 v[0:1], v[28:29], v[210:211], v[0:1]
	v_max_f32_e32 v108, 0, v220
	v_max_f32_e32 v109, 0, v221
	v_pk_fma_f32 v[0:1], v[30:31], v[108:109], v[0:1]
	v_max_f32_e32 v210, 0, v222
	v_max_f32_e32 v211, 0, v223
	v_pk_fma_f32 v[0:1], v[32:33], v[210:211], v[0:1]
	v_mfma_f32_32x32x16_bf16 v[6:21], v[94:97], v[46:49], v[6:21]
	v_max_f32_e32 v108, 0, v224
	v_max_f32_e32 v109, 0, v225
	v_pk_fma_f32 v[0:1], v[34:35], v[108:109], v[0:1]
	v_max_f32_e32 v210, 0, v226
	v_max_f32_e32 v211, 0, v227
	v_pk_fma_f32 v[0:1], v[36:37], v[210:211], v[0:1]
	v_add_f32_e32 v0, v0, v1
	v_ashrrev_i32_e32 v1, 31, v0
	v_mfma_f32_32x32x16_bf16 v[6:21], v[98:101], v[196:199], v[6:21]
	s_waitcnt vmcnt(10)
	v_add_u32_e32 v228, 0x10000, v5
	ds_read_b128 v[38:41], v228 offset:43264
	v_add_u32_e32 v228, 0x10000, v52
	ds_read_b128 v[42:45], v228 offset:43264
	v_add_u32_e32 v228, 0x10000, v55
	ds_read_b128 v[46:49], v228 offset:43264
	v_add_u32_e32 v228, 0x10000, v56
	ds_read_b128 v[196:199], v228 offset:43264
	v_or_b32_e32 v1, 0x80000000, v1
	s_cmpk_gt_i32 s11, 16
	s_cselect_b64 vcc, -1, 0
	v_xor_b32_e32 v0, v1, v0
	v_cndmask_b32_e32 v135, v123, v0, vcc
	s_nop 3
	s_waitcnt lgkmcnt(3)
	v_mfma_f32_32x32x16_bf16 v[212:227], v[70:73], v[38:41], 0
	v_max_f32_e32 v108, 0, v6
	v_max_f32_e32 v109, 0, v7
	v_pk_mul_f32 v[50:51], v[244:245], v[108:109]
	v_max_f32_e32 v210, 0, v8
	v_max_f32_e32 v211, 0, v9
	v_pk_fma_f32 v[50:51], v[246:247], v[210:211], v[50:51]
	v_max_f32_e32 v108, 0, v10
	v_max_f32_e32 v109, 0, v11
	v_pk_fma_f32 v[50:51], v[248:249], v[108:109], v[50:51]
	s_waitcnt lgkmcnt(2)
	v_mfma_f32_32x32x16_bf16 v[212:227], v[74:77], v[42:45], v[212:227]
	v_max_f32_e32 v210, 0, v12
	v_max_f32_e32 v211, 0, v13
	v_pk_fma_f32 v[50:51], v[250:251], v[210:211], v[50:51]
	v_max_f32_e32 v108, 0, v14
	v_max_f32_e32 v109, 0, v15
	v_pk_fma_f32 v[50:51], v[252:253], v[108:109], v[50:51]
	v_max_f32_e32 v210, 0, v16
	v_max_f32_e32 v211, 0, v17
	v_pk_fma_f32 v[50:51], v[254:255], v[210:211], v[50:51]
	s_waitcnt lgkmcnt(1)
	v_mfma_f32_32x32x16_bf16 v[212:227], v[78:81], v[46:49], v[212:227]
	v_max_f32_e32 v108, 0, v18
	v_max_f32_e32 v109, 0, v19
	v_pk_fma_f32 v[50:51], v[200:201], v[108:109], v[50:51]
	v_max_f32_e32 v210, 0, v20
	v_max_f32_e32 v211, 0, v21
	v_pk_fma_f32 v[50:51], v[202:203], v[210:211], v[50:51]
	v_add_f32_e32 v50, v50, v51
	v_ashrrev_i32_e32 v51, 31, v50
	s_waitcnt lgkmcnt(0)
	v_mfma_f32_32x32x16_bf16 v[212:227], v[82:85], v[196:199], v[212:227]
	v_or_b32_e32 v51, 0x80000000, v51
	s_cmpk_gt_i32 s11, 16
	s_cselect_b64 vcc, -1, 0
	v_xor_b32_e32 v50, v51, v50
	v_cndmask_b32_e32 v50, v123, v50, vcc
	global_store_dword v243, v50, s[8:9]
	v_mfma_f32_32x32x16_bf16 v[6:21], v[86:89], v[38:41], 0
	s_add_i32 m0, s10, 65536
	s_nop 0
	global_load_lds_dwordx4 v102, s[6:7]
	s_add_i32 m0, s10, 66560
	s_nop 0
	global_load_lds_dwordx4 v110, s[6:7]
	s_add_i32 m0, s10, 67584
	s_nop 0
	global_load_lds_dwordx4 v112, s[6:7]
	s_add_i32 m0, s10, 68608
	s_nop 0
	global_load_lds_dwordx4 v193, s[6:7]
	s_add_u32 s6, s6, 0x8000
	s_addc_u32 s7, s7, 0
	v_max_f32_e32 v108, 0, v212
	v_max_f32_e32 v109, 0, v213
	v_pk_mul_f32 v[0:1], v[22:23], v[108:109]
	v_max_f32_e32 v210, 0, v214
	v_max_f32_e32 v211, 0, v215
	v_pk_fma_f32 v[0:1], v[24:25], v[210:211], v[0:1]
	v_max_f32_e32 v108, 0, v216
	v_max_f32_e32 v109, 0, v217
	v_pk_fma_f32 v[0:1], v[26:27], v[108:109], v[0:1]
	v_mfma_f32_32x32x16_bf16 v[6:21], v[90:93], v[42:45], v[6:21]
	v_max_f32_e32 v210, 0, v218
	v_max_f32_e32 v211, 0, v219
	v_pk_fma_f32 v[0:1], v[28:29], v[210:211], v[0:1]
	v_max_f32_e32 v108, 0, v220
	v_max_f32_e32 v109, 0, v221
	v_pk_fma_f32 v[0:1], v[30:31], v[108:109], v[0:1]
	v_max_f32_e32 v210, 0, v222
	v_max_f32_e32 v211, 0, v223
	v_pk_fma_f32 v[0:1], v[32:33], v[210:211], v[0:1]
	v_mfma_f32_32x32x16_bf16 v[6:21], v[94:97], v[46:49], v[6:21]
	v_max_f32_e32 v108, 0, v224
	v_max_f32_e32 v109, 0, v225
	v_pk_fma_f32 v[0:1], v[34:35], v[108:109], v[0:1]
	v_max_f32_e32 v210, 0, v226
	v_max_f32_e32 v211, 0, v227
	v_pk_fma_f32 v[0:1], v[36:37], v[210:211], v[0:1]
	v_add_f32_e32 v0, v0, v1
	v_ashrrev_i32_e32 v1, 31, v0
	v_mfma_f32_32x32x16_bf16 v[6:21], v[98:101], v[196:199], v[6:21]
	s_waitcnt vmcnt(10)
	ds_read_b128 v[38:41], v5 offset:10496
	ds_read_b128 v[42:45], v52 offset:10496
	ds_read_b128 v[46:49], v55 offset:10496
	ds_read_b128 v[196:199], v56 offset:10496
	v_or_b32_e32 v1, 0x80000000, v1
	s_cmpk_gt_i32 s11, 24
	s_cselect_b64 vcc, -1, 0
	v_xor_b32_e32 v0, v1, v0
	v_cndmask_b32_e32 v134, v123, v0, vcc
	s_nop 3
	s_waitcnt lgkmcnt(3)
	v_mfma_f32_32x32x16_bf16 v[212:227], v[70:73], v[38:41], 0
	v_max_f32_e32 v108, 0, v6
	v_max_f32_e32 v109, 0, v7
	v_pk_mul_f32 v[50:51], v[244:245], v[108:109]
	v_max_f32_e32 v210, 0, v8
	v_max_f32_e32 v211, 0, v9
	v_pk_fma_f32 v[50:51], v[246:247], v[210:211], v[50:51]
	v_max_f32_e32 v108, 0, v10
	v_max_f32_e32 v109, 0, v11
	v_pk_fma_f32 v[50:51], v[248:249], v[108:109], v[50:51]
	s_waitcnt lgkmcnt(2)
	v_mfma_f32_32x32x16_bf16 v[212:227], v[74:77], v[42:45], v[212:227]
	v_max_f32_e32 v210, 0, v12
	v_max_f32_e32 v211, 0, v13
	v_pk_fma_f32 v[50:51], v[250:251], v[210:211], v[50:51]
	v_max_f32_e32 v108, 0, v14
	v_max_f32_e32 v109, 0, v15
	v_pk_fma_f32 v[50:51], v[252:253], v[108:109], v[50:51]
	v_max_f32_e32 v210, 0, v16
	v_max_f32_e32 v211, 0, v17
	v_pk_fma_f32 v[50:51], v[254:255], v[210:211], v[50:51]
	s_waitcnt lgkmcnt(1)
	v_mfma_f32_32x32x16_bf16 v[212:227], v[78:81], v[46:49], v[212:227]
	v_max_f32_e32 v108, 0, v18
	v_max_f32_e32 v109, 0, v19
	v_pk_fma_f32 v[50:51], v[200:201], v[108:109], v[50:51]
	v_max_f32_e32 v210, 0, v20
	v_max_f32_e32 v211, 0, v21
	v_pk_fma_f32 v[50:51], v[202:203], v[210:211], v[50:51]
	v_add_f32_e32 v50, v50, v51
	v_ashrrev_i32_e32 v51, 31, v50
	s_waitcnt lgkmcnt(0)
	v_mfma_f32_32x32x16_bf16 v[212:227], v[82:85], v[196:199], v[212:227]
	v_or_b32_e32 v51, 0x80000000, v51
	s_cmpk_gt_i32 s11, 24
	s_cselect_b64 vcc, -1, 0
	v_xor_b32_e32 v50, v51, v50
	v_cndmask_b32_e32 v50, v123, v50, vcc
	global_store_dword v243, v50, s[8:9] offset:2048
	s_add_u32 s8, s8, 0x1000
	s_addc_u32 s9, s9, 0
	v_mfma_f32_32x32x16_bf16 v[6:21], v[86:89], v[38:41], 0
	s_add_i32 m0, s10, 98304
	s_nop 0
	global_load_lds_dwordx4 v102, s[6:7]
	s_add_i32 m0, s10, 99328
	s_nop 0
	global_load_lds_dwordx4 v110, s[6:7]
	s_add_i32 m0, s10, 100352
	s_nop 0
	global_load_lds_dwordx4 v112, s[6:7]
	s_add_i32 m0, s10, 101376
	s_nop 0
	global_load_lds_dwordx4 v193, s[6:7]
	s_add_u32 s6, s6, 0x8000
	s_addc_u32 s7, s7, 0
	v_max_f32_e32 v108, 0, v212
	v_max_f32_e32 v109, 0, v213
	v_pk_mul_f32 v[0:1], v[22:23], v[108:109]
	v_max_f32_e32 v210, 0, v214
	v_max_f32_e32 v211, 0, v215
	v_pk_fma_f32 v[0:1], v[24:25], v[210:211], v[0:1]
	v_max_f32_e32 v108, 0, v216
	v_max_f32_e32 v109, 0, v217
	v_pk_fma_f32 v[0:1], v[26:27], v[108:109], v[0:1]
	v_mfma_f32_32x32x16_bf16 v[6:21], v[90:93], v[42:45], v[6:21]
	v_max_f32_e32 v210, 0, v218
	v_max_f32_e32 v211, 0, v219
	v_pk_fma_f32 v[0:1], v[28:29], v[210:211], v[0:1]
	v_max_f32_e32 v108, 0, v220
	v_max_f32_e32 v109, 0, v221
	v_pk_fma_f32 v[0:1], v[30:31], v[108:109], v[0:1]
	v_max_f32_e32 v210, 0, v222
	v_max_f32_e32 v211, 0, v223
	v_pk_fma_f32 v[0:1], v[32:33], v[210:211], v[0:1]
	v_mfma_f32_32x32x16_bf16 v[6:21], v[94:97], v[46:49], v[6:21]
	v_max_f32_e32 v108, 0, v224
	v_max_f32_e32 v109, 0, v225
	v_pk_fma_f32 v[0:1], v[34:35], v[108:109], v[0:1]
	v_max_f32_e32 v210, 0, v226
	v_max_f32_e32 v211, 0, v227
	v_pk_fma_f32 v[0:1], v[36:37], v[210:211], v[0:1]
	v_add_f32_e32 v0, v0, v1
	v_ashrrev_i32_e32 v1, 31, v0
	v_mfma_f32_32x32x16_bf16 v[6:21], v[98:101], v[196:199], v[6:21]
	s_waitcnt vmcnt(10)
	ds_read_b128 v[38:41], v5 offset:43264
	ds_read_b128 v[42:45], v52 offset:43264
	ds_read_b128 v[46:49], v55 offset:43264
	ds_read_b128 v[196:199], v56 offset:43264
	v_or_b32_e32 v1, 0x80000000, v1
	s_cmpk_gt_i32 s11, 32
	s_cselect_b64 vcc, -1, 0
	v_xor_b32_e32 v0, v1, v0
	v_cndmask_b32_e32 v138, v123, v0, vcc
	s_nop 3
	s_waitcnt lgkmcnt(3)
	v_mfma_f32_32x32x16_bf16 v[212:227], v[70:73], v[38:41], 0
	v_max_f32_e32 v108, 0, v6
	v_max_f32_e32 v109, 0, v7
	v_pk_mul_f32 v[50:51], v[244:245], v[108:109]
	v_max_f32_e32 v210, 0, v8
	v_max_f32_e32 v211, 0, v9
	v_pk_fma_f32 v[50:51], v[246:247], v[210:211], v[50:51]
	v_max_f32_e32 v108, 0, v10
	v_max_f32_e32 v109, 0, v11
	v_pk_fma_f32 v[50:51], v[248:249], v[108:109], v[50:51]
	s_waitcnt lgkmcnt(2)
	v_mfma_f32_32x32x16_bf16 v[212:227], v[74:77], v[42:45], v[212:227]
	v_max_f32_e32 v210, 0, v12
	v_max_f32_e32 v211, 0, v13
	v_pk_fma_f32 v[50:51], v[250:251], v[210:211], v[50:51]
	v_max_f32_e32 v108, 0, v14
	v_max_f32_e32 v109, 0, v15
	v_pk_fma_f32 v[50:51], v[252:253], v[108:109], v[50:51]
	v_max_f32_e32 v210, 0, v16
	v_max_f32_e32 v211, 0, v17
	v_pk_fma_f32 v[50:51], v[254:255], v[210:211], v[50:51]
	s_waitcnt lgkmcnt(1)
	v_mfma_f32_32x32x16_bf16 v[212:227], v[78:81], v[46:49], v[212:227]
	v_max_f32_e32 v108, 0, v18
	v_max_f32_e32 v109, 0, v19
	v_pk_fma_f32 v[50:51], v[200:201], v[108:109], v[50:51]
	v_max_f32_e32 v210, 0, v20
	v_max_f32_e32 v211, 0, v21
	v_pk_fma_f32 v[50:51], v[202:203], v[210:211], v[50:51]
	v_add_f32_e32 v50, v50, v51
	v_ashrrev_i32_e32 v51, 31, v50
	s_waitcnt lgkmcnt(0)
	v_mfma_f32_32x32x16_bf16 v[212:227], v[82:85], v[196:199], v[212:227]
	v_or_b32_e32 v51, 0x80000000, v51
	s_cmpk_gt_i32 s11, 32
	s_cselect_b64 vcc, -1, 0
	v_xor_b32_e32 v50, v51, v50
	v_cndmask_b32_e32 v50, v123, v50, vcc
	global_store_dword v243, v50, s[8:9]
	v_mfma_f32_32x32x16_bf16 v[6:21], v[86:89], v[38:41], 0
	s_add_i32 m0, s10, 0
	s_nop 0
	global_load_lds_dwordx4 v102, s[6:7]
	s_add_i32 m0, s10, 1024
	s_nop 0
	global_load_lds_dwordx4 v110, s[6:7]
	s_add_i32 m0, s10, 2048
	s_nop 0
	global_load_lds_dwordx4 v112, s[6:7]
	s_add_i32 m0, s10, 3072
	s_nop 0
	global_load_lds_dwordx4 v193, s[6:7]
	s_add_u32 s6, s6, 0x8000
	s_addc_u32 s7, s7, 0
	v_max_f32_e32 v108, 0, v212
	v_max_f32_e32 v109, 0, v213
	v_pk_mul_f32 v[0:1], v[22:23], v[108:109]
	v_max_f32_e32 v210, 0, v214
	v_max_f32_e32 v211, 0, v215
	v_pk_fma_f32 v[0:1], v[24:25], v[210:211], v[0:1]
	v_max_f32_e32 v108, 0, v216
	v_max_f32_e32 v109, 0, v217
	v_pk_fma_f32 v[0:1], v[26:27], v[108:109], v[0:1]
	v_mfma_f32_32x32x16_bf16 v[6:21], v[90:93], v[42:45], v[6:21]
	v_max_f32_e32 v210, 0, v218
	v_max_f32_e32 v211, 0, v219
	v_pk_fma_f32 v[0:1], v[28:29], v[210:211], v[0:1]
	v_max_f32_e32 v108, 0, v220
	v_max_f32_e32 v109, 0, v221
	v_pk_fma_f32 v[0:1], v[30:31], v[108:109], v[0:1]
	v_max_f32_e32 v210, 0, v222
	v_max_f32_e32 v211, 0, v223
	v_pk_fma_f32 v[0:1], v[32:33], v[210:211], v[0:1]
	v_mfma_f32_32x32x16_bf16 v[6:21], v[94:97], v[46:49], v[6:21]
	v_max_f32_e32 v108, 0, v224
	v_max_f32_e32 v109, 0, v225
	v_pk_fma_f32 v[0:1], v[34:35], v[108:109], v[0:1]
	v_max_f32_e32 v210, 0, v226
	v_max_f32_e32 v211, 0, v227
	v_pk_fma_f32 v[0:1], v[36:37], v[210:211], v[0:1]
	v_add_f32_e32 v0, v0, v1
	v_ashrrev_i32_e32 v1, 31, v0
	v_mfma_f32_32x32x16_bf16 v[6:21], v[98:101], v[196:199], v[6:21]
	s_waitcnt vmcnt(10)
	v_add_u32_e32 v228, 0x10000, v5
	ds_read_b128 v[38:41], v228 offset:10496
	v_add_u32_e32 v228, 0x10000, v52
	ds_read_b128 v[42:45], v228 offset:10496
	v_add_u32_e32 v228, 0x10000, v55
	ds_read_b128 v[46:49], v228 offset:10496
	v_add_u32_e32 v228, 0x10000, v56
	ds_read_b128 v[196:199], v228 offset:10496
	v_or_b32_e32 v1, 0x80000000, v1
	s_cmpk_gt_i32 s11, 40
	s_cselect_b64 vcc, -1, 0
	v_xor_b32_e32 v0, v1, v0
	v_cndmask_b32_e32 v137, v123, v0, vcc
	s_nop 3
	s_waitcnt lgkmcnt(3)
	v_mfma_f32_32x32x16_bf16 v[212:227], v[70:73], v[38:41], 0
	v_max_f32_e32 v108, 0, v6
	v_max_f32_e32 v109, 0, v7
	v_pk_mul_f32 v[50:51], v[244:245], v[108:109]
	v_max_f32_e32 v210, 0, v8
	v_max_f32_e32 v211, 0, v9
	v_pk_fma_f32 v[50:51], v[246:247], v[210:211], v[50:51]
	v_max_f32_e32 v108, 0, v10
	v_max_f32_e32 v109, 0, v11
	v_pk_fma_f32 v[50:51], v[248:249], v[108:109], v[50:51]
	s_waitcnt lgkmcnt(2)
	v_mfma_f32_32x32x16_bf16 v[212:227], v[74:77], v[42:45], v[212:227]
	v_max_f32_e32 v210, 0, v12
	v_max_f32_e32 v211, 0, v13
	v_pk_fma_f32 v[50:51], v[250:251], v[210:211], v[50:51]
	v_max_f32_e32 v108, 0, v14
	v_max_f32_e32 v109, 0, v15
	v_pk_fma_f32 v[50:51], v[252:253], v[108:109], v[50:51]
	v_max_f32_e32 v210, 0, v16
	v_max_f32_e32 v211, 0, v17
	v_pk_fma_f32 v[50:51], v[254:255], v[210:211], v[50:51]
	s_waitcnt lgkmcnt(1)
	v_mfma_f32_32x32x16_bf16 v[212:227], v[78:81], v[46:49], v[212:227]
	v_max_f32_e32 v108, 0, v18
	v_max_f32_e32 v109, 0, v19
	v_pk_fma_f32 v[50:51], v[200:201], v[108:109], v[50:51]
	v_max_f32_e32 v210, 0, v20
	v_max_f32_e32 v211, 0, v21
	v_pk_fma_f32 v[50:51], v[202:203], v[210:211], v[50:51]
	v_add_f32_e32 v50, v50, v51
	v_ashrrev_i32_e32 v51, 31, v50
	s_waitcnt lgkmcnt(0)
	v_mfma_f32_32x32x16_bf16 v[212:227], v[82:85], v[196:199], v[212:227]
	v_or_b32_e32 v51, 0x80000000, v51
	s_cmpk_gt_i32 s11, 40
	s_cselect_b64 vcc, -1, 0
	v_xor_b32_e32 v50, v51, v50
	v_cndmask_b32_e32 v50, v123, v50, vcc
	global_store_dword v243, v50, s[8:9] offset:2048
	s_add_u32 s8, s8, 0x1000
	s_addc_u32 s9, s9, 0
	v_mfma_f32_32x32x16_bf16 v[6:21], v[86:89], v[38:41], 0
	s_add_i32 m0, s10, 32768
	s_nop 0
	global_load_lds_dwordx4 v102, s[6:7]
	s_add_i32 m0, s10, 33792
	s_nop 0
	global_load_lds_dwordx4 v110, s[6:7]
	s_add_i32 m0, s10, 34816
	s_nop 0
	global_load_lds_dwordx4 v112, s[6:7]
	s_add_i32 m0, s10, 35840
	s_nop 0
	global_load_lds_dwordx4 v193, s[6:7]
	s_add_u32 s6, s6, 0x8000
	s_addc_u32 s7, s7, 0
	v_max_f32_e32 v108, 0, v212
	v_max_f32_e32 v109, 0, v213
	v_pk_mul_f32 v[0:1], v[22:23], v[108:109]
	v_max_f32_e32 v210, 0, v214
	v_max_f32_e32 v211, 0, v215
	v_pk_fma_f32 v[0:1], v[24:25], v[210:211], v[0:1]
	v_max_f32_e32 v108, 0, v216
	v_max_f32_e32 v109, 0, v217
	v_pk_fma_f32 v[0:1], v[26:27], v[108:109], v[0:1]
	v_mfma_f32_32x32x16_bf16 v[6:21], v[90:93], v[42:45], v[6:21]
	v_max_f32_e32 v210, 0, v218
	v_max_f32_e32 v211, 0, v219
	v_pk_fma_f32 v[0:1], v[28:29], v[210:211], v[0:1]
	v_max_f32_e32 v108, 0, v220
	v_max_f32_e32 v109, 0, v221
	v_pk_fma_f32 v[0:1], v[30:31], v[108:109], v[0:1]
	v_max_f32_e32 v210, 0, v222
	v_max_f32_e32 v211, 0, v223
	v_pk_fma_f32 v[0:1], v[32:33], v[210:211], v[0:1]
	v_mfma_f32_32x32x16_bf16 v[6:21], v[94:97], v[46:49], v[6:21]
	v_max_f32_e32 v108, 0, v224
	v_max_f32_e32 v109, 0, v225
	v_pk_fma_f32 v[0:1], v[34:35], v[108:109], v[0:1]
	v_max_f32_e32 v210, 0, v226
	v_max_f32_e32 v211, 0, v227
	v_pk_fma_f32 v[0:1], v[36:37], v[210:211], v[0:1]
	v_add_f32_e32 v0, v0, v1
	v_ashrrev_i32_e32 v1, 31, v0
	v_mfma_f32_32x32x16_bf16 v[6:21], v[98:101], v[196:199], v[6:21]
	s_waitcnt vmcnt(10)
	v_add_u32_e32 v228, 0x10000, v5
	ds_read_b128 v[38:41], v228 offset:43264
	v_add_u32_e32 v228, 0x10000, v52
	ds_read_b128 v[42:45], v228 offset:43264
	v_add_u32_e32 v228, 0x10000, v55
	ds_read_b128 v[46:49], v228 offset:43264
	v_add_u32_e32 v228, 0x10000, v56
	ds_read_b128 v[196:199], v228 offset:43264
	v_or_b32_e32 v1, 0x80000000, v1
	s_cmpk_gt_i32 s11, 48
	s_cselect_b64 vcc, -1, 0
	v_xor_b32_e32 v0, v1, v0
	v_cndmask_b32_e32 v140, v123, v0, vcc
	s_nop 3
	s_waitcnt lgkmcnt(3)
	v_mfma_f32_32x32x16_bf16 v[212:227], v[70:73], v[38:41], 0
	v_max_f32_e32 v108, 0, v6
	v_max_f32_e32 v109, 0, v7
	v_pk_mul_f32 v[50:51], v[244:245], v[108:109]
	v_max_f32_e32 v210, 0, v8
	v_max_f32_e32 v211, 0, v9
	v_pk_fma_f32 v[50:51], v[246:247], v[210:211], v[50:51]
	v_max_f32_e32 v108, 0, v10
	v_max_f32_e32 v109, 0, v11
	v_pk_fma_f32 v[50:51], v[248:249], v[108:109], v[50:51]
	s_waitcnt lgkmcnt(2)
	v_mfma_f32_32x32x16_bf16 v[212:227], v[74:77], v[42:45], v[212:227]
	v_max_f32_e32 v210, 0, v12
	v_max_f32_e32 v211, 0, v13
	v_pk_fma_f32 v[50:51], v[250:251], v[210:211], v[50:51]
	v_max_f32_e32 v108, 0, v14
	v_max_f32_e32 v109, 0, v15
	v_pk_fma_f32 v[50:51], v[252:253], v[108:109], v[50:51]
	v_max_f32_e32 v210, 0, v16
	v_max_f32_e32 v211, 0, v17
	v_pk_fma_f32 v[50:51], v[254:255], v[210:211], v[50:51]
	s_waitcnt lgkmcnt(1)
	v_mfma_f32_32x32x16_bf16 v[212:227], v[78:81], v[46:49], v[212:227]
	v_max_f32_e32 v108, 0, v18
	v_max_f32_e32 v109, 0, v19
	v_pk_fma_f32 v[50:51], v[200:201], v[108:109], v[50:51]
	v_max_f32_e32 v210, 0, v20
	v_max_f32_e32 v211, 0, v21
	v_pk_fma_f32 v[50:51], v[202:203], v[210:211], v[50:51]
	v_add_f32_e32 v50, v50, v51
	v_ashrrev_i32_e32 v51, 31, v50
	s_waitcnt lgkmcnt(0)
	v_mfma_f32_32x32x16_bf16 v[212:227], v[82:85], v[196:199], v[212:227]
	v_or_b32_e32 v51, 0x80000000, v51
	s_cmpk_gt_i32 s11, 48
	s_cselect_b64 vcc, -1, 0
	v_xor_b32_e32 v50, v51, v50
	v_cndmask_b32_e32 v50, v123, v50, vcc
	global_store_dword v243, v50, s[8:9]
	v_mfma_f32_32x32x16_bf16 v[6:21], v[86:89], v[38:41], 0
	s_add_i32 m0, s10, 65536
	s_nop 0
	global_load_lds_dwordx4 v102, s[6:7]
	s_add_i32 m0, s10, 66560
	s_nop 0
	global_load_lds_dwordx4 v110, s[6:7]
	s_add_i32 m0, s10, 67584
	s_nop 0
	global_load_lds_dwordx4 v112, s[6:7]
	s_add_i32 m0, s10, 68608
	s_nop 0
	global_load_lds_dwordx4 v193, s[6:7]
	s_add_u32 s6, s6, 0x8000
	s_addc_u32 s7, s7, 0
	v_max_f32_e32 v108, 0, v212
	v_max_f32_e32 v109, 0, v213
	v_pk_mul_f32 v[0:1], v[22:23], v[108:109]
	v_max_f32_e32 v210, 0, v214
	v_max_f32_e32 v211, 0, v215
	v_pk_fma_f32 v[0:1], v[24:25], v[210:211], v[0:1]
	v_max_f32_e32 v108, 0, v216
	v_max_f32_e32 v109, 0, v217
	v_pk_fma_f32 v[0:1], v[26:27], v[108:109], v[0:1]
	v_mfma_f32_32x32x16_bf16 v[6:21], v[90:93], v[42:45], v[6:21]
	v_max_f32_e32 v210, 0, v218
	v_max_f32_e32 v211, 0, v219
	v_pk_fma_f32 v[0:1], v[28:29], v[210:211], v[0:1]
	v_max_f32_e32 v108, 0, v220
	v_max_f32_e32 v109, 0, v221
	v_pk_fma_f32 v[0:1], v[30:31], v[108:109], v[0:1]
	v_max_f32_e32 v210, 0, v222
	v_max_f32_e32 v211, 0, v223
	v_pk_fma_f32 v[0:1], v[32:33], v[210:211], v[0:1]
	v_mfma_f32_32x32x16_bf16 v[6:21], v[94:97], v[46:49], v[6:21]
	v_max_f32_e32 v108, 0, v224
	v_max_f32_e32 v109, 0, v225
	v_pk_fma_f32 v[0:1], v[34:35], v[108:109], v[0:1]
	v_max_f32_e32 v210, 0, v226
	v_max_f32_e32 v211, 0, v227
	v_pk_fma_f32 v[0:1], v[36:37], v[210:211], v[0:1]
	v_add_f32_e32 v0, v0, v1
	v_ashrrev_i32_e32 v1, 31, v0
	v_mfma_f32_32x32x16_bf16 v[6:21], v[98:101], v[196:199], v[6:21]
	s_waitcnt vmcnt(10)
	ds_read_b128 v[38:41], v5 offset:10496
	ds_read_b128 v[42:45], v52 offset:10496
	ds_read_b128 v[46:49], v55 offset:10496
	ds_read_b128 v[196:199], v56 offset:10496
	v_or_b32_e32 v1, 0x80000000, v1
	s_cmpk_gt_i32 s11, 56
	s_cselect_b64 vcc, -1, 0
	v_xor_b32_e32 v0, v1, v0
	v_cndmask_b32_e32 v139, v123, v0, vcc
	s_nop 3
	v_max_f32_e32 v108, 0, v6
	v_max_f32_e32 v109, 0, v7
	v_pk_mul_f32 v[50:51], v[244:245], v[108:109]
	v_max_f32_e32 v210, 0, v8
	v_max_f32_e32 v211, 0, v9
	v_pk_fma_f32 v[50:51], v[246:247], v[210:211], v[50:51]
	v_max_f32_e32 v108, 0, v10
	v_max_f32_e32 v109, 0, v11
	v_pk_fma_f32 v[50:51], v[248:249], v[108:109], v[50:51]
	v_max_f32_e32 v210, 0, v12
	v_max_f32_e32 v211, 0, v13
	v_pk_fma_f32 v[50:51], v[250:251], v[210:211], v[50:51]
	v_max_f32_e32 v108, 0, v14
	v_max_f32_e32 v109, 0, v15
	v_pk_fma_f32 v[50:51], v[252:253], v[108:109], v[50:51]
	v_max_f32_e32 v210, 0, v16
	v_max_f32_e32 v211, 0, v17
	v_pk_fma_f32 v[50:51], v[254:255], v[210:211], v[50:51]
	v_max_f32_e32 v108, 0, v18
	v_max_f32_e32 v109, 0, v19
	v_pk_fma_f32 v[50:51], v[200:201], v[108:109], v[50:51]
	v_max_f32_e32 v210, 0, v20
	v_max_f32_e32 v211, 0, v21
	v_pk_fma_f32 v[50:51], v[202:203], v[210:211], v[50:51]
	v_add_f32_e32 v50, v50, v51
	v_ashrrev_i32_e32 v51, 31, v50
	v_or_b32_e32 v51, 0x80000000, v51
	s_cmpk_gt_i32 s11, 56
	s_cselect_b64 vcc, -1, 0
	v_xor_b32_e32 v50, v51, v50
	v_cndmask_b32_e32 v50, v123, v50, vcc
	global_store_dword v243, v50, s[8:9] offset:2048
	s_add_u32 s8, s8, 0x1000
	s_addc_u32 s9, s9, 0
	s_cmpk_gt_i32 s81, 8
	s_cbranch_scc0 .Lix_fill_1
	s_waitcnt lgkmcnt(3)
	v_mfma_f32_32x32x16_bf16 v[212:227], v[70:73], v[38:41], 0
	s_add_i32 m0, s10, 98304
	s_nop 0
	global_load_lds_dwordx4 v102, s[6:7]
	s_waitcnt lgkmcnt(2)
	v_mfma_f32_32x32x16_bf16 v[212:227], v[74:77], v[42:45], v[212:227]
	s_add_i32 m0, s10, 99328
	s_nop 0
	global_load_lds_dwordx4 v110, s[6:7]
	s_waitcnt lgkmcnt(1)
	v_mfma_f32_32x32x16_bf16 v[212:227], v[78:81], v[46:49], v[212:227]
	s_add_i32 m0, s10, 100352
	s_nop 0
	global_load_lds_dwordx4 v112, s[6:7]
	s_waitcnt lgkmcnt(0)
	v_mfma_f32_32x32x16_bf16 v[212:227], v[82:85], v[196:199], v[212:227]
	s_add_i32 m0, s10, 101376
	s_nop 0
	global_load_lds_dwordx4 v193, s[6:7]
	s_add_u32 s6, s6, 0x8000
	s_addc_u32 s7, s7, 0
	v_mfma_f32_32x32x16_bf16 v[6:21], v[86:89], v[38:41], 0
	s_nop 7
	s_nop 2
	v_max_f32_e32 v108, 0, v212
	v_max_f32_e32 v109, 0, v213
	v_pk_mul_f32 v[0:1], v[22:23], v[108:109]
	v_max_f32_e32 v210, 0, v214
	v_max_f32_e32 v211, 0, v215
	v_pk_fma_f32 v[0:1], v[24:25], v[210:211], v[0:1]
	v_max_f32_e32 v108, 0, v216
	v_max_f32_e32 v109, 0, v217
	v_pk_fma_f32 v[0:1], v[26:27], v[108:109], v[0:1]
	v_mfma_f32_32x32x16_bf16 v[6:21], v[90:93], v[42:45], v[6:21]
	v_max_f32_e32 v210, 0, v218
	v_max_f32_e32 v211, 0, v219
	v_pk_fma_f32 v[0:1], v[28:29], v[210:211], v[0:1]
	v_max_f32_e32 v108, 0, v220
	v_max_f32_e32 v109, 0, v221
	v_pk_fma_f32 v[0:1], v[30:31], v[108:109], v[0:1]
	v_max_f32_e32 v210, 0, v222
	v_max_f32_e32 v211, 0, v223
	v_pk_fma_f32 v[0:1], v[32:33], v[210:211], v[0:1]
	v_mfma_f32_32x32x16_bf16 v[6:21], v[94:97], v[46:49], v[6:21]
	v_max_f32_e32 v108, 0, v224
	v_max_f32_e32 v109, 0, v225
	v_pk_fma_f32 v[0:1], v[34:35], v[108:109], v[0:1]
	v_max_f32_e32 v210, 0, v226
	v_max_f32_e32 v211, 0, v227
	v_pk_fma_f32 v[0:1], v[36:37], v[210:211], v[0:1]
	v_add_f32_e32 v0, v0, v1
	v_ashrrev_i32_e32 v1, 31, v0
	v_mfma_f32_32x32x16_bf16 v[6:21], v[98:101], v[196:199], v[6:21]
	s_waitcnt vmcnt(10)
	ds_read_b128 v[38:41], v5 offset:43264
	ds_read_b128 v[42:45], v52 offset:43264
	ds_read_b128 v[46:49], v55 offset:43264
	ds_read_b128 v[196:199], v56 offset:43264
	v_or_b32_e32 v1, 0x80000000, v1
	s_cmpk_gt_i32 s11, 64
	s_cselect_b64 vcc, -1, 0
	v_xor_b32_e32 v0, v1, v0
	v_cndmask_b32_e32 v142, v123, v0, vcc
	s_nop 3
	s_waitcnt lgkmcnt(3)
	v_mfma_f32_32x32x16_bf16 v[212:227], v[70:73], v[38:41], 0
	v_max_f32_e32 v108, 0, v6
	v_max_f32_e32 v109, 0, v7
	v_pk_mul_f32 v[50:51], v[244:245], v[108:109]
	v_max_f32_e32 v210, 0, v8
	v_max_f32_e32 v211, 0, v9
	v_pk_fma_f32 v[50:51], v[246:247], v[210:211], v[50:51]
	v_max_f32_e32 v108, 0, v10
	v_max_f32_e32 v109, 0, v11
	v_pk_fma_f32 v[50:51], v[248:249], v[108:109], v[50:51]
	s_waitcnt lgkmcnt(2)
	v_mfma_f32_32x32x16_bf16 v[212:227], v[74:77], v[42:45], v[212:227]
	v_max_f32_e32 v210, 0, v12
	v_max_f32_e32 v211, 0, v13
	v_pk_fma_f32 v[50:51], v[250:251], v[210:211], v[50:51]
	v_max_f32_e32 v108, 0, v14
	v_max_f32_e32 v109, 0, v15
	v_pk_fma_f32 v[50:51], v[252:253], v[108:109], v[50:51]
	v_max_f32_e32 v210, 0, v16
	v_max_f32_e32 v211, 0, v17
	v_pk_fma_f32 v[50:51], v[254:255], v[210:211], v[50:51]
	s_waitcnt lgkmcnt(1)
	v_mfma_f32_32x32x16_bf16 v[212:227], v[78:81], v[46:49], v[212:227]
	v_max_f32_e32 v108, 0, v18
	v_max_f32_e32 v109, 0, v19
	v_pk_fma_f32 v[50:51], v[200:201], v[108:109], v[50:51]
	v_max_f32_e32 v210, 0, v20
	v_max_f32_e32 v211, 0, v21
	v_pk_fma_f32 v[50:51], v[202:203], v[210:211], v[50:51]
	v_add_f32_e32 v50, v50, v51
	v_ashrrev_i32_e32 v51, 31, v50
	s_waitcnt lgkmcnt(0)
	v_mfma_f32_32x32x16_bf16 v[212:227], v[82:85], v[196:199], v[212:227]
	v_or_b32_e32 v51, 0x80000000, v51
	s_cmpk_gt_i32 s11, 64
	s_cselect_b64 vcc, -1, 0
	v_xor_b32_e32 v50, v51, v50
	v_cndmask_b32_e32 v50, v123, v50, vcc
	global_store_dword v243, v50, s[8:9]
	v_mfma_f32_32x32x16_bf16 v[6:21], v[86:89], v[38:41], 0
	s_add_i32 m0, s10, 0
	s_nop 0
	global_load_lds_dwordx4 v102, s[6:7]
	s_add_i32 m0, s10, 1024
	s_nop 0
	global_load_lds_dwordx4 v110, s[6:7]
	s_add_i32 m0, s10, 2048
	s_nop 0
	global_load_lds_dwordx4 v112, s[6:7]
	s_add_i32 m0, s10, 3072
	s_nop 0
	global_load_lds_dwordx4 v193, s[6:7]
	s_add_u32 s6, s6, 0x8000
	s_addc_u32 s7, s7, 0
	v_max_f32_e32 v108, 0, v212
	v_max_f32_e32 v109, 0, v213
	v_pk_mul_f32 v[0:1], v[22:23], v[108:109]
	v_max_f32_e32 v210, 0, v214
	v_max_f32_e32 v211, 0, v215
	v_pk_fma_f32 v[0:1], v[24:25], v[210:211], v[0:1]
	v_max_f32_e32 v108, 0, v216
	v_max_f32_e32 v109, 0, v217
	v_pk_fma_f32 v[0:1], v[26:27], v[108:109], v[0:1]
	v_mfma_f32_32x32x16_bf16 v[6:21], v[90:93], v[42:45], v[6:21]
	v_max_f32_e32 v210, 0, v218
	v_max_f32_e32 v211, 0, v219
	v_pk_fma_f32 v[0:1], v[28:29], v[210:211], v[0:1]
	v_max_f32_e32 v108, 0, v220
	v_max_f32_e32 v109, 0, v221
	v_pk_fma_f32 v[0:1], v[30:31], v[108:109], v[0:1]
	v_max_f32_e32 v210, 0, v222
	v_max_f32_e32 v211, 0, v223
	v_pk_fma_f32 v[0:1], v[32:33], v[210:211], v[0:1]
	v_mfma_f32_32x32x16_bf16 v[6:21], v[94:97], v[46:49], v[6:21]
	v_max_f32_e32 v108, 0, v224
	v_max_f32_e32 v109, 0, v225
	v_pk_fma_f32 v[0:1], v[34:35], v[108:109], v[0:1]
	v_max_f32_e32 v210, 0, v226
	v_max_f32_e32 v211, 0, v227
	v_pk_fma_f32 v[0:1], v[36:37], v[210:211], v[0:1]
	v_add_f32_e32 v0, v0, v1
	v_ashrrev_i32_e32 v1, 31, v0
	v_mfma_f32_32x32x16_bf16 v[6:21], v[98:101], v[196:199], v[6:21]
	s_waitcnt vmcnt(10)
	v_add_u32_e32 v228, 0x10000, v5
	ds_read_b128 v[38:41], v228 offset:10496
	v_add_u32_e32 v228, 0x10000, v52
	ds_read_b128 v[42:45], v228 offset:10496
	v_add_u32_e32 v228, 0x10000, v55
	ds_read_b128 v[46:49], v228 offset:10496
	v_add_u32_e32 v228, 0x10000, v56
	ds_read_b128 v[196:199], v228 offset:10496
	v_or_b32_e32 v1, 0x80000000, v1
	s_cmpk_gt_i32 s11, 72
	s_cselect_b64 vcc, -1, 0
	v_xor_b32_e32 v0, v1, v0
	v_cndmask_b32_e32 v141, v123, v0, vcc
	s_nop 3
	s_waitcnt lgkmcnt(3)
	v_mfma_f32_32x32x16_bf16 v[212:227], v[70:73], v[38:41], 0
	v_max_f32_e32 v108, 0, v6
	v_max_f32_e32 v109, 0, v7
	v_pk_mul_f32 v[50:51], v[244:245], v[108:109]
	v_max_f32_e32 v210, 0, v8
	v_max_f32_e32 v211, 0, v9
	v_pk_fma_f32 v[50:51], v[246:247], v[210:211], v[50:51]
	v_max_f32_e32 v108, 0, v10
	v_max_f32_e32 v109, 0, v11
	v_pk_fma_f32 v[50:51], v[248:249], v[108:109], v[50:51]
	s_waitcnt lgkmcnt(2)
	v_mfma_f32_32x32x16_bf16 v[212:227], v[74:77], v[42:45], v[212:227]
	v_max_f32_e32 v210, 0, v12
	v_max_f32_e32 v211, 0, v13
	v_pk_fma_f32 v[50:51], v[250:251], v[210:211], v[50:51]
	v_max_f32_e32 v108, 0, v14
	v_max_f32_e32 v109, 0, v15
	v_pk_fma_f32 v[50:51], v[252:253], v[108:109], v[50:51]
	v_max_f32_e32 v210, 0, v16
	v_max_f32_e32 v211, 0, v17
	v_pk_fma_f32 v[50:51], v[254:255], v[210:211], v[50:51]
	s_waitcnt lgkmcnt(1)
	v_mfma_f32_32x32x16_bf16 v[212:227], v[78:81], v[46:49], v[212:227]
	v_max_f32_e32 v108, 0, v18
	v_max_f32_e32 v109, 0, v19
	v_pk_fma_f32 v[50:51], v[200:201], v[108:109], v[50:51]
	v_max_f32_e32 v210, 0, v20
	v_max_f32_e32 v211, 0, v21
	v_pk_fma_f32 v[50:51], v[202:203], v[210:211], v[50:51]
	v_add_f32_e32 v50, v50, v51
	v_ashrrev_i32_e32 v51, 31, v50
	s_waitcnt lgkmcnt(0)
	v_mfma_f32_32x32x16_bf16 v[212:227], v[82:85], v[196:199], v[212:227]
	v_or_b32_e32 v51, 0x80000000, v51
	s_cmpk_gt_i32 s11, 72
	s_cselect_b64 vcc, -1, 0
	v_xor_b32_e32 v50, v51, v50
	v_cndmask_b32_e32 v50, v123, v50, vcc
	global_store_dword v243, v50, s[8:9] offset:2048
	s_add_u32 s8, s8, 0x1000
	s_addc_u32 s9, s9, 0
	v_mfma_f32_32x32x16_bf16 v[6:21], v[86:89], v[38:41], 0
	s_add_i32 m0, s10, 32768
	s_nop 0
	global_load_lds_dwordx4 v102, s[6:7]
	s_add_i32 m0, s10, 33792
	s_nop 0
	global_load_lds_dwordx4 v110, s[6:7]
	s_add_i32 m0, s10, 34816
	s_nop 0
	global_load_lds_dwordx4 v112, s[6:7]
	s_add_i32 m0, s10, 35840
	s_nop 0
	global_load_lds_dwordx4 v193, s[6:7]
	s_add_u32 s6, s6, 0x8000
	s_addc_u32 s7, s7, 0
	v_max_f32_e32 v108, 0, v212
	v_max_f32_e32 v109, 0, v213
	v_pk_mul_f32 v[0:1], v[22:23], v[108:109]
	v_max_f32_e32 v210, 0, v214
	v_max_f32_e32 v211, 0, v215
	v_pk_fma_f32 v[0:1], v[24:25], v[210:211], v[0:1]
	v_max_f32_e32 v108, 0, v216
	v_max_f32_e32 v109, 0, v217
	v_pk_fma_f32 v[0:1], v[26:27], v[108:109], v[0:1]
	v_mfma_f32_32x32x16_bf16 v[6:21], v[90:93], v[42:45], v[6:21]
	v_max_f32_e32 v210, 0, v218
	v_max_f32_e32 v211, 0, v219
	v_pk_fma_f32 v[0:1], v[28:29], v[210:211], v[0:1]
	v_max_f32_e32 v108, 0, v220
	v_max_f32_e32 v109, 0, v221
	v_pk_fma_f32 v[0:1], v[30:31], v[108:109], v[0:1]
	v_max_f32_e32 v210, 0, v222
	v_max_f32_e32 v211, 0, v223
	v_pk_fma_f32 v[0:1], v[32:33], v[210:211], v[0:1]
	v_mfma_f32_32x32x16_bf16 v[6:21], v[94:97], v[46:49], v[6:21]
	v_max_f32_e32 v108, 0, v224
	v_max_f32_e32 v109, 0, v225
	v_pk_fma_f32 v[0:1], v[34:35], v[108:109], v[0:1]
	v_max_f32_e32 v210, 0, v226
	v_max_f32_e32 v211, 0, v227
	v_pk_fma_f32 v[0:1], v[36:37], v[210:211], v[0:1]
	v_add_f32_e32 v0, v0, v1
	v_ashrrev_i32_e32 v1, 31, v0
	v_mfma_f32_32x32x16_bf16 v[6:21], v[98:101], v[196:199], v[6:21]
	s_waitcnt vmcnt(10)
	v_add_u32_e32 v228, 0x10000, v5
	ds_read_b128 v[38:41], v228 offset:43264
	v_add_u32_e32 v228, 0x10000, v52
	ds_read_b128 v[42:45], v228 offset:43264
	v_add_u32_e32 v228, 0x10000, v55
	ds_read_b128 v[46:49], v228 offset:43264
	v_add_u32_e32 v228, 0x10000, v56
	ds_read_b128 v[196:199], v228 offset:43264
	v_or_b32_e32 v1, 0x80000000, v1
	s_cmpk_gt_i32 s11, 80
	s_cselect_b64 vcc, -1, 0
	v_xor_b32_e32 v0, v1, v0
	v_cndmask_b32_e32 v144, v123, v0, vcc
	s_nop 3
	s_waitcnt lgkmcnt(3)
	v_mfma_f32_32x32x16_bf16 v[212:227], v[70:73], v[38:41], 0
	v_max_f32_e32 v108, 0, v6
	v_max_f32_e32 v109, 0, v7
	v_pk_mul_f32 v[50:51], v[244:245], v[108:109]
	v_max_f32_e32 v210, 0, v8
	v_max_f32_e32 v211, 0, v9
	v_pk_fma_f32 v[50:51], v[246:247], v[210:211], v[50:51]
	v_max_f32_e32 v108, 0, v10
	v_max_f32_e32 v109, 0, v11
	v_pk_fma_f32 v[50:51], v[248:249], v[108:109], v[50:51]
	s_waitcnt lgkmcnt(2)
	v_mfma_f32_32x32x16_bf16 v[212:227], v[74:77], v[42:45], v[212:227]
	v_max_f32_e32 v210, 0, v12
	v_max_f32_e32 v211, 0, v13
	v_pk_fma_f32 v[50:51], v[250:251], v[210:211], v[50:51]
	v_max_f32_e32 v108, 0, v14
	v_max_f32_e32 v109, 0, v15
	v_pk_fma_f32 v[50:51], v[252:253], v[108:109], v[50:51]
	v_max_f32_e32 v210, 0, v16
	v_max_f32_e32 v211, 0, v17
	v_pk_fma_f32 v[50:51], v[254:255], v[210:211], v[50:51]
	s_waitcnt lgkmcnt(1)
	v_mfma_f32_32x32x16_bf16 v[212:227], v[78:81], v[46:49], v[212:227]
	v_max_f32_e32 v108, 0, v18
	v_max_f32_e32 v109, 0, v19
	v_pk_fma_f32 v[50:51], v[200:201], v[108:109], v[50:51]
	v_max_f32_e32 v210, 0, v20
	v_max_f32_e32 v211, 0, v21
	v_pk_fma_f32 v[50:51], v[202:203], v[210:211], v[50:51]
	v_add_f32_e32 v50, v50, v51
	v_ashrrev_i32_e32 v51, 31, v50
	s_waitcnt lgkmcnt(0)
	v_mfma_f32_32x32x16_bf16 v[212:227], v[82:85], v[196:199], v[212:227]
	v_or_b32_e32 v51, 0x80000000, v51
	s_cmpk_gt_i32 s11, 80
	s_cselect_b64 vcc, -1, 0
	v_xor_b32_e32 v50, v51, v50
	v_cndmask_b32_e32 v50, v123, v50, vcc
	global_store_dword v243, v50, s[8:9]
	v_mfma_f32_32x32x16_bf16 v[6:21], v[86:89], v[38:41], 0
	s_add_i32 m0, s10, 65536
	s_nop 0
	global_load_lds_dwordx4 v102, s[6:7]
	s_add_i32 m0, s10, 66560
	s_nop 0
	global_load_lds_dwordx4 v110, s[6:7]
	s_add_i32 m0, s10, 67584
	s_nop 0
	global_load_lds_dwordx4 v112, s[6:7]
	s_add_i32 m0, s10, 68608
	s_nop 0
	global_load_lds_dwordx4 v193, s[6:7]
	s_add_u32 s6, s6, 0x8000
	s_addc_u32 s7, s7, 0
	v_max_f32_e32 v108, 0, v212
	v_max_f32_e32 v109, 0, v213
	v_pk_mul_f32 v[0:1], v[22:23], v[108:109]
	v_max_f32_e32 v210, 0, v214
	v_max_f32_e32 v211, 0, v215
	v_pk_fma_f32 v[0:1], v[24:25], v[210:211], v[0:1]
	v_max_f32_e32 v108, 0, v216
	v_max_f32_e32 v109, 0, v217
	v_pk_fma_f32 v[0:1], v[26:27], v[108:109], v[0:1]
	v_mfma_f32_32x32x16_bf16 v[6:21], v[90:93], v[42:45], v[6:21]
	v_max_f32_e32 v210, 0, v218
	v_max_f32_e32 v211, 0, v219
	v_pk_fma_f32 v[0:1], v[28:29], v[210:211], v[0:1]
	v_max_f32_e32 v108, 0, v220
	v_max_f32_e32 v109, 0, v221
	v_pk_fma_f32 v[0:1], v[30:31], v[108:109], v[0:1]
	v_max_f32_e32 v210, 0, v222
	v_max_f32_e32 v211, 0, v223
	v_pk_fma_f32 v[0:1], v[32:33], v[210:211], v[0:1]
	v_mfma_f32_32x32x16_bf16 v[6:21], v[94:97], v[46:49], v[6:21]
	v_max_f32_e32 v108, 0, v224
	v_max_f32_e32 v109, 0, v225
	v_pk_fma_f32 v[0:1], v[34:35], v[108:109], v[0:1]
	v_max_f32_e32 v210, 0, v226
	v_max_f32_e32 v211, 0, v227
	v_pk_fma_f32 v[0:1], v[36:37], v[210:211], v[0:1]
	v_add_f32_e32 v0, v0, v1
	v_ashrrev_i32_e32 v1, 31, v0
	v_mfma_f32_32x32x16_bf16 v[6:21], v[98:101], v[196:199], v[6:21]
	s_waitcnt vmcnt(10)
	ds_read_b128 v[38:41], v5 offset:10496
	ds_read_b128 v[42:45], v52 offset:10496
	ds_read_b128 v[46:49], v55 offset:10496
	ds_read_b128 v[196:199], v56 offset:10496
	v_or_b32_e32 v1, 0x80000000, v1
	s_cmpk_gt_i32 s11, 88
	s_cselect_b64 vcc, -1, 0
	v_xor_b32_e32 v0, v1, v0
	v_cndmask_b32_e32 v143, v123, v0, vcc
	s_nop 3
	s_waitcnt lgkmcnt(3)
	v_mfma_f32_32x32x16_bf16 v[212:227], v[70:73], v[38:41], 0
	v_max_f32_e32 v108, 0, v6
	v_max_f32_e32 v109, 0, v7
	v_pk_mul_f32 v[50:51], v[244:245], v[108:109]
	v_max_f32_e32 v210, 0, v8
	v_max_f32_e32 v211, 0, v9
	v_pk_fma_f32 v[50:51], v[246:247], v[210:211], v[50:51]
	v_max_f32_e32 v108, 0, v10
	v_max_f32_e32 v109, 0, v11
	v_pk_fma_f32 v[50:51], v[248:249], v[108:109], v[50:51]
	s_waitcnt lgkmcnt(2)
	v_mfma_f32_32x32x16_bf16 v[212:227], v[74:77], v[42:45], v[212:227]
	v_max_f32_e32 v210, 0, v12
	v_max_f32_e32 v211, 0, v13
	v_pk_fma_f32 v[50:51], v[250:251], v[210:211], v[50:51]
	v_max_f32_e32 v108, 0, v14
	v_max_f32_e32 v109, 0, v15
	v_pk_fma_f32 v[50:51], v[252:253], v[108:109], v[50:51]
	v_max_f32_e32 v210, 0, v16
	v_max_f32_e32 v211, 0, v17
	v_pk_fma_f32 v[50:51], v[254:255], v[210:211], v[50:51]
	s_waitcnt lgkmcnt(1)
	v_mfma_f32_32x32x16_bf16 v[212:227], v[78:81], v[46:49], v[212:227]
	v_max_f32_e32 v108, 0, v18
	v_max_f32_e32 v109, 0, v19
	v_pk_fma_f32 v[50:51], v[200:201], v[108:109], v[50:51]
	v_max_f32_e32 v210, 0, v20
	v_max_f32_e32 v211, 0, v21
	v_pk_fma_f32 v[50:51], v[202:203], v[210:211], v[50:51]
	v_add_f32_e32 v50, v50, v51
	v_ashrrev_i32_e32 v51, 31, v50
	s_waitcnt lgkmcnt(0)
	v_mfma_f32_32x32x16_bf16 v[212:227], v[82:85], v[196:199], v[212:227]
	v_or_b32_e32 v51, 0x80000000, v51
	s_cmpk_gt_i32 s11, 88
	s_cselect_b64 vcc, -1, 0
	v_xor_b32_e32 v50, v51, v50
	v_cndmask_b32_e32 v50, v123, v50, vcc
	global_store_dword v243, v50, s[8:9] offset:2048
	s_add_u32 s8, s8, 0x1000
	s_addc_u32 s9, s9, 0
	v_mfma_f32_32x32x16_bf16 v[6:21], v[86:89], v[38:41], 0
	s_add_i32 m0, s10, 98304
	s_nop 0
	global_load_lds_dwordx4 v102, s[6:7]
	s_add_i32 m0, s10, 99328
	s_nop 0
	global_load_lds_dwordx4 v110, s[6:7]
	s_add_i32 m0, s10, 100352
	s_nop 0
	global_load_lds_dwordx4 v112, s[6:7]
	s_add_i32 m0, s10, 101376
	s_nop 0
	global_load_lds_dwordx4 v193, s[6:7]
	s_add_u32 s6, s6, 0x8000
	s_addc_u32 s7, s7, 0
	v_max_f32_e32 v108, 0, v212
	v_max_f32_e32 v109, 0, v213
	v_pk_mul_f32 v[0:1], v[22:23], v[108:109]
	v_max_f32_e32 v210, 0, v214
	v_max_f32_e32 v211, 0, v215
	v_pk_fma_f32 v[0:1], v[24:25], v[210:211], v[0:1]
	v_max_f32_e32 v108, 0, v216
	v_max_f32_e32 v109, 0, v217
	v_pk_fma_f32 v[0:1], v[26:27], v[108:109], v[0:1]
	v_mfma_f32_32x32x16_bf16 v[6:21], v[90:93], v[42:45], v[6:21]
	v_max_f32_e32 v210, 0, v218
	v_max_f32_e32 v211, 0, v219
	v_pk_fma_f32 v[0:1], v[28:29], v[210:211], v[0:1]
	v_max_f32_e32 v108, 0, v220
	v_max_f32_e32 v109, 0, v221
	v_pk_fma_f32 v[0:1], v[30:31], v[108:109], v[0:1]
	v_max_f32_e32 v210, 0, v222
	v_max_f32_e32 v211, 0, v223
	v_pk_fma_f32 v[0:1], v[32:33], v[210:211], v[0:1]
	v_mfma_f32_32x32x16_bf16 v[6:21], v[94:97], v[46:49], v[6:21]
	v_max_f32_e32 v108, 0, v224
	v_max_f32_e32 v109, 0, v225
	v_pk_fma_f32 v[0:1], v[34:35], v[108:109], v[0:1]
	v_max_f32_e32 v210, 0, v226
	v_max_f32_e32 v211, 0, v227
	v_pk_fma_f32 v[0:1], v[36:37], v[210:211], v[0:1]
	v_add_f32_e32 v0, v0, v1
	v_ashrrev_i32_e32 v1, 31, v0
	v_mfma_f32_32x32x16_bf16 v[6:21], v[98:101], v[196:199], v[6:21]
	s_waitcnt vmcnt(10)
	ds_read_b128 v[38:41], v5 offset:43264
	ds_read_b128 v[42:45], v52 offset:43264
	ds_read_b128 v[46:49], v55 offset:43264
	ds_read_b128 v[196:199], v56 offset:43264
	v_or_b32_e32 v1, 0x80000000, v1
	s_cmpk_gt_i32 s11, 96
	s_cselect_b64 vcc, -1, 0
	v_xor_b32_e32 v0, v1, v0
	v_cndmask_b32_e32 v146, v123, v0, vcc
	s_nop 3
	s_waitcnt lgkmcnt(3)
	v_mfma_f32_32x32x16_bf16 v[212:227], v[70:73], v[38:41], 0
	v_max_f32_e32 v108, 0, v6
	v_max_f32_e32 v109, 0, v7
	v_pk_mul_f32 v[50:51], v[244:245], v[108:109]
	v_max_f32_e32 v210, 0, v8
	v_max_f32_e32 v211, 0, v9
	v_pk_fma_f32 v[50:51], v[246:247], v[210:211], v[50:51]
	v_max_f32_e32 v108, 0, v10
	v_max_f32_e32 v109, 0, v11
	v_pk_fma_f32 v[50:51], v[248:249], v[108:109], v[50:51]
	s_waitcnt lgkmcnt(2)
	v_mfma_f32_32x32x16_bf16 v[212:227], v[74:77], v[42:45], v[212:227]
	v_max_f32_e32 v210, 0, v12
	v_max_f32_e32 v211, 0, v13
	v_pk_fma_f32 v[50:51], v[250:251], v[210:211], v[50:51]
	v_max_f32_e32 v108, 0, v14
	v_max_f32_e32 v109, 0, v15
	v_pk_fma_f32 v[50:51], v[252:253], v[108:109], v[50:51]
	v_max_f32_e32 v210, 0, v16
	v_max_f32_e32 v211, 0, v17
	v_pk_fma_f32 v[50:51], v[254:255], v[210:211], v[50:51]
	s_waitcnt lgkmcnt(1)
	v_mfma_f32_32x32x16_bf16 v[212:227], v[78:81], v[46:49], v[212:227]
	v_max_f32_e32 v108, 0, v18
	v_max_f32_e32 v109, 0, v19
	v_pk_fma_f32 v[50:51], v[200:201], v[108:109], v[50:51]
	v_max_f32_e32 v210, 0, v20
	v_max_f32_e32 v211, 0, v21
	v_pk_fma_f32 v[50:51], v[202:203], v[210:211], v[50:51]
	v_add_f32_e32 v50, v50, v51
	v_ashrrev_i32_e32 v51, 31, v50
	s_waitcnt lgkmcnt(0)
	v_mfma_f32_32x32x16_bf16 v[212:227], v[82:85], v[196:199], v[212:227]
	v_or_b32_e32 v51, 0x80000000, v51
	s_cmpk_gt_i32 s11, 96
	s_cselect_b64 vcc, -1, 0
	v_xor_b32_e32 v50, v51, v50
	v_cndmask_b32_e32 v50, v123, v50, vcc
	global_store_dword v243, v50, s[8:9]
	v_mfma_f32_32x32x16_bf16 v[6:21], v[86:89], v[38:41], 0
	s_add_i32 m0, s10, 0
	s_nop 0
	global_load_lds_dwordx4 v102, s[6:7]
	s_add_i32 m0, s10, 1024
	s_nop 0
	global_load_lds_dwordx4 v110, s[6:7]
	s_add_i32 m0, s10, 2048
	s_nop 0
	global_load_lds_dwordx4 v112, s[6:7]
	s_add_i32 m0, s10, 3072
	s_nop 0
	global_load_lds_dwordx4 v193, s[6:7]
	s_add_u32 s6, s6, 0x8000
	s_addc_u32 s7, s7, 0
	v_max_f32_e32 v108, 0, v212
	v_max_f32_e32 v109, 0, v213
	v_pk_mul_f32 v[0:1], v[22:23], v[108:109]
	v_max_f32_e32 v210, 0, v214
	v_max_f32_e32 v211, 0, v215
	v_pk_fma_f32 v[0:1], v[24:25], v[210:211], v[0:1]
	v_max_f32_e32 v108, 0, v216
	v_max_f32_e32 v109, 0, v217
	v_pk_fma_f32 v[0:1], v[26:27], v[108:109], v[0:1]
	v_mfma_f32_32x32x16_bf16 v[6:21], v[90:93], v[42:45], v[6:21]
	v_max_f32_e32 v210, 0, v218
	v_max_f32_e32 v211, 0, v219
	v_pk_fma_f32 v[0:1], v[28:29], v[210:211], v[0:1]
	v_max_f32_e32 v108, 0, v220
	v_max_f32_e32 v109, 0, v221
	v_pk_fma_f32 v[0:1], v[30:31], v[108:109], v[0:1]
	v_max_f32_e32 v210, 0, v222
	v_max_f32_e32 v211, 0, v223
	v_pk_fma_f32 v[0:1], v[32:33], v[210:211], v[0:1]
	v_mfma_f32_32x32x16_bf16 v[6:21], v[94:97], v[46:49], v[6:21]
	v_max_f32_e32 v108, 0, v224
	v_max_f32_e32 v109, 0, v225
	v_pk_fma_f32 v[0:1], v[34:35], v[108:109], v[0:1]
	v_max_f32_e32 v210, 0, v226
	v_max_f32_e32 v211, 0, v227
	v_pk_fma_f32 v[0:1], v[36:37], v[210:211], v[0:1]
	v_add_f32_e32 v0, v0, v1
	v_ashrrev_i32_e32 v1, 31, v0
	v_mfma_f32_32x32x16_bf16 v[6:21], v[98:101], v[196:199], v[6:21]
	s_waitcnt vmcnt(10)
	v_add_u32_e32 v228, 0x10000, v5
	ds_read_b128 v[38:41], v228 offset:10496
	v_add_u32_e32 v228, 0x10000, v52
	ds_read_b128 v[42:45], v228 offset:10496
	v_add_u32_e32 v228, 0x10000, v55
	ds_read_b128 v[46:49], v228 offset:10496
	v_add_u32_e32 v228, 0x10000, v56
	ds_read_b128 v[196:199], v228 offset:10496
	v_or_b32_e32 v1, 0x80000000, v1
	s_cmpk_gt_i32 s11, 104
	s_cselect_b64 vcc, -1, 0
	v_xor_b32_e32 v0, v1, v0
	v_cndmask_b32_e32 v145, v123, v0, vcc
	s_nop 3
	s_waitcnt lgkmcnt(3)
	v_mfma_f32_32x32x16_bf16 v[212:227], v[70:73], v[38:41], 0
	v_max_f32_e32 v108, 0, v6
	v_max_f32_e32 v109, 0, v7
	v_pk_mul_f32 v[50:51], v[244:245], v[108:109]
	v_max_f32_e32 v210, 0, v8
	v_max_f32_e32 v211, 0, v9
	v_pk_fma_f32 v[50:51], v[246:247], v[210:211], v[50:51]
	v_max_f32_e32 v108, 0, v10
	v_max_f32_e32 v109, 0, v11
	v_pk_fma_f32 v[50:51], v[248:249], v[108:109], v[50:51]
	s_waitcnt lgkmcnt(2)
	v_mfma_f32_32x32x16_bf16 v[212:227], v[74:77], v[42:45], v[212:227]
	v_max_f32_e32 v210, 0, v12
	v_max_f32_e32 v211, 0, v13
	v_pk_fma_f32 v[50:51], v[250:251], v[210:211], v[50:51]
	v_max_f32_e32 v108, 0, v14
	v_max_f32_e32 v109, 0, v15
	v_pk_fma_f32 v[50:51], v[252:253], v[108:109], v[50:51]
	v_max_f32_e32 v210, 0, v16
	v_max_f32_e32 v211, 0, v17
	v_pk_fma_f32 v[50:51], v[254:255], v[210:211], v[50:51]
	s_waitcnt lgkmcnt(1)
	v_mfma_f32_32x32x16_bf16 v[212:227], v[78:81], v[46:49], v[212:227]
	v_max_f32_e32 v108, 0, v18
	v_max_f32_e32 v109, 0, v19
	v_pk_fma_f32 v[50:51], v[200:201], v[108:109], v[50:51]
	v_max_f32_e32 v210, 0, v20
	v_max_f32_e32 v211, 0, v21
	v_pk_fma_f32 v[50:51], v[202:203], v[210:211], v[50:51]
	v_add_f32_e32 v50, v50, v51
	v_ashrrev_i32_e32 v51, 31, v50
	s_waitcnt lgkmcnt(0)
	v_mfma_f32_32x32x16_bf16 v[212:227], v[82:85], v[196:199], v[212:227]
	v_or_b32_e32 v51, 0x80000000, v51
	s_cmpk_gt_i32 s11, 104
	s_cselect_b64 vcc, -1, 0
	v_xor_b32_e32 v50, v51, v50
	v_cndmask_b32_e32 v50, v123, v50, vcc
	global_store_dword v243, v50, s[8:9] offset:2048
	s_add_u32 s8, s8, 0x1000
	s_addc_u32 s9, s9, 0
	v_mfma_f32_32x32x16_bf16 v[6:21], v[86:89], v[38:41], 0
	s_add_i32 m0, s10, 32768
	s_nop 0
	global_load_lds_dwordx4 v102, s[6:7]
	s_add_i32 m0, s10, 33792
	s_nop 0
	global_load_lds_dwordx4 v110, s[6:7]
	s_add_i32 m0, s10, 34816
	s_nop 0
	global_load_lds_dwordx4 v112, s[6:7]
	s_add_i32 m0, s10, 35840
	s_nop 0
	global_load_lds_dwordx4 v193, s[6:7]
	s_add_u32 s6, s6, 0x8000
	s_addc_u32 s7, s7, 0
	v_max_f32_e32 v108, 0, v212
	v_max_f32_e32 v109, 0, v213
	v_pk_mul_f32 v[0:1], v[22:23], v[108:109]
	v_max_f32_e32 v210, 0, v214
	v_max_f32_e32 v211, 0, v215
	v_pk_fma_f32 v[0:1], v[24:25], v[210:211], v[0:1]
	v_max_f32_e32 v108, 0, v216
	v_max_f32_e32 v109, 0, v217
	v_pk_fma_f32 v[0:1], v[26:27], v[108:109], v[0:1]
	v_mfma_f32_32x32x16_bf16 v[6:21], v[90:93], v[42:45], v[6:21]
	v_max_f32_e32 v210, 0, v218
	v_max_f32_e32 v211, 0, v219
	v_pk_fma_f32 v[0:1], v[28:29], v[210:211], v[0:1]
	v_max_f32_e32 v108, 0, v220
	v_max_f32_e32 v109, 0, v221
	v_pk_fma_f32 v[0:1], v[30:31], v[108:109], v[0:1]
	v_max_f32_e32 v210, 0, v222
	v_max_f32_e32 v211, 0, v223
	v_pk_fma_f32 v[0:1], v[32:33], v[210:211], v[0:1]
	v_mfma_f32_32x32x16_bf16 v[6:21], v[94:97], v[46:49], v[6:21]
	v_max_f32_e32 v108, 0, v224
	v_max_f32_e32 v109, 0, v225
	v_pk_fma_f32 v[0:1], v[34:35], v[108:109], v[0:1]
	v_max_f32_e32 v210, 0, v226
	v_max_f32_e32 v211, 0, v227
	v_pk_fma_f32 v[0:1], v[36:37], v[210:211], v[0:1]
	v_add_f32_e32 v0, v0, v1
	v_ashrrev_i32_e32 v1, 31, v0
	v_mfma_f32_32x32x16_bf16 v[6:21], v[98:101], v[196:199], v[6:21]
	s_waitcnt vmcnt(10)
	v_add_u32_e32 v228, 0x10000, v5
	ds_read_b128 v[38:41], v228 offset:43264
	v_add_u32_e32 v228, 0x10000, v52
	ds_read_b128 v[42:45], v228 offset:43264
	v_add_u32_e32 v228, 0x10000, v55
	ds_read_b128 v[46:49], v228 offset:43264
	v_add_u32_e32 v228, 0x10000, v56
	ds_read_b128 v[196:199], v228 offset:43264
	v_or_b32_e32 v1, 0x80000000, v1
	s_cmpk_gt_i32 s11, 112
	s_cselect_b64 vcc, -1, 0
	v_xor_b32_e32 v0, v1, v0
	v_cndmask_b32_e32 v147, v123, v0, vcc
	s_nop 3
	s_waitcnt lgkmcnt(3)
	v_mfma_f32_32x32x16_bf16 v[212:227], v[70:73], v[38:41], 0
	v_max_f32_e32 v108, 0, v6
	v_max_f32_e32 v109, 0, v7
	v_pk_mul_f32 v[50:51], v[244:245], v[108:109]
	v_max_f32_e32 v210, 0, v8
	v_max_f32_e32 v211, 0, v9
	v_pk_fma_f32 v[50:51], v[246:247], v[210:211], v[50:51]
	v_max_f32_e32 v108, 0, v10
	v_max_f32_e32 v109, 0, v11
	v_pk_fma_f32 v[50:51], v[248:249], v[108:109], v[50:51]
	s_waitcnt lgkmcnt(2)
	v_mfma_f32_32x32x16_bf16 v[212:227], v[74:77], v[42:45], v[212:227]
	v_max_f32_e32 v210, 0, v12
	v_max_f32_e32 v211, 0, v13
	v_pk_fma_f32 v[50:51], v[250:251], v[210:211], v[50:51]
	v_max_f32_e32 v108, 0, v14
	v_max_f32_e32 v109, 0, v15
	v_pk_fma_f32 v[50:51], v[252:253], v[108:109], v[50:51]
	v_max_f32_e32 v210, 0, v16
	v_max_f32_e32 v211, 0, v17
	v_pk_fma_f32 v[50:51], v[254:255], v[210:211], v[50:51]
	s_waitcnt lgkmcnt(1)
	v_mfma_f32_32x32x16_bf16 v[212:227], v[78:81], v[46:49], v[212:227]
	v_max_f32_e32 v108, 0, v18
	v_max_f32_e32 v109, 0, v19
	v_pk_fma_f32 v[50:51], v[200:201], v[108:109], v[50:51]
	v_max_f32_e32 v210, 0, v20
	v_max_f32_e32 v211, 0, v21
	v_pk_fma_f32 v[50:51], v[202:203], v[210:211], v[50:51]
	v_add_f32_e32 v50, v50, v51
	v_ashrrev_i32_e32 v51, 31, v50
	s_waitcnt lgkmcnt(0)
	v_mfma_f32_32x32x16_bf16 v[212:227], v[82:85], v[196:199], v[212:227]
	v_or_b32_e32 v51, 0x80000000, v51
	s_cmpk_gt_i32 s11, 112
	s_cselect_b64 vcc, -1, 0
	v_xor_b32_e32 v50, v51, v50
	v_cndmask_b32_e32 v50, v123, v50, vcc
	global_store_dword v243, v50, s[8:9]
	v_mfma_f32_32x32x16_bf16 v[6:21], v[86:89], v[38:41], 0
	s_add_i32 m0, s10, 65536
	s_nop 0
	global_load_lds_dwordx4 v102, s[6:7]
	s_add_i32 m0, s10, 66560
	s_nop 0
	global_load_lds_dwordx4 v110, s[6:7]
	s_add_i32 m0, s10, 67584
	s_nop 0
	global_load_lds_dwordx4 v112, s[6:7]
	s_add_i32 m0, s10, 68608
	s_nop 0
	global_load_lds_dwordx4 v193, s[6:7]
	s_add_u32 s6, s6, 0x8000
	s_addc_u32 s7, s7, 0
	v_max_f32_e32 v108, 0, v212
	v_max_f32_e32 v109, 0, v213
	v_pk_mul_f32 v[0:1], v[22:23], v[108:109]
	v_max_f32_e32 v210, 0, v214
	v_max_f32_e32 v211, 0, v215
	v_pk_fma_f32 v[0:1], v[24:25], v[210:211], v[0:1]
	v_max_f32_e32 v108, 0, v216
	v_max_f32_e32 v109, 0, v217
	v_pk_fma_f32 v[0:1], v[26:27], v[108:109], v[0:1]
	v_mfma_f32_32x32x16_bf16 v[6:21], v[90:93], v[42:45], v[6:21]
	v_max_f32_e32 v210, 0, v218
	v_max_f32_e32 v211, 0, v219
	v_pk_fma_f32 v[0:1], v[28:29], v[210:211], v[0:1]
	v_max_f32_e32 v108, 0, v220
	v_max_f32_e32 v109, 0, v221
	v_pk_fma_f32 v[0:1], v[30:31], v[108:109], v[0:1]
	v_max_f32_e32 v210, 0, v222
	v_max_f32_e32 v211, 0, v223
	v_pk_fma_f32 v[0:1], v[32:33], v[210:211], v[0:1]
	v_mfma_f32_32x32x16_bf16 v[6:21], v[94:97], v[46:49], v[6:21]
	v_max_f32_e32 v108, 0, v224
	v_max_f32_e32 v109, 0, v225
	v_pk_fma_f32 v[0:1], v[34:35], v[108:109], v[0:1]
	v_max_f32_e32 v210, 0, v226
	v_max_f32_e32 v211, 0, v227
	v_pk_fma_f32 v[0:1], v[36:37], v[210:211], v[0:1]
	v_add_f32_e32 v0, v0, v1
	v_ashrrev_i32_e32 v1, 31, v0
	v_mfma_f32_32x32x16_bf16 v[6:21], v[98:101], v[196:199], v[6:21]
	s_waitcnt vmcnt(10)
	ds_read_b128 v[38:41], v5 offset:10496
	ds_read_b128 v[42:45], v52 offset:10496
	ds_read_b128 v[46:49], v55 offset:10496
	ds_read_b128 v[196:199], v56 offset:10496
	v_or_b32_e32 v1, 0x80000000, v1
	s_cmpk_gt_i32 s11, 120
	s_cselect_b64 vcc, -1, 0
	v_xor_b32_e32 v0, v1, v0
	v_cndmask_b32_e32 v136, v123, v0, vcc
	s_nop 3
	v_max_f32_e32 v108, 0, v6
	v_max_f32_e32 v109, 0, v7
	v_pk_mul_f32 v[50:51], v[244:245], v[108:109]
	v_max_f32_e32 v210, 0, v8
	v_max_f32_e32 v211, 0, v9
	v_pk_fma_f32 v[50:51], v[246:247], v[210:211], v[50:51]
	v_max_f32_e32 v108, 0, v10
	v_max_f32_e32 v109, 0, v11
	v_pk_fma_f32 v[50:51], v[248:249], v[108:109], v[50:51]
	v_max_f32_e32 v210, 0, v12
	v_max_f32_e32 v211, 0, v13
	v_pk_fma_f32 v[50:51], v[250:251], v[210:211], v[50:51]
	v_max_f32_e32 v108, 0, v14
	v_max_f32_e32 v109, 0, v15
	v_pk_fma_f32 v[50:51], v[252:253], v[108:109], v[50:51]
	v_max_f32_e32 v210, 0, v16
	v_max_f32_e32 v211, 0, v17
	v_pk_fma_f32 v[50:51], v[254:255], v[210:211], v[50:51]
	v_max_f32_e32 v108, 0, v18
	v_max_f32_e32 v109, 0, v19
	v_pk_fma_f32 v[50:51], v[200:201], v[108:109], v[50:51]
	v_max_f32_e32 v210, 0, v20
	v_max_f32_e32 v211, 0, v21
	v_pk_fma_f32 v[50:51], v[202:203], v[210:211], v[50:51]
	v_add_f32_e32 v50, v50, v51
	v_ashrrev_i32_e32 v51, 31, v50
	v_or_b32_e32 v51, 0x80000000, v51
	s_cmpk_gt_i32 s11, 120
	s_cselect_b64 vcc, -1, 0
	v_xor_b32_e32 v50, v51, v50
	v_cndmask_b32_e32 v50, v123, v50, vcc
	global_store_dword v243, v50, s[8:9] offset:2048
	s_add_u32 s8, s8, 0x1000
	s_addc_u32 s9, s9, 0
	s_cmpk_gt_i32 s81, 16
	s_cbranch_scc0 .Lix_fill_2
	s_waitcnt lgkmcnt(3)
	v_mfma_f32_32x32x16_bf16 v[212:227], v[70:73], v[38:41], 0
	s_add_i32 m0, s10, 98304
	s_nop 0
	global_load_lds_dwordx4 v102, s[6:7]
	s_waitcnt lgkmcnt(2)
	v_mfma_f32_32x32x16_bf16 v[212:227], v[74:77], v[42:45], v[212:227]
	s_add_i32 m0, s10, 99328
	s_nop 0
	global_load_lds_dwordx4 v110, s[6:7]
	s_waitcnt lgkmcnt(1)
	v_mfma_f32_32x32x16_bf16 v[212:227], v[78:81], v[46:49], v[212:227]
	s_add_i32 m0, s10, 100352
	s_nop 0
	global_load_lds_dwordx4 v112, s[6:7]
	s_waitcnt lgkmcnt(0)
	v_mfma_f32_32x32x16_bf16 v[212:227], v[82:85], v[196:199], v[212:227]
	s_add_i32 m0, s10, 101376
	s_nop 0
	global_load_lds_dwordx4 v193, s[6:7]
	s_add_u32 s6, s6, 0x8000
	s_addc_u32 s7, s7, 0
	v_mfma_f32_32x32x16_bf16 v[6:21], v[86:89], v[38:41], 0
	s_nop 7
	s_nop 2
	v_max_f32_e32 v108, 0, v212
	v_max_f32_e32 v109, 0, v213
	v_pk_mul_f32 v[0:1], v[22:23], v[108:109]
	v_max_f32_e32 v210, 0, v214
	v_max_f32_e32 v211, 0, v215
	v_pk_fma_f32 v[0:1], v[24:25], v[210:211], v[0:1]
	v_max_f32_e32 v108, 0, v216
	v_max_f32_e32 v109, 0, v217
	v_pk_fma_f32 v[0:1], v[26:27], v[108:109], v[0:1]
	v_mfma_f32_32x32x16_bf16 v[6:21], v[90:93], v[42:45], v[6:21]
	v_max_f32_e32 v210, 0, v218
	v_max_f32_e32 v211, 0, v219
	v_pk_fma_f32 v[0:1], v[28:29], v[210:211], v[0:1]
	v_max_f32_e32 v108, 0, v220
	v_max_f32_e32 v109, 0, v221
	v_pk_fma_f32 v[0:1], v[30:31], v[108:109], v[0:1]
	v_max_f32_e32 v210, 0, v222
	v_max_f32_e32 v211, 0, v223
	v_pk_fma_f32 v[0:1], v[32:33], v[210:211], v[0:1]
	v_mfma_f32_32x32x16_bf16 v[6:21], v[94:97], v[46:49], v[6:21]
	v_max_f32_e32 v108, 0, v224
	v_max_f32_e32 v109, 0, v225
	v_pk_fma_f32 v[0:1], v[34:35], v[108:109], v[0:1]
	v_max_f32_e32 v210, 0, v226
	v_max_f32_e32 v211, 0, v227
	v_pk_fma_f32 v[0:1], v[36:37], v[210:211], v[0:1]
	v_add_f32_e32 v0, v0, v1
	v_ashrrev_i32_e32 v1, 31, v0
	v_mfma_f32_32x32x16_bf16 v[6:21], v[98:101], v[196:199], v[6:21]
	s_waitcnt vmcnt(10)
	ds_read_b128 v[38:41], v5 offset:43264
	ds_read_b128 v[42:45], v52 offset:43264
	ds_read_b128 v[46:49], v55 offset:43264
	ds_read_b128 v[196:199], v56 offset:43264
	v_or_b32_e32 v1, 0x80000000, v1
	s_cmpk_gt_i32 s11, 128
	s_cselect_b64 vcc, -1, 0
	v_xor_b32_e32 v0, v1, v0
	v_cndmask_b32_e32 v149, v123, v0, vcc
	s_nop 3
	s_waitcnt lgkmcnt(3)
	v_mfma_f32_32x32x16_bf16 v[212:227], v[70:73], v[38:41], 0
	v_max_f32_e32 v108, 0, v6
	v_max_f32_e32 v109, 0, v7
	v_pk_mul_f32 v[50:51], v[244:245], v[108:109]
	v_max_f32_e32 v210, 0, v8
	v_max_f32_e32 v211, 0, v9
	v_pk_fma_f32 v[50:51], v[246:247], v[210:211], v[50:51]
	v_max_f32_e32 v108, 0, v10
	v_max_f32_e32 v109, 0, v11
	v_pk_fma_f32 v[50:51], v[248:249], v[108:109], v[50:51]
	s_waitcnt lgkmcnt(2)
	v_mfma_f32_32x32x16_bf16 v[212:227], v[74:77], v[42:45], v[212:227]
	v_max_f32_e32 v210, 0, v12
	v_max_f32_e32 v211, 0, v13
	v_pk_fma_f32 v[50:51], v[250:251], v[210:211], v[50:51]
	v_max_f32_e32 v108, 0, v14
	v_max_f32_e32 v109, 0, v15
	v_pk_fma_f32 v[50:51], v[252:253], v[108:109], v[50:51]
	v_max_f32_e32 v210, 0, v16
	v_max_f32_e32 v211, 0, v17
	v_pk_fma_f32 v[50:51], v[254:255], v[210:211], v[50:51]
	s_waitcnt lgkmcnt(1)
	v_mfma_f32_32x32x16_bf16 v[212:227], v[78:81], v[46:49], v[212:227]
	v_max_f32_e32 v108, 0, v18
	v_max_f32_e32 v109, 0, v19
	v_pk_fma_f32 v[50:51], v[200:201], v[108:109], v[50:51]
	v_max_f32_e32 v210, 0, v20
	v_max_f32_e32 v211, 0, v21
	v_pk_fma_f32 v[50:51], v[202:203], v[210:211], v[50:51]
	v_add_f32_e32 v50, v50, v51
	v_ashrrev_i32_e32 v51, 31, v50
	s_waitcnt lgkmcnt(0)
	v_mfma_f32_32x32x16_bf16 v[212:227], v[82:85], v[196:199], v[212:227]
	v_or_b32_e32 v51, 0x80000000, v51
	s_cmpk_gt_i32 s11, 128
	s_cselect_b64 vcc, -1, 0
	v_xor_b32_e32 v50, v51, v50
	v_cndmask_b32_e32 v50, v123, v50, vcc
	global_store_dword v243, v50, s[8:9]
	v_mfma_f32_32x32x16_bf16 v[6:21], v[86:89], v[38:41], 0
	s_add_i32 m0, s10, 0
	s_nop 0
	global_load_lds_dwordx4 v102, s[6:7]
	s_add_i32 m0, s10, 1024
	s_nop 0
	global_load_lds_dwordx4 v110, s[6:7]
	s_add_i32 m0, s10, 2048
	s_nop 0
	global_load_lds_dwordx4 v112, s[6:7]
	s_add_i32 m0, s10, 3072
	s_nop 0
	global_load_lds_dwordx4 v193, s[6:7]
	s_add_u32 s6, s6, 0x8000
	s_addc_u32 s7, s7, 0
	v_max_f32_e32 v108, 0, v212
	v_max_f32_e32 v109, 0, v213
	v_pk_mul_f32 v[0:1], v[22:23], v[108:109]
	v_max_f32_e32 v210, 0, v214
	v_max_f32_e32 v211, 0, v215
	v_pk_fma_f32 v[0:1], v[24:25], v[210:211], v[0:1]
	v_max_f32_e32 v108, 0, v216
	v_max_f32_e32 v109, 0, v217
	v_pk_fma_f32 v[0:1], v[26:27], v[108:109], v[0:1]
	v_mfma_f32_32x32x16_bf16 v[6:21], v[90:93], v[42:45], v[6:21]
	v_max_f32_e32 v210, 0, v218
	v_max_f32_e32 v211, 0, v219
	v_pk_fma_f32 v[0:1], v[28:29], v[210:211], v[0:1]
	v_max_f32_e32 v108, 0, v220
	v_max_f32_e32 v109, 0, v221
	v_pk_fma_f32 v[0:1], v[30:31], v[108:109], v[0:1]
	v_max_f32_e32 v210, 0, v222
	v_max_f32_e32 v211, 0, v223
	v_pk_fma_f32 v[0:1], v[32:33], v[210:211], v[0:1]
	v_mfma_f32_32x32x16_bf16 v[6:21], v[94:97], v[46:49], v[6:21]
	v_max_f32_e32 v108, 0, v224
	v_max_f32_e32 v109, 0, v225
	v_pk_fma_f32 v[0:1], v[34:35], v[108:109], v[0:1]
	v_max_f32_e32 v210, 0, v226
	v_max_f32_e32 v211, 0, v227
	v_pk_fma_f32 v[0:1], v[36:37], v[210:211], v[0:1]
	v_add_f32_e32 v0, v0, v1
	v_ashrrev_i32_e32 v1, 31, v0
	v_mfma_f32_32x32x16_bf16 v[6:21], v[98:101], v[196:199], v[6:21]
	s_waitcnt vmcnt(10)
	v_add_u32_e32 v228, 0x10000, v5
	ds_read_b128 v[38:41], v228 offset:10496
	v_add_u32_e32 v228, 0x10000, v52
	ds_read_b128 v[42:45], v228 offset:10496
	v_add_u32_e32 v228, 0x10000, v55
	ds_read_b128 v[46:49], v228 offset:10496
	v_add_u32_e32 v228, 0x10000, v56
	ds_read_b128 v[196:199], v228 offset:10496
	v_or_b32_e32 v1, 0x80000000, v1
	s_cmpk_gt_i32 s11, 136
	s_cselect_b64 vcc, -1, 0
	v_xor_b32_e32 v0, v1, v0
	v_cndmask_b32_e32 v148, v123, v0, vcc
	s_nop 3
	s_waitcnt lgkmcnt(3)
	v_mfma_f32_32x32x16_bf16 v[212:227], v[70:73], v[38:41], 0
	v_max_f32_e32 v108, 0, v6
	v_max_f32_e32 v109, 0, v7
	v_pk_mul_f32 v[50:51], v[244:245], v[108:109]
	v_max_f32_e32 v210, 0, v8
	v_max_f32_e32 v211, 0, v9
	v_pk_fma_f32 v[50:51], v[246:247], v[210:211], v[50:51]
	v_max_f32_e32 v108, 0, v10
	v_max_f32_e32 v109, 0, v11
	v_pk_fma_f32 v[50:51], v[248:249], v[108:109], v[50:51]
	s_waitcnt lgkmcnt(2)
	v_mfma_f32_32x32x16_bf16 v[212:227], v[74:77], v[42:45], v[212:227]
	v_max_f32_e32 v210, 0, v12
	v_max_f32_e32 v211, 0, v13
	v_pk_fma_f32 v[50:51], v[250:251], v[210:211], v[50:51]
	v_max_f32_e32 v108, 0, v14
	v_max_f32_e32 v109, 0, v15
	v_pk_fma_f32 v[50:51], v[252:253], v[108:109], v[50:51]
	v_max_f32_e32 v210, 0, v16
	v_max_f32_e32 v211, 0, v17
	v_pk_fma_f32 v[50:51], v[254:255], v[210:211], v[50:51]
	s_waitcnt lgkmcnt(1)
	v_mfma_f32_32x32x16_bf16 v[212:227], v[78:81], v[46:49], v[212:227]
	v_max_f32_e32 v108, 0, v18
	v_max_f32_e32 v109, 0, v19
	v_pk_fma_f32 v[50:51], v[200:201], v[108:109], v[50:51]
	v_max_f32_e32 v210, 0, v20
	v_max_f32_e32 v211, 0, v21
	v_pk_fma_f32 v[50:51], v[202:203], v[210:211], v[50:51]
	v_add_f32_e32 v50, v50, v51
	v_ashrrev_i32_e32 v51, 31, v50
	s_waitcnt lgkmcnt(0)
	v_mfma_f32_32x32x16_bf16 v[212:227], v[82:85], v[196:199], v[212:227]
	v_or_b32_e32 v51, 0x80000000, v51
	s_cmpk_gt_i32 s11, 136
	s_cselect_b64 vcc, -1, 0
	v_xor_b32_e32 v50, v51, v50
	v_cndmask_b32_e32 v50, v123, v50, vcc
	global_store_dword v243, v50, s[8:9] offset:2048
	s_add_u32 s8, s8, 0x1000
	s_addc_u32 s9, s9, 0
	v_mfma_f32_32x32x16_bf16 v[6:21], v[86:89], v[38:41], 0
	s_add_i32 m0, s10, 32768
	s_nop 0
	global_load_lds_dwordx4 v102, s[6:7]
	s_add_i32 m0, s10, 33792
	s_nop 0
	global_load_lds_dwordx4 v110, s[6:7]
	s_add_i32 m0, s10, 34816
	s_nop 0
	global_load_lds_dwordx4 v112, s[6:7]
	s_add_i32 m0, s10, 35840
	s_nop 0
	global_load_lds_dwordx4 v193, s[6:7]
	s_add_u32 s6, s6, 0x8000
	s_addc_u32 s7, s7, 0
	v_max_f32_e32 v108, 0, v212
	v_max_f32_e32 v109, 0, v213
	v_pk_mul_f32 v[0:1], v[22:23], v[108:109]
	v_max_f32_e32 v210, 0, v214
	v_max_f32_e32 v211, 0, v215
	v_pk_fma_f32 v[0:1], v[24:25], v[210:211], v[0:1]
	v_max_f32_e32 v108, 0, v216
	v_max_f32_e32 v109, 0, v217
	v_pk_fma_f32 v[0:1], v[26:27], v[108:109], v[0:1]
	v_mfma_f32_32x32x16_bf16 v[6:21], v[90:93], v[42:45], v[6:21]
	v_max_f32_e32 v210, 0, v218
	v_max_f32_e32 v211, 0, v219
	v_pk_fma_f32 v[0:1], v[28:29], v[210:211], v[0:1]
	v_max_f32_e32 v108, 0, v220
	v_max_f32_e32 v109, 0, v221
	v_pk_fma_f32 v[0:1], v[30:31], v[108:109], v[0:1]
	v_max_f32_e32 v210, 0, v222
	v_max_f32_e32 v211, 0, v223
	v_pk_fma_f32 v[0:1], v[32:33], v[210:211], v[0:1]
	v_mfma_f32_32x32x16_bf16 v[6:21], v[94:97], v[46:49], v[6:21]
	v_max_f32_e32 v108, 0, v224
	v_max_f32_e32 v109, 0, v225
	v_pk_fma_f32 v[0:1], v[34:35], v[108:109], v[0:1]
	v_max_f32_e32 v210, 0, v226
	v_max_f32_e32 v211, 0, v227
	v_pk_fma_f32 v[0:1], v[36:37], v[210:211], v[0:1]
	v_add_f32_e32 v0, v0, v1
	v_ashrrev_i32_e32 v1, 31, v0
	v_mfma_f32_32x32x16_bf16 v[6:21], v[98:101], v[196:199], v[6:21]
	s_waitcnt vmcnt(10)
	v_add_u32_e32 v228, 0x10000, v5
	ds_read_b128 v[38:41], v228 offset:43264
	v_add_u32_e32 v228, 0x10000, v52
	ds_read_b128 v[42:45], v228 offset:43264
	v_add_u32_e32 v228, 0x10000, v55
	ds_read_b128 v[46:49], v228 offset:43264
	v_add_u32_e32 v228, 0x10000, v56
	ds_read_b128 v[196:199], v228 offset:43264
	v_or_b32_e32 v1, 0x80000000, v1
	s_cmpk_gt_i32 s11, 144
	s_cselect_b64 vcc, -1, 0
	v_xor_b32_e32 v0, v1, v0
	v_cndmask_b32_e32 v151, v123, v0, vcc
	s_nop 3
	s_waitcnt lgkmcnt(3)
	v_mfma_f32_32x32x16_bf16 v[212:227], v[70:73], v[38:41], 0
	v_max_f32_e32 v108, 0, v6
	v_max_f32_e32 v109, 0, v7
	v_pk_mul_f32 v[50:51], v[244:245], v[108:109]
	v_max_f32_e32 v210, 0, v8
	v_max_f32_e32 v211, 0, v9
	v_pk_fma_f32 v[50:51], v[246:247], v[210:211], v[50:51]
	v_max_f32_e32 v108, 0, v10
	v_max_f32_e32 v109, 0, v11
	v_pk_fma_f32 v[50:51], v[248:249], v[108:109], v[50:51]
	s_waitcnt lgkmcnt(2)
	v_mfma_f32_32x32x16_bf16 v[212:227], v[74:77], v[42:45], v[212:227]
	v_max_f32_e32 v210, 0, v12
	v_max_f32_e32 v211, 0, v13
	v_pk_fma_f32 v[50:51], v[250:251], v[210:211], v[50:51]
	v_max_f32_e32 v108, 0, v14
	v_max_f32_e32 v109, 0, v15
	v_pk_fma_f32 v[50:51], v[252:253], v[108:109], v[50:51]
	v_max_f32_e32 v210, 0, v16
	v_max_f32_e32 v211, 0, v17
	v_pk_fma_f32 v[50:51], v[254:255], v[210:211], v[50:51]
	s_waitcnt lgkmcnt(1)
	v_mfma_f32_32x32x16_bf16 v[212:227], v[78:81], v[46:49], v[212:227]
	v_max_f32_e32 v108, 0, v18
	v_max_f32_e32 v109, 0, v19
	v_pk_fma_f32 v[50:51], v[200:201], v[108:109], v[50:51]
	v_max_f32_e32 v210, 0, v20
	v_max_f32_e32 v211, 0, v21
	v_pk_fma_f32 v[50:51], v[202:203], v[210:211], v[50:51]
	v_add_f32_e32 v50, v50, v51
	v_ashrrev_i32_e32 v51, 31, v50
	s_waitcnt lgkmcnt(0)
	v_mfma_f32_32x32x16_bf16 v[212:227], v[82:85], v[196:199], v[212:227]
	v_or_b32_e32 v51, 0x80000000, v51
	s_cmpk_gt_i32 s11, 144
	s_cselect_b64 vcc, -1, 0
	v_xor_b32_e32 v50, v51, v50
	v_cndmask_b32_e32 v50, v123, v50, vcc
	global_store_dword v243, v50, s[8:9]
	v_mfma_f32_32x32x16_bf16 v[6:21], v[86:89], v[38:41], 0
	s_add_i32 m0, s10, 65536
	s_nop 0
	global_load_lds_dwordx4 v102, s[6:7]
	s_add_i32 m0, s10, 66560
	s_nop 0
	global_load_lds_dwordx4 v110, s[6:7]
	s_add_i32 m0, s10, 67584
	s_nop 0
	global_load_lds_dwordx4 v112, s[6:7]
	s_add_i32 m0, s10, 68608
	s_nop 0
	global_load_lds_dwordx4 v193, s[6:7]
	s_add_u32 s6, s6, 0x8000
	s_addc_u32 s7, s7, 0
	v_max_f32_e32 v108, 0, v212
	v_max_f32_e32 v109, 0, v213
	v_pk_mul_f32 v[0:1], v[22:23], v[108:109]
	v_max_f32_e32 v210, 0, v214
	v_max_f32_e32 v211, 0, v215
	v_pk_fma_f32 v[0:1], v[24:25], v[210:211], v[0:1]
	v_max_f32_e32 v108, 0, v216
	v_max_f32_e32 v109, 0, v217
	v_pk_fma_f32 v[0:1], v[26:27], v[108:109], v[0:1]
	v_mfma_f32_32x32x16_bf16 v[6:21], v[90:93], v[42:45], v[6:21]
	v_max_f32_e32 v210, 0, v218
	v_max_f32_e32 v211, 0, v219
	v_pk_fma_f32 v[0:1], v[28:29], v[210:211], v[0:1]
	v_max_f32_e32 v108, 0, v220
	v_max_f32_e32 v109, 0, v221
	v_pk_fma_f32 v[0:1], v[30:31], v[108:109], v[0:1]
	v_max_f32_e32 v210, 0, v222
	v_max_f32_e32 v211, 0, v223
	v_pk_fma_f32 v[0:1], v[32:33], v[210:211], v[0:1]
	v_mfma_f32_32x32x16_bf16 v[6:21], v[94:97], v[46:49], v[6:21]
	v_max_f32_e32 v108, 0, v224
	v_max_f32_e32 v109, 0, v225
	v_pk_fma_f32 v[0:1], v[34:35], v[108:109], v[0:1]
	v_max_f32_e32 v210, 0, v226
	v_max_f32_e32 v211, 0, v227
	v_pk_fma_f32 v[0:1], v[36:37], v[210:211], v[0:1]
	v_add_f32_e32 v0, v0, v1
	v_ashrrev_i32_e32 v1, 31, v0
	v_mfma_f32_32x32x16_bf16 v[6:21], v[98:101], v[196:199], v[6:21]
	s_waitcnt vmcnt(10)
	ds_read_b128 v[38:41], v5 offset:10496
	ds_read_b128 v[42:45], v52 offset:10496
	ds_read_b128 v[46:49], v55 offset:10496
	ds_read_b128 v[196:199], v56 offset:10496
	v_or_b32_e32 v1, 0x80000000, v1
	s_cmpk_gt_i32 s11, 152
	s_cselect_b64 vcc, -1, 0
	v_xor_b32_e32 v0, v1, v0
	v_cndmask_b32_e32 v150, v123, v0, vcc
	s_nop 3
	s_waitcnt lgkmcnt(3)
	v_mfma_f32_32x32x16_bf16 v[212:227], v[70:73], v[38:41], 0
	v_max_f32_e32 v108, 0, v6
	v_max_f32_e32 v109, 0, v7
	v_pk_mul_f32 v[50:51], v[244:245], v[108:109]
	v_max_f32_e32 v210, 0, v8
	v_max_f32_e32 v211, 0, v9
	v_pk_fma_f32 v[50:51], v[246:247], v[210:211], v[50:51]
	v_max_f32_e32 v108, 0, v10
	v_max_f32_e32 v109, 0, v11
	v_pk_fma_f32 v[50:51], v[248:249], v[108:109], v[50:51]
	s_waitcnt lgkmcnt(2)
	v_mfma_f32_32x32x16_bf16 v[212:227], v[74:77], v[42:45], v[212:227]
	v_max_f32_e32 v210, 0, v12
	v_max_f32_e32 v211, 0, v13
	v_pk_fma_f32 v[50:51], v[250:251], v[210:211], v[50:51]
	v_max_f32_e32 v108, 0, v14
	v_max_f32_e32 v109, 0, v15
	v_pk_fma_f32 v[50:51], v[252:253], v[108:109], v[50:51]
	v_max_f32_e32 v210, 0, v16
	v_max_f32_e32 v211, 0, v17
	v_pk_fma_f32 v[50:51], v[254:255], v[210:211], v[50:51]
	s_waitcnt lgkmcnt(1)
	v_mfma_f32_32x32x16_bf16 v[212:227], v[78:81], v[46:49], v[212:227]
	v_max_f32_e32 v108, 0, v18
	v_max_f32_e32 v109, 0, v19
	v_pk_fma_f32 v[50:51], v[200:201], v[108:109], v[50:51]
	v_max_f32_e32 v210, 0, v20
	v_max_f32_e32 v211, 0, v21
	v_pk_fma_f32 v[50:51], v[202:203], v[210:211], v[50:51]
	v_add_f32_e32 v50, v50, v51
	v_ashrrev_i32_e32 v51, 31, v50
	s_waitcnt lgkmcnt(0)
	v_mfma_f32_32x32x16_bf16 v[212:227], v[82:85], v[196:199], v[212:227]
	v_or_b32_e32 v51, 0x80000000, v51
	s_cmpk_gt_i32 s11, 152
	s_cselect_b64 vcc, -1, 0
	v_xor_b32_e32 v50, v51, v50
	v_cndmask_b32_e32 v50, v123, v50, vcc
	global_store_dword v243, v50, s[8:9] offset:2048
	s_add_u32 s8, s8, 0x1000
	s_addc_u32 s9, s9, 0
	v_mfma_f32_32x32x16_bf16 v[6:21], v[86:89], v[38:41], 0
	s_add_i32 m0, s10, 98304
	s_nop 0
	global_load_lds_dwordx4 v102, s[6:7]
	s_add_i32 m0, s10, 99328
	s_nop 0
	global_load_lds_dwordx4 v110, s[6:7]
	s_add_i32 m0, s10, 100352
	s_nop 0
	global_load_lds_dwordx4 v112, s[6:7]
	s_add_i32 m0, s10, 101376
	s_nop 0
	global_load_lds_dwordx4 v193, s[6:7]
	s_add_u32 s6, s6, 0x8000
	s_addc_u32 s7, s7, 0
	v_max_f32_e32 v108, 0, v212
	v_max_f32_e32 v109, 0, v213
	v_pk_mul_f32 v[0:1], v[22:23], v[108:109]
	v_max_f32_e32 v210, 0, v214
	v_max_f32_e32 v211, 0, v215
	v_pk_fma_f32 v[0:1], v[24:25], v[210:211], v[0:1]
	v_max_f32_e32 v108, 0, v216
	v_max_f32_e32 v109, 0, v217
	v_pk_fma_f32 v[0:1], v[26:27], v[108:109], v[0:1]
	v_mfma_f32_32x32x16_bf16 v[6:21], v[90:93], v[42:45], v[6:21]
	v_max_f32_e32 v210, 0, v218
	v_max_f32_e32 v211, 0, v219
	v_pk_fma_f32 v[0:1], v[28:29], v[210:211], v[0:1]
	v_max_f32_e32 v108, 0, v220
	v_max_f32_e32 v109, 0, v221
	v_pk_fma_f32 v[0:1], v[30:31], v[108:109], v[0:1]
	v_max_f32_e32 v210, 0, v222
	v_max_f32_e32 v211, 0, v223
	v_pk_fma_f32 v[0:1], v[32:33], v[210:211], v[0:1]
	v_mfma_f32_32x32x16_bf16 v[6:21], v[94:97], v[46:49], v[6:21]
	v_max_f32_e32 v108, 0, v224
	v_max_f32_e32 v109, 0, v225
	v_pk_fma_f32 v[0:1], v[34:35], v[108:109], v[0:1]
	v_max_f32_e32 v210, 0, v226
	v_max_f32_e32 v211, 0, v227
	v_pk_fma_f32 v[0:1], v[36:37], v[210:211], v[0:1]
	v_add_f32_e32 v0, v0, v1
	v_ashrrev_i32_e32 v1, 31, v0
	v_mfma_f32_32x32x16_bf16 v[6:21], v[98:101], v[196:199], v[6:21]
	s_waitcnt vmcnt(10)
	ds_read_b128 v[38:41], v5 offset:43264
	ds_read_b128 v[42:45], v52 offset:43264
	ds_read_b128 v[46:49], v55 offset:43264
	ds_read_b128 v[196:199], v56 offset:43264
	v_or_b32_e32 v1, 0x80000000, v1
	s_cmpk_gt_i32 s11, 160
	s_cselect_b64 vcc, -1, 0
	v_xor_b32_e32 v0, v1, v0
	v_cndmask_b32_e32 v154, v123, v0, vcc
	s_nop 3
	s_waitcnt lgkmcnt(3)
	v_mfma_f32_32x32x16_bf16 v[212:227], v[70:73], v[38:41], 0
	v_max_f32_e32 v108, 0, v6
	v_max_f32_e32 v109, 0, v7
	v_pk_mul_f32 v[50:51], v[244:245], v[108:109]
	v_max_f32_e32 v210, 0, v8
	v_max_f32_e32 v211, 0, v9
	v_pk_fma_f32 v[50:51], v[246:247], v[210:211], v[50:51]
	v_max_f32_e32 v108, 0, v10
	v_max_f32_e32 v109, 0, v11
	v_pk_fma_f32 v[50:51], v[248:249], v[108:109], v[50:51]
	s_waitcnt lgkmcnt(2)
	v_mfma_f32_32x32x16_bf16 v[212:227], v[74:77], v[42:45], v[212:227]
	v_max_f32_e32 v210, 0, v12
	v_max_f32_e32 v211, 0, v13
	v_pk_fma_f32 v[50:51], v[250:251], v[210:211], v[50:51]
	v_max_f32_e32 v108, 0, v14
	v_max_f32_e32 v109, 0, v15
	v_pk_fma_f32 v[50:51], v[252:253], v[108:109], v[50:51]
	v_max_f32_e32 v210, 0, v16
	v_max_f32_e32 v211, 0, v17
	v_pk_fma_f32 v[50:51], v[254:255], v[210:211], v[50:51]
	s_waitcnt lgkmcnt(1)
	v_mfma_f32_32x32x16_bf16 v[212:227], v[78:81], v[46:49], v[212:227]
	v_max_f32_e32 v108, 0, v18
	v_max_f32_e32 v109, 0, v19
	v_pk_fma_f32 v[50:51], v[200:201], v[108:109], v[50:51]
	v_max_f32_e32 v210, 0, v20
	v_max_f32_e32 v211, 0, v21
	v_pk_fma_f32 v[50:51], v[202:203], v[210:211], v[50:51]
	v_add_f32_e32 v50, v50, v51
	v_ashrrev_i32_e32 v51, 31, v50
	s_waitcnt lgkmcnt(0)
	v_mfma_f32_32x32x16_bf16 v[212:227], v[82:85], v[196:199], v[212:227]
	v_or_b32_e32 v51, 0x80000000, v51
	s_cmpk_gt_i32 s11, 160
	s_cselect_b64 vcc, -1, 0
	v_xor_b32_e32 v50, v51, v50
	v_cndmask_b32_e32 v50, v123, v50, vcc
	global_store_dword v243, v50, s[8:9]
	v_mfma_f32_32x32x16_bf16 v[6:21], v[86:89], v[38:41], 0
	s_add_i32 m0, s10, 0
	s_nop 0
	global_load_lds_dwordx4 v102, s[6:7]
	s_add_i32 m0, s10, 1024
	s_nop 0
	global_load_lds_dwordx4 v110, s[6:7]
	s_add_i32 m0, s10, 2048
	s_nop 0
	global_load_lds_dwordx4 v112, s[6:7]
	s_add_i32 m0, s10, 3072
	s_nop 0
	global_load_lds_dwordx4 v193, s[6:7]
	s_add_u32 s6, s6, 0x8000
	s_addc_u32 s7, s7, 0
	v_max_f32_e32 v108, 0, v212
	v_max_f32_e32 v109, 0, v213
	v_pk_mul_f32 v[0:1], v[22:23], v[108:109]
	v_max_f32_e32 v210, 0, v214
	v_max_f32_e32 v211, 0, v215
	v_pk_fma_f32 v[0:1], v[24:25], v[210:211], v[0:1]
	v_max_f32_e32 v108, 0, v216
	v_max_f32_e32 v109, 0, v217
	v_pk_fma_f32 v[0:1], v[26:27], v[108:109], v[0:1]
	v_mfma_f32_32x32x16_bf16 v[6:21], v[90:93], v[42:45], v[6:21]
	v_max_f32_e32 v210, 0, v218
	v_max_f32_e32 v211, 0, v219
	v_pk_fma_f32 v[0:1], v[28:29], v[210:211], v[0:1]
	v_max_f32_e32 v108, 0, v220
	v_max_f32_e32 v109, 0, v221
	v_pk_fma_f32 v[0:1], v[30:31], v[108:109], v[0:1]
	v_max_f32_e32 v210, 0, v222
	v_max_f32_e32 v211, 0, v223
	v_pk_fma_f32 v[0:1], v[32:33], v[210:211], v[0:1]
	v_mfma_f32_32x32x16_bf16 v[6:21], v[94:97], v[46:49], v[6:21]
	v_max_f32_e32 v108, 0, v224
	v_max_f32_e32 v109, 0, v225
	v_pk_fma_f32 v[0:1], v[34:35], v[108:109], v[0:1]
	v_max_f32_e32 v210, 0, v226
	v_max_f32_e32 v211, 0, v227
	v_pk_fma_f32 v[0:1], v[36:37], v[210:211], v[0:1]
	v_add_f32_e32 v0, v0, v1
	v_ashrrev_i32_e32 v1, 31, v0
	v_mfma_f32_32x32x16_bf16 v[6:21], v[98:101], v[196:199], v[6:21]
	s_waitcnt vmcnt(10)
	v_add_u32_e32 v228, 0x10000, v5
	ds_read_b128 v[38:41], v228 offset:10496
	v_add_u32_e32 v228, 0x10000, v52
	ds_read_b128 v[42:45], v228 offset:10496
	v_add_u32_e32 v228, 0x10000, v55
	ds_read_b128 v[46:49], v228 offset:10496
	v_add_u32_e32 v228, 0x10000, v56
	ds_read_b128 v[196:199], v228 offset:10496
	v_or_b32_e32 v1, 0x80000000, v1
	s_cmpk_gt_i32 s11, 168
	s_cselect_b64 vcc, -1, 0
	v_xor_b32_e32 v0, v1, v0
	v_cndmask_b32_e32 v153, v123, v0, vcc
	s_nop 3
	s_waitcnt lgkmcnt(3)
	v_mfma_f32_32x32x16_bf16 v[212:227], v[70:73], v[38:41], 0
	v_max_f32_e32 v108, 0, v6
	v_max_f32_e32 v109, 0, v7
	v_pk_mul_f32 v[50:51], v[244:245], v[108:109]
	v_max_f32_e32 v210, 0, v8
	v_max_f32_e32 v211, 0, v9
	v_pk_fma_f32 v[50:51], v[246:247], v[210:211], v[50:51]
	v_max_f32_e32 v108, 0, v10
	v_max_f32_e32 v109, 0, v11
	v_pk_fma_f32 v[50:51], v[248:249], v[108:109], v[50:51]
	s_waitcnt lgkmcnt(2)
	v_mfma_f32_32x32x16_bf16 v[212:227], v[74:77], v[42:45], v[212:227]
	v_max_f32_e32 v210, 0, v12
	v_max_f32_e32 v211, 0, v13
	v_pk_fma_f32 v[50:51], v[250:251], v[210:211], v[50:51]
	v_max_f32_e32 v108, 0, v14
	v_max_f32_e32 v109, 0, v15
	v_pk_fma_f32 v[50:51], v[252:253], v[108:109], v[50:51]
	v_max_f32_e32 v210, 0, v16
	v_max_f32_e32 v211, 0, v17
	v_pk_fma_f32 v[50:51], v[254:255], v[210:211], v[50:51]
	s_waitcnt lgkmcnt(1)
	v_mfma_f32_32x32x16_bf16 v[212:227], v[78:81], v[46:49], v[212:227]
	v_max_f32_e32 v108, 0, v18
	v_max_f32_e32 v109, 0, v19
	v_pk_fma_f32 v[50:51], v[200:201], v[108:109], v[50:51]
	v_max_f32_e32 v210, 0, v20
	v_max_f32_e32 v211, 0, v21
	v_pk_fma_f32 v[50:51], v[202:203], v[210:211], v[50:51]
	v_add_f32_e32 v50, v50, v51
	v_ashrrev_i32_e32 v51, 31, v50
	s_waitcnt lgkmcnt(0)
	v_mfma_f32_32x32x16_bf16 v[212:227], v[82:85], v[196:199], v[212:227]
	v_or_b32_e32 v51, 0x80000000, v51
	s_cmpk_gt_i32 s11, 168
	s_cselect_b64 vcc, -1, 0
	v_xor_b32_e32 v50, v51, v50
	v_cndmask_b32_e32 v50, v123, v50, vcc
	global_store_dword v243, v50, s[8:9] offset:2048
	s_add_u32 s8, s8, 0x1000
	s_addc_u32 s9, s9, 0
	v_mfma_f32_32x32x16_bf16 v[6:21], v[86:89], v[38:41], 0
	s_add_i32 m0, s10, 32768
	s_nop 0
	global_load_lds_dwordx4 v102, s[6:7]
	s_add_i32 m0, s10, 33792
	s_nop 0
	global_load_lds_dwordx4 v110, s[6:7]
	s_add_i32 m0, s10, 34816
	s_nop 0
	global_load_lds_dwordx4 v112, s[6:7]
	s_add_i32 m0, s10, 35840
	s_nop 0
	global_load_lds_dwordx4 v193, s[6:7]
	s_add_u32 s6, s6, 0x8000
	s_addc_u32 s7, s7, 0
	v_max_f32_e32 v108, 0, v212
	v_max_f32_e32 v109, 0, v213
	v_pk_mul_f32 v[0:1], v[22:23], v[108:109]
	v_max_f32_e32 v210, 0, v214
	v_max_f32_e32 v211, 0, v215
	v_pk_fma_f32 v[0:1], v[24:25], v[210:211], v[0:1]
	v_max_f32_e32 v108, 0, v216
	v_max_f32_e32 v109, 0, v217
	v_pk_fma_f32 v[0:1], v[26:27], v[108:109], v[0:1]
	v_mfma_f32_32x32x16_bf16 v[6:21], v[90:93], v[42:45], v[6:21]
	v_max_f32_e32 v210, 0, v218
	v_max_f32_e32 v211, 0, v219
	v_pk_fma_f32 v[0:1], v[28:29], v[210:211], v[0:1]
	v_max_f32_e32 v108, 0, v220
	v_max_f32_e32 v109, 0, v221
	v_pk_fma_f32 v[0:1], v[30:31], v[108:109], v[0:1]
	v_max_f32_e32 v210, 0, v222
	v_max_f32_e32 v211, 0, v223
	v_pk_fma_f32 v[0:1], v[32:33], v[210:211], v[0:1]
	v_mfma_f32_32x32x16_bf16 v[6:21], v[94:97], v[46:49], v[6:21]
	v_max_f32_e32 v108, 0, v224
	v_max_f32_e32 v109, 0, v225
	v_pk_fma_f32 v[0:1], v[34:35], v[108:109], v[0:1]
	v_max_f32_e32 v210, 0, v226
	v_max_f32_e32 v211, 0, v227
	v_pk_fma_f32 v[0:1], v[36:37], v[210:211], v[0:1]
	v_add_f32_e32 v0, v0, v1
	v_ashrrev_i32_e32 v1, 31, v0
	v_mfma_f32_32x32x16_bf16 v[6:21], v[98:101], v[196:199], v[6:21]
	s_waitcnt vmcnt(10)
	v_add_u32_e32 v228, 0x10000, v5
	ds_read_b128 v[38:41], v228 offset:43264
	v_add_u32_e32 v228, 0x10000, v52
	ds_read_b128 v[42:45], v228 offset:43264
	v_add_u32_e32 v228, 0x10000, v55
	ds_read_b128 v[46:49], v228 offset:43264
	v_add_u32_e32 v228, 0x10000, v56
	ds_read_b128 v[196:199], v228 offset:43264
	v_or_b32_e32 v1, 0x80000000, v1
	s_cmpk_gt_i32 s11, 176
	s_cselect_b64 vcc, -1, 0
	v_xor_b32_e32 v0, v1, v0
	v_cndmask_b32_e32 v156, v123, v0, vcc
	s_nop 3
	s_waitcnt lgkmcnt(3)
	v_mfma_f32_32x32x16_bf16 v[212:227], v[70:73], v[38:41], 0
	v_max_f32_e32 v108, 0, v6
	v_max_f32_e32 v109, 0, v7
	v_pk_mul_f32 v[50:51], v[244:245], v[108:109]
	v_max_f32_e32 v210, 0, v8
	v_max_f32_e32 v211, 0, v9
	v_pk_fma_f32 v[50:51], v[246:247], v[210:211], v[50:51]
	v_max_f32_e32 v108, 0, v10
	v_max_f32_e32 v109, 0, v11
	v_pk_fma_f32 v[50:51], v[248:249], v[108:109], v[50:51]
	s_waitcnt lgkmcnt(2)
	v_mfma_f32_32x32x16_bf16 v[212:227], v[74:77], v[42:45], v[212:227]
	v_max_f32_e32 v210, 0, v12
	v_max_f32_e32 v211, 0, v13
	v_pk_fma_f32 v[50:51], v[250:251], v[210:211], v[50:51]
	v_max_f32_e32 v108, 0, v14
	v_max_f32_e32 v109, 0, v15
	v_pk_fma_f32 v[50:51], v[252:253], v[108:109], v[50:51]
	v_max_f32_e32 v210, 0, v16
	v_max_f32_e32 v211, 0, v17
	v_pk_fma_f32 v[50:51], v[254:255], v[210:211], v[50:51]
	s_waitcnt lgkmcnt(1)
	v_mfma_f32_32x32x16_bf16 v[212:227], v[78:81], v[46:49], v[212:227]
	v_max_f32_e32 v108, 0, v18
	v_max_f32_e32 v109, 0, v19
	v_pk_fma_f32 v[50:51], v[200:201], v[108:109], v[50:51]
	v_max_f32_e32 v210, 0, v20
	v_max_f32_e32 v211, 0, v21
	v_pk_fma_f32 v[50:51], v[202:203], v[210:211], v[50:51]
	v_add_f32_e32 v50, v50, v51
	v_ashrrev_i32_e32 v51, 31, v50
	s_waitcnt lgkmcnt(0)
	v_mfma_f32_32x32x16_bf16 v[212:227], v[82:85], v[196:199], v[212:227]
	v_or_b32_e32 v51, 0x80000000, v51
	s_cmpk_gt_i32 s11, 176
	s_cselect_b64 vcc, -1, 0
	v_xor_b32_e32 v50, v51, v50
	v_cndmask_b32_e32 v50, v123, v50, vcc
	global_store_dword v243, v50, s[8:9]
	v_mfma_f32_32x32x16_bf16 v[6:21], v[86:89], v[38:41], 0
	s_add_i32 m0, s10, 65536
	s_nop 0
	global_load_lds_dwordx4 v102, s[6:7]
	s_add_i32 m0, s10, 66560
	s_nop 0
	global_load_lds_dwordx4 v110, s[6:7]
	s_add_i32 m0, s10, 67584
	s_nop 0
	global_load_lds_dwordx4 v112, s[6:7]
	s_add_i32 m0, s10, 68608
	s_nop 0
	global_load_lds_dwordx4 v193, s[6:7]
	s_add_u32 s6, s6, 0x8000
	s_addc_u32 s7, s7, 0
	v_max_f32_e32 v108, 0, v212
	v_max_f32_e32 v109, 0, v213
	v_pk_mul_f32 v[0:1], v[22:23], v[108:109]
	v_max_f32_e32 v210, 0, v214
	v_max_f32_e32 v211, 0, v215
	v_pk_fma_f32 v[0:1], v[24:25], v[210:211], v[0:1]
	v_max_f32_e32 v108, 0, v216
	v_max_f32_e32 v109, 0, v217
	v_pk_fma_f32 v[0:1], v[26:27], v[108:109], v[0:1]
	v_mfma_f32_32x32x16_bf16 v[6:21], v[90:93], v[42:45], v[6:21]
	v_max_f32_e32 v210, 0, v218
	v_max_f32_e32 v211, 0, v219
	v_pk_fma_f32 v[0:1], v[28:29], v[210:211], v[0:1]
	v_max_f32_e32 v108, 0, v220
	v_max_f32_e32 v109, 0, v221
	v_pk_fma_f32 v[0:1], v[30:31], v[108:109], v[0:1]
	v_max_f32_e32 v210, 0, v222
	v_max_f32_e32 v211, 0, v223
	v_pk_fma_f32 v[0:1], v[32:33], v[210:211], v[0:1]
	v_mfma_f32_32x32x16_bf16 v[6:21], v[94:97], v[46:49], v[6:21]
	v_max_f32_e32 v108, 0, v224
	v_max_f32_e32 v109, 0, v225
	v_pk_fma_f32 v[0:1], v[34:35], v[108:109], v[0:1]
	v_max_f32_e32 v210, 0, v226
	v_max_f32_e32 v211, 0, v227
	v_pk_fma_f32 v[0:1], v[36:37], v[210:211], v[0:1]
	v_add_f32_e32 v0, v0, v1
	v_ashrrev_i32_e32 v1, 31, v0
	v_mfma_f32_32x32x16_bf16 v[6:21], v[98:101], v[196:199], v[6:21]
	s_waitcnt vmcnt(10)
	ds_read_b128 v[38:41], v5 offset:10496
	ds_read_b128 v[42:45], v52 offset:10496
	ds_read_b128 v[46:49], v55 offset:10496
	ds_read_b128 v[196:199], v56 offset:10496
	v_or_b32_e32 v1, 0x80000000, v1
	s_cmpk_gt_i32 s11, 184
	s_cselect_b64 vcc, -1, 0
	v_xor_b32_e32 v0, v1, v0
	v_cndmask_b32_e32 v155, v123, v0, vcc
	s_nop 3
	v_max_f32_e32 v108, 0, v6
	v_max_f32_e32 v109, 0, v7
	v_pk_mul_f32 v[50:51], v[244:245], v[108:109]
	v_max_f32_e32 v210, 0, v8
	v_max_f32_e32 v211, 0, v9
	v_pk_fma_f32 v[50:51], v[246:247], v[210:211], v[50:51]
	v_max_f32_e32 v108, 0, v10
	v_max_f32_e32 v109, 0, v11
	v_pk_fma_f32 v[50:51], v[248:249], v[108:109], v[50:51]
	v_max_f32_e32 v210, 0, v12
	v_max_f32_e32 v211, 0, v13
	v_pk_fma_f32 v[50:51], v[250:251], v[210:211], v[50:51]
	v_max_f32_e32 v108, 0, v14
	v_max_f32_e32 v109, 0, v15
	v_pk_fma_f32 v[50:51], v[252:253], v[108:109], v[50:51]
	v_max_f32_e32 v210, 0, v16
	v_max_f32_e32 v211, 0, v17
	v_pk_fma_f32 v[50:51], v[254:255], v[210:211], v[50:51]
	v_max_f32_e32 v108, 0, v18
	v_max_f32_e32 v109, 0, v19
	v_pk_fma_f32 v[50:51], v[200:201], v[108:109], v[50:51]
	v_max_f32_e32 v210, 0, v20
	v_max_f32_e32 v211, 0, v21
	v_pk_fma_f32 v[50:51], v[202:203], v[210:211], v[50:51]
	v_add_f32_e32 v50, v50, v51
	v_ashrrev_i32_e32 v51, 31, v50
	v_or_b32_e32 v51, 0x80000000, v51
	s_cmpk_gt_i32 s11, 184
	s_cselect_b64 vcc, -1, 0
	v_xor_b32_e32 v50, v51, v50
	v_cndmask_b32_e32 v50, v123, v50, vcc
	global_store_dword v243, v50, s[8:9] offset:2048
	s_add_u32 s8, s8, 0x1000
	s_addc_u32 s9, s9, 0
	s_cmpk_gt_i32 s81, 24
	s_cbranch_scc0 .Lix_fill_3
	s_waitcnt lgkmcnt(3)
	v_mfma_f32_32x32x16_bf16 v[212:227], v[70:73], v[38:41], 0
	s_add_i32 m0, s10, 98304
	s_nop 0
	global_load_lds_dwordx4 v102, s[6:7]
	s_waitcnt lgkmcnt(2)
	v_mfma_f32_32x32x16_bf16 v[212:227], v[74:77], v[42:45], v[212:227]
	s_add_i32 m0, s10, 99328
	s_nop 0
	global_load_lds_dwordx4 v110, s[6:7]
	s_waitcnt lgkmcnt(1)
	v_mfma_f32_32x32x16_bf16 v[212:227], v[78:81], v[46:49], v[212:227]
	s_add_i32 m0, s10, 100352
	s_nop 0
	global_load_lds_dwordx4 v112, s[6:7]
	s_waitcnt lgkmcnt(0)
	v_mfma_f32_32x32x16_bf16 v[212:227], v[82:85], v[196:199], v[212:227]
	s_add_i32 m0, s10, 101376
	s_nop 0
	global_load_lds_dwordx4 v193, s[6:7]
	s_add_u32 s6, s6, 0x8000
	s_addc_u32 s7, s7, 0
	v_mfma_f32_32x32x16_bf16 v[6:21], v[86:89], v[38:41], 0
	s_nop 7
	s_nop 2
	v_max_f32_e32 v108, 0, v212
	v_max_f32_e32 v109, 0, v213
	v_pk_mul_f32 v[0:1], v[22:23], v[108:109]
	v_max_f32_e32 v210, 0, v214
	v_max_f32_e32 v211, 0, v215
	v_pk_fma_f32 v[0:1], v[24:25], v[210:211], v[0:1]
	v_max_f32_e32 v108, 0, v216
	v_max_f32_e32 v109, 0, v217
	v_pk_fma_f32 v[0:1], v[26:27], v[108:109], v[0:1]
	v_mfma_f32_32x32x16_bf16 v[6:21], v[90:93], v[42:45], v[6:21]
	v_max_f32_e32 v210, 0, v218
	v_max_f32_e32 v211, 0, v219
	v_pk_fma_f32 v[0:1], v[28:29], v[210:211], v[0:1]
	v_max_f32_e32 v108, 0, v220
	v_max_f32_e32 v109, 0, v221
	v_pk_fma_f32 v[0:1], v[30:31], v[108:109], v[0:1]
	v_max_f32_e32 v210, 0, v222
	v_max_f32_e32 v211, 0, v223
	v_pk_fma_f32 v[0:1], v[32:33], v[210:211], v[0:1]
	v_mfma_f32_32x32x16_bf16 v[6:21], v[94:97], v[46:49], v[6:21]
	v_max_f32_e32 v108, 0, v224
	v_max_f32_e32 v109, 0, v225
	v_pk_fma_f32 v[0:1], v[34:35], v[108:109], v[0:1]
	v_max_f32_e32 v210, 0, v226
	v_max_f32_e32 v211, 0, v227
	v_pk_fma_f32 v[0:1], v[36:37], v[210:211], v[0:1]
	v_add_f32_e32 v0, v0, v1
	v_ashrrev_i32_e32 v1, 31, v0
	v_mfma_f32_32x32x16_bf16 v[6:21], v[98:101], v[196:199], v[6:21]
	s_waitcnt vmcnt(10)
	ds_read_b128 v[38:41], v5 offset:43264
	ds_read_b128 v[42:45], v52 offset:43264
	ds_read_b128 v[46:49], v55 offset:43264
	ds_read_b128 v[196:199], v56 offset:43264
	v_or_b32_e32 v1, 0x80000000, v1
	s_cmpk_gt_i32 s11, 192
	s_cselect_b64 vcc, -1, 0
	v_xor_b32_e32 v0, v1, v0
	v_cndmask_b32_e32 v158, v123, v0, vcc
	s_nop 3
	s_waitcnt lgkmcnt(3)
	v_mfma_f32_32x32x16_bf16 v[212:227], v[70:73], v[38:41], 0
	v_max_f32_e32 v108, 0, v6
	v_max_f32_e32 v109, 0, v7
	v_pk_mul_f32 v[50:51], v[244:245], v[108:109]
	v_max_f32_e32 v210, 0, v8
	v_max_f32_e32 v211, 0, v9
	v_pk_fma_f32 v[50:51], v[246:247], v[210:211], v[50:51]
	v_max_f32_e32 v108, 0, v10
	v_max_f32_e32 v109, 0, v11
	v_pk_fma_f32 v[50:51], v[248:249], v[108:109], v[50:51]
	s_waitcnt lgkmcnt(2)
	v_mfma_f32_32x32x16_bf16 v[212:227], v[74:77], v[42:45], v[212:227]
	v_max_f32_e32 v210, 0, v12
	v_max_f32_e32 v211, 0, v13
	v_pk_fma_f32 v[50:51], v[250:251], v[210:211], v[50:51]
	v_max_f32_e32 v108, 0, v14
	v_max_f32_e32 v109, 0, v15
	v_pk_fma_f32 v[50:51], v[252:253], v[108:109], v[50:51]
	v_max_f32_e32 v210, 0, v16
	v_max_f32_e32 v211, 0, v17
	v_pk_fma_f32 v[50:51], v[254:255], v[210:211], v[50:51]
	s_waitcnt lgkmcnt(1)
	v_mfma_f32_32x32x16_bf16 v[212:227], v[78:81], v[46:49], v[212:227]
	v_max_f32_e32 v108, 0, v18
	v_max_f32_e32 v109, 0, v19
	v_pk_fma_f32 v[50:51], v[200:201], v[108:109], v[50:51]
	v_max_f32_e32 v210, 0, v20
	v_max_f32_e32 v211, 0, v21
	v_pk_fma_f32 v[50:51], v[202:203], v[210:211], v[50:51]
	v_add_f32_e32 v50, v50, v51
	v_ashrrev_i32_e32 v51, 31, v50
	s_waitcnt lgkmcnt(0)
	v_mfma_f32_32x32x16_bf16 v[212:227], v[82:85], v[196:199], v[212:227]
	v_or_b32_e32 v51, 0x80000000, v51
	s_cmpk_gt_i32 s11, 192
	s_cselect_b64 vcc, -1, 0
	v_xor_b32_e32 v50, v51, v50
	v_cndmask_b32_e32 v50, v123, v50, vcc
	global_store_dword v243, v50, s[8:9]
	v_mfma_f32_32x32x16_bf16 v[6:21], v[86:89], v[38:41], 0
	s_add_i32 m0, s10, 0
	s_nop 0
	global_load_lds_dwordx4 v102, s[6:7]
	s_add_i32 m0, s10, 1024
	s_nop 0
	global_load_lds_dwordx4 v110, s[6:7]
	s_add_i32 m0, s10, 2048
	s_nop 0
	global_load_lds_dwordx4 v112, s[6:7]
	s_add_i32 m0, s10, 3072
	s_nop 0
	global_load_lds_dwordx4 v193, s[6:7]
	s_add_u32 s6, s6, 0x8000
	s_addc_u32 s7, s7, 0
	v_max_f32_e32 v108, 0, v212
	v_max_f32_e32 v109, 0, v213
	v_pk_mul_f32 v[0:1], v[22:23], v[108:109]
	v_max_f32_e32 v210, 0, v214
	v_max_f32_e32 v211, 0, v215
	v_pk_fma_f32 v[0:1], v[24:25], v[210:211], v[0:1]
	v_max_f32_e32 v108, 0, v216
	v_max_f32_e32 v109, 0, v217
	v_pk_fma_f32 v[0:1], v[26:27], v[108:109], v[0:1]
	v_mfma_f32_32x32x16_bf16 v[6:21], v[90:93], v[42:45], v[6:21]
	v_max_f32_e32 v210, 0, v218
	v_max_f32_e32 v211, 0, v219
	v_pk_fma_f32 v[0:1], v[28:29], v[210:211], v[0:1]
	v_max_f32_e32 v108, 0, v220
	v_max_f32_e32 v109, 0, v221
	v_pk_fma_f32 v[0:1], v[30:31], v[108:109], v[0:1]
	v_max_f32_e32 v210, 0, v222
	v_max_f32_e32 v211, 0, v223
	v_pk_fma_f32 v[0:1], v[32:33], v[210:211], v[0:1]
	v_mfma_f32_32x32x16_bf16 v[6:21], v[94:97], v[46:49], v[6:21]
	v_max_f32_e32 v108, 0, v224
	v_max_f32_e32 v109, 0, v225
	v_pk_fma_f32 v[0:1], v[34:35], v[108:109], v[0:1]
	v_max_f32_e32 v210, 0, v226
	v_max_f32_e32 v211, 0, v227
	v_pk_fma_f32 v[0:1], v[36:37], v[210:211], v[0:1]
	v_add_f32_e32 v0, v0, v1
	v_ashrrev_i32_e32 v1, 31, v0
	v_mfma_f32_32x32x16_bf16 v[6:21], v[98:101], v[196:199], v[6:21]
	s_waitcnt vmcnt(10)
	v_add_u32_e32 v228, 0x10000, v5
	ds_read_b128 v[38:41], v228 offset:10496
	v_add_u32_e32 v228, 0x10000, v52
	ds_read_b128 v[42:45], v228 offset:10496
	v_add_u32_e32 v228, 0x10000, v55
	ds_read_b128 v[46:49], v228 offset:10496
	v_add_u32_e32 v228, 0x10000, v56
	ds_read_b128 v[196:199], v228 offset:10496
	v_or_b32_e32 v1, 0x80000000, v1
	s_cmpk_gt_i32 s11, 200
	s_cselect_b64 vcc, -1, 0
	v_xor_b32_e32 v0, v1, v0
	v_cndmask_b32_e32 v157, v123, v0, vcc
	s_nop 3
	s_waitcnt lgkmcnt(3)
	v_mfma_f32_32x32x16_bf16 v[212:227], v[70:73], v[38:41], 0
	v_max_f32_e32 v108, 0, v6
	v_max_f32_e32 v109, 0, v7
	v_pk_mul_f32 v[50:51], v[244:245], v[108:109]
	v_max_f32_e32 v210, 0, v8
	v_max_f32_e32 v211, 0, v9
	v_pk_fma_f32 v[50:51], v[246:247], v[210:211], v[50:51]
	v_max_f32_e32 v108, 0, v10
	v_max_f32_e32 v109, 0, v11
	v_pk_fma_f32 v[50:51], v[248:249], v[108:109], v[50:51]
	s_waitcnt lgkmcnt(2)
	v_mfma_f32_32x32x16_bf16 v[212:227], v[74:77], v[42:45], v[212:227]
	v_max_f32_e32 v210, 0, v12
	v_max_f32_e32 v211, 0, v13
	v_pk_fma_f32 v[50:51], v[250:251], v[210:211], v[50:51]
	v_max_f32_e32 v108, 0, v14
	v_max_f32_e32 v109, 0, v15
	v_pk_fma_f32 v[50:51], v[252:253], v[108:109], v[50:51]
	v_max_f32_e32 v210, 0, v16
	v_max_f32_e32 v211, 0, v17
	v_pk_fma_f32 v[50:51], v[254:255], v[210:211], v[50:51]
	s_waitcnt lgkmcnt(1)
	v_mfma_f32_32x32x16_bf16 v[212:227], v[78:81], v[46:49], v[212:227]
	v_max_f32_e32 v108, 0, v18
	v_max_f32_e32 v109, 0, v19
	v_pk_fma_f32 v[50:51], v[200:201], v[108:109], v[50:51]
	v_max_f32_e32 v210, 0, v20
	v_max_f32_e32 v211, 0, v21
	v_pk_fma_f32 v[50:51], v[202:203], v[210:211], v[50:51]
	v_add_f32_e32 v50, v50, v51
	v_ashrrev_i32_e32 v51, 31, v50
	s_waitcnt lgkmcnt(0)
	v_mfma_f32_32x32x16_bf16 v[212:227], v[82:85], v[196:199], v[212:227]
	v_or_b32_e32 v51, 0x80000000, v51
	s_cmpk_gt_i32 s11, 200
	s_cselect_b64 vcc, -1, 0
	v_xor_b32_e32 v50, v51, v50
	v_cndmask_b32_e32 v50, v123, v50, vcc
	global_store_dword v243, v50, s[8:9] offset:2048
	s_add_u32 s8, s8, 0x1000
	s_addc_u32 s9, s9, 0
	v_mfma_f32_32x32x16_bf16 v[6:21], v[86:89], v[38:41], 0
	s_add_i32 m0, s10, 32768
	s_nop 0
	global_load_lds_dwordx4 v102, s[6:7]
	s_add_i32 m0, s10, 33792
	s_nop 0
	global_load_lds_dwordx4 v110, s[6:7]
	s_add_i32 m0, s10, 34816
	s_nop 0
	global_load_lds_dwordx4 v112, s[6:7]
	s_add_i32 m0, s10, 35840
	s_nop 0
	global_load_lds_dwordx4 v193, s[6:7]
	s_add_u32 s6, s6, 0x8000
	s_addc_u32 s7, s7, 0
	v_max_f32_e32 v108, 0, v212
	v_max_f32_e32 v109, 0, v213
	v_pk_mul_f32 v[0:1], v[22:23], v[108:109]
	v_max_f32_e32 v210, 0, v214
	v_max_f32_e32 v211, 0, v215
	v_pk_fma_f32 v[0:1], v[24:25], v[210:211], v[0:1]
	v_max_f32_e32 v108, 0, v216
	v_max_f32_e32 v109, 0, v217
	v_pk_fma_f32 v[0:1], v[26:27], v[108:109], v[0:1]
	v_mfma_f32_32x32x16_bf16 v[6:21], v[90:93], v[42:45], v[6:21]
	v_max_f32_e32 v210, 0, v218
	v_max_f32_e32 v211, 0, v219
	v_pk_fma_f32 v[0:1], v[28:29], v[210:211], v[0:1]
	v_max_f32_e32 v108, 0, v220
	v_max_f32_e32 v109, 0, v221
	v_pk_fma_f32 v[0:1], v[30:31], v[108:109], v[0:1]
	v_max_f32_e32 v210, 0, v222
	v_max_f32_e32 v211, 0, v223
	v_pk_fma_f32 v[0:1], v[32:33], v[210:211], v[0:1]
	v_mfma_f32_32x32x16_bf16 v[6:21], v[94:97], v[46:49], v[6:21]
	v_max_f32_e32 v108, 0, v224
	v_max_f32_e32 v109, 0, v225
	v_pk_fma_f32 v[0:1], v[34:35], v[108:109], v[0:1]
	v_max_f32_e32 v210, 0, v226
	v_max_f32_e32 v211, 0, v227
	v_pk_fma_f32 v[0:1], v[36:37], v[210:211], v[0:1]
	v_add_f32_e32 v0, v0, v1
	v_ashrrev_i32_e32 v1, 31, v0
	v_mfma_f32_32x32x16_bf16 v[6:21], v[98:101], v[196:199], v[6:21]
	s_waitcnt vmcnt(10)
	v_add_u32_e32 v228, 0x10000, v5
	ds_read_b128 v[38:41], v228 offset:43264
	v_add_u32_e32 v228, 0x10000, v52
	ds_read_b128 v[42:45], v228 offset:43264
	v_add_u32_e32 v228, 0x10000, v55
	ds_read_b128 v[46:49], v228 offset:43264
	v_add_u32_e32 v228, 0x10000, v56
	ds_read_b128 v[196:199], v228 offset:43264
	v_or_b32_e32 v1, 0x80000000, v1
	s_cmpk_gt_i32 s11, 208
	s_cselect_b64 vcc, -1, 0
	v_xor_b32_e32 v0, v1, v0
	v_cndmask_b32_e32 v160, v123, v0, vcc
	s_nop 3
	s_waitcnt lgkmcnt(3)
	v_mfma_f32_32x32x16_bf16 v[212:227], v[70:73], v[38:41], 0
	v_max_f32_e32 v108, 0, v6
	v_max_f32_e32 v109, 0, v7
	v_pk_mul_f32 v[50:51], v[244:245], v[108:109]
	v_max_f32_e32 v210, 0, v8
	v_max_f32_e32 v211, 0, v9
	v_pk_fma_f32 v[50:51], v[246:247], v[210:211], v[50:51]
	v_max_f32_e32 v108, 0, v10
	v_max_f32_e32 v109, 0, v11
	v_pk_fma_f32 v[50:51], v[248:249], v[108:109], v[50:51]
	s_waitcnt lgkmcnt(2)
	v_mfma_f32_32x32x16_bf16 v[212:227], v[74:77], v[42:45], v[212:227]
	v_max_f32_e32 v210, 0, v12
	v_max_f32_e32 v211, 0, v13
	v_pk_fma_f32 v[50:51], v[250:251], v[210:211], v[50:51]
	v_max_f32_e32 v108, 0, v14
	v_max_f32_e32 v109, 0, v15
	v_pk_fma_f32 v[50:51], v[252:253], v[108:109], v[50:51]
	v_max_f32_e32 v210, 0, v16
	v_max_f32_e32 v211, 0, v17
	v_pk_fma_f32 v[50:51], v[254:255], v[210:211], v[50:51]
	s_waitcnt lgkmcnt(1)
	v_mfma_f32_32x32x16_bf16 v[212:227], v[78:81], v[46:49], v[212:227]
	v_max_f32_e32 v108, 0, v18
	v_max_f32_e32 v109, 0, v19
	v_pk_fma_f32 v[50:51], v[200:201], v[108:109], v[50:51]
	v_max_f32_e32 v210, 0, v20
	v_max_f32_e32 v211, 0, v21
	v_pk_fma_f32 v[50:51], v[202:203], v[210:211], v[50:51]
	v_add_f32_e32 v50, v50, v51
	v_ashrrev_i32_e32 v51, 31, v50
	s_waitcnt lgkmcnt(0)
	v_mfma_f32_32x32x16_bf16 v[212:227], v[82:85], v[196:199], v[212:227]
	v_or_b32_e32 v51, 0x80000000, v51
	s_cmpk_gt_i32 s11, 208
	s_cselect_b64 vcc, -1, 0
	v_xor_b32_e32 v50, v51, v50
	v_cndmask_b32_e32 v50, v123, v50, vcc
	global_store_dword v243, v50, s[8:9]
	v_mfma_f32_32x32x16_bf16 v[6:21], v[86:89], v[38:41], 0
	s_add_i32 m0, s10, 65536
	s_nop 0
	global_load_lds_dwordx4 v102, s[6:7]
	s_add_i32 m0, s10, 66560
	s_nop 0
	global_load_lds_dwordx4 v110, s[6:7]
	s_add_i32 m0, s10, 67584
	s_nop 0
	global_load_lds_dwordx4 v112, s[6:7]
	s_add_i32 m0, s10, 68608
	s_nop 0
	global_load_lds_dwordx4 v193, s[6:7]
	s_add_u32 s6, s6, 0x8000
	s_addc_u32 s7, s7, 0
	v_max_f32_e32 v108, 0, v212
	v_max_f32_e32 v109, 0, v213
	v_pk_mul_f32 v[0:1], v[22:23], v[108:109]
	v_max_f32_e32 v210, 0, v214
	v_max_f32_e32 v211, 0, v215
	v_pk_fma_f32 v[0:1], v[24:25], v[210:211], v[0:1]
	v_max_f32_e32 v108, 0, v216
	v_max_f32_e32 v109, 0, v217
	v_pk_fma_f32 v[0:1], v[26:27], v[108:109], v[0:1]
	v_mfma_f32_32x32x16_bf16 v[6:21], v[90:93], v[42:45], v[6:21]
	v_max_f32_e32 v210, 0, v218
	v_max_f32_e32 v211, 0, v219
	v_pk_fma_f32 v[0:1], v[28:29], v[210:211], v[0:1]
	v_max_f32_e32 v108, 0, v220
	v_max_f32_e32 v109, 0, v221
	v_pk_fma_f32 v[0:1], v[30:31], v[108:109], v[0:1]
	v_max_f32_e32 v210, 0, v222
	v_max_f32_e32 v211, 0, v223
	v_pk_fma_f32 v[0:1], v[32:33], v[210:211], v[0:1]
	v_mfma_f32_32x32x16_bf16 v[6:21], v[94:97], v[46:49], v[6:21]
	v_max_f32_e32 v108, 0, v224
	v_max_f32_e32 v109, 0, v225
	v_pk_fma_f32 v[0:1], v[34:35], v[108:109], v[0:1]
	v_max_f32_e32 v210, 0, v226
	v_max_f32_e32 v211, 0, v227
	v_pk_fma_f32 v[0:1], v[36:37], v[210:211], v[0:1]
	v_add_f32_e32 v0, v0, v1
	v_ashrrev_i32_e32 v1, 31, v0
	v_mfma_f32_32x32x16_bf16 v[6:21], v[98:101], v[196:199], v[6:21]
	s_waitcnt vmcnt(10)
	ds_read_b128 v[38:41], v5 offset:10496
	ds_read_b128 v[42:45], v52 offset:10496
	ds_read_b128 v[46:49], v55 offset:10496
	ds_read_b128 v[196:199], v56 offset:10496
	v_or_b32_e32 v1, 0x80000000, v1
	s_cmpk_gt_i32 s11, 216
	s_cselect_b64 vcc, -1, 0
	v_xor_b32_e32 v0, v1, v0
	v_cndmask_b32_e32 v159, v123, v0, vcc
	s_nop 3
	s_waitcnt lgkmcnt(3)
	v_mfma_f32_32x32x16_bf16 v[212:227], v[70:73], v[38:41], 0
	v_max_f32_e32 v108, 0, v6
	v_max_f32_e32 v109, 0, v7
	v_pk_mul_f32 v[50:51], v[244:245], v[108:109]
	v_max_f32_e32 v210, 0, v8
	v_max_f32_e32 v211, 0, v9
	v_pk_fma_f32 v[50:51], v[246:247], v[210:211], v[50:51]
	v_max_f32_e32 v108, 0, v10
	v_max_f32_e32 v109, 0, v11
	v_pk_fma_f32 v[50:51], v[248:249], v[108:109], v[50:51]
	s_waitcnt lgkmcnt(2)
	v_mfma_f32_32x32x16_bf16 v[212:227], v[74:77], v[42:45], v[212:227]
	v_max_f32_e32 v210, 0, v12
	v_max_f32_e32 v211, 0, v13
	v_pk_fma_f32 v[50:51], v[250:251], v[210:211], v[50:51]
	v_max_f32_e32 v108, 0, v14
	v_max_f32_e32 v109, 0, v15
	v_pk_fma_f32 v[50:51], v[252:253], v[108:109], v[50:51]
	v_max_f32_e32 v210, 0, v16
	v_max_f32_e32 v211, 0, v17
	v_pk_fma_f32 v[50:51], v[254:255], v[210:211], v[50:51]
	s_waitcnt lgkmcnt(1)
	v_mfma_f32_32x32x16_bf16 v[212:227], v[78:81], v[46:49], v[212:227]
	v_max_f32_e32 v108, 0, v18
	v_max_f32_e32 v109, 0, v19
	v_pk_fma_f32 v[50:51], v[200:201], v[108:109], v[50:51]
	v_max_f32_e32 v210, 0, v20
	v_max_f32_e32 v211, 0, v21
	v_pk_fma_f32 v[50:51], v[202:203], v[210:211], v[50:51]
	v_add_f32_e32 v50, v50, v51
	v_ashrrev_i32_e32 v51, 31, v50
	s_waitcnt lgkmcnt(0)
	v_mfma_f32_32x32x16_bf16 v[212:227], v[82:85], v[196:199], v[212:227]
	v_or_b32_e32 v51, 0x80000000, v51
	s_cmpk_gt_i32 s11, 216
	s_cselect_b64 vcc, -1, 0
	v_xor_b32_e32 v50, v51, v50
	v_cndmask_b32_e32 v50, v123, v50, vcc
	global_store_dword v243, v50, s[8:9] offset:2048
	s_add_u32 s8, s8, 0x1000
	s_addc_u32 s9, s9, 0
	v_mfma_f32_32x32x16_bf16 v[6:21], v[86:89], v[38:41], 0
	s_add_i32 m0, s10, 98304
	s_nop 0
	global_load_lds_dwordx4 v102, s[6:7]
	s_add_i32 m0, s10, 99328
	s_nop 0
	global_load_lds_dwordx4 v110, s[6:7]
	s_add_i32 m0, s10, 100352
	s_nop 0
	global_load_lds_dwordx4 v112, s[6:7]
	s_add_i32 m0, s10, 101376
	s_nop 0
	global_load_lds_dwordx4 v193, s[6:7]
	s_add_u32 s6, s6, 0x8000
	s_addc_u32 s7, s7, 0
	v_max_f32_e32 v108, 0, v212
	v_max_f32_e32 v109, 0, v213
	v_pk_mul_f32 v[0:1], v[22:23], v[108:109]
	v_max_f32_e32 v210, 0, v214
	v_max_f32_e32 v211, 0, v215
	v_pk_fma_f32 v[0:1], v[24:25], v[210:211], v[0:1]
	v_max_f32_e32 v108, 0, v216
	v_max_f32_e32 v109, 0, v217
	v_pk_fma_f32 v[0:1], v[26:27], v[108:109], v[0:1]
	v_mfma_f32_32x32x16_bf16 v[6:21], v[90:93], v[42:45], v[6:21]
	v_max_f32_e32 v210, 0, v218
	v_max_f32_e32 v211, 0, v219
	v_pk_fma_f32 v[0:1], v[28:29], v[210:211], v[0:1]
	v_max_f32_e32 v108, 0, v220
	v_max_f32_e32 v109, 0, v221
	v_pk_fma_f32 v[0:1], v[30:31], v[108:109], v[0:1]
	v_max_f32_e32 v210, 0, v222
	v_max_f32_e32 v211, 0, v223
	v_pk_fma_f32 v[0:1], v[32:33], v[210:211], v[0:1]
	v_mfma_f32_32x32x16_bf16 v[6:21], v[94:97], v[46:49], v[6:21]
	v_max_f32_e32 v108, 0, v224
	v_max_f32_e32 v109, 0, v225
	v_pk_fma_f32 v[0:1], v[34:35], v[108:109], v[0:1]
	v_max_f32_e32 v210, 0, v226
	v_max_f32_e32 v211, 0, v227
	v_pk_fma_f32 v[0:1], v[36:37], v[210:211], v[0:1]
	v_add_f32_e32 v0, v0, v1
	v_ashrrev_i32_e32 v1, 31, v0
	v_mfma_f32_32x32x16_bf16 v[6:21], v[98:101], v[196:199], v[6:21]
	s_waitcnt vmcnt(10)
	ds_read_b128 v[38:41], v5 offset:43264
	ds_read_b128 v[42:45], v52 offset:43264
	ds_read_b128 v[46:49], v55 offset:43264
	ds_read_b128 v[196:199], v56 offset:43264
	v_or_b32_e32 v1, 0x80000000, v1
	s_cmpk_gt_i32 s11, 224
	s_cselect_b64 vcc, -1, 0
	v_xor_b32_e32 v0, v1, v0
	v_cndmask_b32_e32 v162, v123, v0, vcc
	s_nop 3
	s_waitcnt lgkmcnt(3)
	v_mfma_f32_32x32x16_bf16 v[212:227], v[70:73], v[38:41], 0
	v_max_f32_e32 v108, 0, v6
	v_max_f32_e32 v109, 0, v7
	v_pk_mul_f32 v[50:51], v[244:245], v[108:109]
	v_max_f32_e32 v210, 0, v8
	v_max_f32_e32 v211, 0, v9
	v_pk_fma_f32 v[50:51], v[246:247], v[210:211], v[50:51]
	v_max_f32_e32 v108, 0, v10
	v_max_f32_e32 v109, 0, v11
	v_pk_fma_f32 v[50:51], v[248:249], v[108:109], v[50:51]
	s_waitcnt lgkmcnt(2)
	v_mfma_f32_32x32x16_bf16 v[212:227], v[74:77], v[42:45], v[212:227]
	v_max_f32_e32 v210, 0, v12
	v_max_f32_e32 v211, 0, v13
	v_pk_fma_f32 v[50:51], v[250:251], v[210:211], v[50:51]
	v_max_f32_e32 v108, 0, v14
	v_max_f32_e32 v109, 0, v15
	v_pk_fma_f32 v[50:51], v[252:253], v[108:109], v[50:51]
	v_max_f32_e32 v210, 0, v16
	v_max_f32_e32 v211, 0, v17
	v_pk_fma_f32 v[50:51], v[254:255], v[210:211], v[50:51]
	s_waitcnt lgkmcnt(1)
	v_mfma_f32_32x32x16_bf16 v[212:227], v[78:81], v[46:49], v[212:227]
	v_max_f32_e32 v108, 0, v18
	v_max_f32_e32 v109, 0, v19
	v_pk_fma_f32 v[50:51], v[200:201], v[108:109], v[50:51]
	v_max_f32_e32 v210, 0, v20
	v_max_f32_e32 v211, 0, v21
	v_pk_fma_f32 v[50:51], v[202:203], v[210:211], v[50:51]
	v_add_f32_e32 v50, v50, v51
	v_ashrrev_i32_e32 v51, 31, v50
	s_waitcnt lgkmcnt(0)
	v_mfma_f32_32x32x16_bf16 v[212:227], v[82:85], v[196:199], v[212:227]
	v_or_b32_e32 v51, 0x80000000, v51
	s_cmpk_gt_i32 s11, 224
	s_cselect_b64 vcc, -1, 0
	v_xor_b32_e32 v50, v51, v50
	v_cndmask_b32_e32 v50, v123, v50, vcc
	global_store_dword v243, v50, s[8:9]
	v_mfma_f32_32x32x16_bf16 v[6:21], v[86:89], v[38:41], 0
	s_add_i32 m0, s10, 0
	s_nop 0
	global_load_lds_dwordx4 v102, s[6:7]
	s_add_i32 m0, s10, 1024
	s_nop 0
	global_load_lds_dwordx4 v110, s[6:7]
	s_add_i32 m0, s10, 2048
	s_nop 0
	global_load_lds_dwordx4 v112, s[6:7]
	s_add_i32 m0, s10, 3072
	s_nop 0
	global_load_lds_dwordx4 v193, s[6:7]
	s_add_u32 s6, s6, 0x8000
	s_addc_u32 s7, s7, 0
	v_max_f32_e32 v108, 0, v212
	v_max_f32_e32 v109, 0, v213
	v_pk_mul_f32 v[0:1], v[22:23], v[108:109]
	v_max_f32_e32 v210, 0, v214
	v_max_f32_e32 v211, 0, v215
	v_pk_fma_f32 v[0:1], v[24:25], v[210:211], v[0:1]
	v_max_f32_e32 v108, 0, v216
	v_max_f32_e32 v109, 0, v217
	v_pk_fma_f32 v[0:1], v[26:27], v[108:109], v[0:1]
	v_mfma_f32_32x32x16_bf16 v[6:21], v[90:93], v[42:45], v[6:21]
	v_max_f32_e32 v210, 0, v218
	v_max_f32_e32 v211, 0, v219
	v_pk_fma_f32 v[0:1], v[28:29], v[210:211], v[0:1]
	v_max_f32_e32 v108, 0, v220
	v_max_f32_e32 v109, 0, v221
	v_pk_fma_f32 v[0:1], v[30:31], v[108:109], v[0:1]
	v_max_f32_e32 v210, 0, v222
	v_max_f32_e32 v211, 0, v223
	v_pk_fma_f32 v[0:1], v[32:33], v[210:211], v[0:1]
	v_mfma_f32_32x32x16_bf16 v[6:21], v[94:97], v[46:49], v[6:21]
	v_max_f32_e32 v108, 0, v224
	v_max_f32_e32 v109, 0, v225
	v_pk_fma_f32 v[0:1], v[34:35], v[108:109], v[0:1]
	v_max_f32_e32 v210, 0, v226
	v_max_f32_e32 v211, 0, v227
	v_pk_fma_f32 v[0:1], v[36:37], v[210:211], v[0:1]
	v_add_f32_e32 v0, v0, v1
	v_ashrrev_i32_e32 v1, 31, v0
	v_mfma_f32_32x32x16_bf16 v[6:21], v[98:101], v[196:199], v[6:21]
	s_waitcnt vmcnt(10)
	v_add_u32_e32 v228, 0x10000, v5
	ds_read_b128 v[38:41], v228 offset:10496
	v_add_u32_e32 v228, 0x10000, v52
	ds_read_b128 v[42:45], v228 offset:10496
	v_add_u32_e32 v228, 0x10000, v55
	ds_read_b128 v[46:49], v228 offset:10496
	v_add_u32_e32 v228, 0x10000, v56
	ds_read_b128 v[196:199], v228 offset:10496
	v_or_b32_e32 v1, 0x80000000, v1
	s_cmpk_gt_i32 s11, 232
	s_cselect_b64 vcc, -1, 0
	v_xor_b32_e32 v0, v1, v0
	v_cndmask_b32_e32 v161, v123, v0, vcc
	s_nop 3
	s_waitcnt lgkmcnt(3)
	v_mfma_f32_32x32x16_bf16 v[212:227], v[70:73], v[38:41], 0
	v_max_f32_e32 v108, 0, v6
	v_max_f32_e32 v109, 0, v7
	v_pk_mul_f32 v[50:51], v[244:245], v[108:109]
	v_max_f32_e32 v210, 0, v8
	v_max_f32_e32 v211, 0, v9
	v_pk_fma_f32 v[50:51], v[246:247], v[210:211], v[50:51]
	v_max_f32_e32 v108, 0, v10
	v_max_f32_e32 v109, 0, v11
	v_pk_fma_f32 v[50:51], v[248:249], v[108:109], v[50:51]
	s_waitcnt lgkmcnt(2)
	v_mfma_f32_32x32x16_bf16 v[212:227], v[74:77], v[42:45], v[212:227]
	v_max_f32_e32 v210, 0, v12
	v_max_f32_e32 v211, 0, v13
	v_pk_fma_f32 v[50:51], v[250:251], v[210:211], v[50:51]
	v_max_f32_e32 v108, 0, v14
	v_max_f32_e32 v109, 0, v15
	v_pk_fma_f32 v[50:51], v[252:253], v[108:109], v[50:51]
	v_max_f32_e32 v210, 0, v16
	v_max_f32_e32 v211, 0, v17
	v_pk_fma_f32 v[50:51], v[254:255], v[210:211], v[50:51]
	s_waitcnt lgkmcnt(1)
	v_mfma_f32_32x32x16_bf16 v[212:227], v[78:81], v[46:49], v[212:227]
	v_max_f32_e32 v108, 0, v18
	v_max_f32_e32 v109, 0, v19
	v_pk_fma_f32 v[50:51], v[200:201], v[108:109], v[50:51]
	v_max_f32_e32 v210, 0, v20
	v_max_f32_e32 v211, 0, v21
	v_pk_fma_f32 v[50:51], v[202:203], v[210:211], v[50:51]
	v_add_f32_e32 v50, v50, v51
	v_ashrrev_i32_e32 v51, 31, v50
	s_waitcnt lgkmcnt(0)
	v_mfma_f32_32x32x16_bf16 v[212:227], v[82:85], v[196:199], v[212:227]
	v_or_b32_e32 v51, 0x80000000, v51
	s_cmpk_gt_i32 s11, 232
	s_cselect_b64 vcc, -1, 0
	v_xor_b32_e32 v50, v51, v50
	v_cndmask_b32_e32 v50, v123, v50, vcc
	global_store_dword v243, v50, s[8:9] offset:2048
	s_add_u32 s8, s8, 0x1000
	s_addc_u32 s9, s9, 0
	v_mfma_f32_32x32x16_bf16 v[6:21], v[86:89], v[38:41], 0
	s_add_i32 m0, s10, 32768
	s_nop 0
	global_load_lds_dwordx4 v102, s[6:7]
	s_add_i32 m0, s10, 33792
	s_nop 0
	global_load_lds_dwordx4 v110, s[6:7]
	s_add_i32 m0, s10, 34816
	s_nop 0
	global_load_lds_dwordx4 v112, s[6:7]
	s_add_i32 m0, s10, 35840
	s_nop 0
	global_load_lds_dwordx4 v193, s[6:7]
	s_add_u32 s6, s6, 0x8000
	s_addc_u32 s7, s7, 0
	v_max_f32_e32 v108, 0, v212
	v_max_f32_e32 v109, 0, v213
	v_pk_mul_f32 v[0:1], v[22:23], v[108:109]
	v_max_f32_e32 v210, 0, v214
	v_max_f32_e32 v211, 0, v215
	v_pk_fma_f32 v[0:1], v[24:25], v[210:211], v[0:1]
	v_max_f32_e32 v108, 0, v216
	v_max_f32_e32 v109, 0, v217
	v_pk_fma_f32 v[0:1], v[26:27], v[108:109], v[0:1]
	v_mfma_f32_32x32x16_bf16 v[6:21], v[90:93], v[42:45], v[6:21]
	v_max_f32_e32 v210, 0, v218
	v_max_f32_e32 v211, 0, v219
	v_pk_fma_f32 v[0:1], v[28:29], v[210:211], v[0:1]
	v_max_f32_e32 v108, 0, v220
	v_max_f32_e32 v109, 0, v221
	v_pk_fma_f32 v[0:1], v[30:31], v[108:109], v[0:1]
	v_max_f32_e32 v210, 0, v222
	v_max_f32_e32 v211, 0, v223
	v_pk_fma_f32 v[0:1], v[32:33], v[210:211], v[0:1]
	v_mfma_f32_32x32x16_bf16 v[6:21], v[94:97], v[46:49], v[6:21]
	v_max_f32_e32 v108, 0, v224
	v_max_f32_e32 v109, 0, v225
	v_pk_fma_f32 v[0:1], v[34:35], v[108:109], v[0:1]
	v_max_f32_e32 v210, 0, v226
	v_max_f32_e32 v211, 0, v227
	v_pk_fma_f32 v[0:1], v[36:37], v[210:211], v[0:1]
	v_add_f32_e32 v0, v0, v1
	v_ashrrev_i32_e32 v1, 31, v0
	v_mfma_f32_32x32x16_bf16 v[6:21], v[98:101], v[196:199], v[6:21]
	s_waitcnt vmcnt(10)
	v_add_u32_e32 v228, 0x10000, v5
	ds_read_b128 v[38:41], v228 offset:43264
	v_add_u32_e32 v228, 0x10000, v52
	ds_read_b128 v[42:45], v228 offset:43264
	v_add_u32_e32 v228, 0x10000, v55
	ds_read_b128 v[46:49], v228 offset:43264
	v_add_u32_e32 v228, 0x10000, v56
	ds_read_b128 v[196:199], v228 offset:43264
	v_or_b32_e32 v1, 0x80000000, v1
	s_cmpk_gt_i32 s11, 240
	s_cselect_b64 vcc, -1, 0
	v_xor_b32_e32 v0, v1, v0
	v_cndmask_b32_e32 v163, v123, v0, vcc
	s_nop 3
	s_waitcnt lgkmcnt(3)
	v_mfma_f32_32x32x16_bf16 v[212:227], v[70:73], v[38:41], 0
	v_max_f32_e32 v108, 0, v6
	v_max_f32_e32 v109, 0, v7
	v_pk_mul_f32 v[50:51], v[244:245], v[108:109]
	v_max_f32_e32 v210, 0, v8
	v_max_f32_e32 v211, 0, v9
	v_pk_fma_f32 v[50:51], v[246:247], v[210:211], v[50:51]
	v_max_f32_e32 v108, 0, v10
	v_max_f32_e32 v109, 0, v11
	v_pk_fma_f32 v[50:51], v[248:249], v[108:109], v[50:51]
	s_waitcnt lgkmcnt(2)
	v_mfma_f32_32x32x16_bf16 v[212:227], v[74:77], v[42:45], v[212:227]
	v_max_f32_e32 v210, 0, v12
	v_max_f32_e32 v211, 0, v13
	v_pk_fma_f32 v[50:51], v[250:251], v[210:211], v[50:51]
	v_max_f32_e32 v108, 0, v14
	v_max_f32_e32 v109, 0, v15
	v_pk_fma_f32 v[50:51], v[252:253], v[108:109], v[50:51]
	v_max_f32_e32 v210, 0, v16
	v_max_f32_e32 v211, 0, v17
	v_pk_fma_f32 v[50:51], v[254:255], v[210:211], v[50:51]
	s_waitcnt lgkmcnt(1)
	v_mfma_f32_32x32x16_bf16 v[212:227], v[78:81], v[46:49], v[212:227]
	v_max_f32_e32 v108, 0, v18
	v_max_f32_e32 v109, 0, v19
	v_pk_fma_f32 v[50:51], v[200:201], v[108:109], v[50:51]
	v_max_f32_e32 v210, 0, v20
	v_max_f32_e32 v211, 0, v21
	v_pk_fma_f32 v[50:51], v[202:203], v[210:211], v[50:51]
	v_add_f32_e32 v50, v50, v51
	v_ashrrev_i32_e32 v51, 31, v50
	s_waitcnt lgkmcnt(0)
	v_mfma_f32_32x32x16_bf16 v[212:227], v[82:85], v[196:199], v[212:227]
	v_or_b32_e32 v51, 0x80000000, v51
	s_cmpk_gt_i32 s11, 240
	s_cselect_b64 vcc, -1, 0
	v_xor_b32_e32 v50, v51, v50
	v_cndmask_b32_e32 v50, v123, v50, vcc
	global_store_dword v243, v50, s[8:9]
	v_mfma_f32_32x32x16_bf16 v[6:21], v[86:89], v[38:41], 0
	s_add_i32 m0, s10, 65536
	s_nop 0
	global_load_lds_dwordx4 v102, s[6:7]
	s_add_i32 m0, s10, 66560
	s_nop 0
	global_load_lds_dwordx4 v110, s[6:7]
	s_add_i32 m0, s10, 67584
	s_nop 0
	global_load_lds_dwordx4 v112, s[6:7]
	s_add_i32 m0, s10, 68608
	s_nop 0
	global_load_lds_dwordx4 v193, s[6:7]
	s_add_u32 s6, s6, 0x8000
	s_addc_u32 s7, s7, 0
	v_max_f32_e32 v108, 0, v212
	v_max_f32_e32 v109, 0, v213
	v_pk_mul_f32 v[0:1], v[22:23], v[108:109]
	v_max_f32_e32 v210, 0, v214
	v_max_f32_e32 v211, 0, v215
	v_pk_fma_f32 v[0:1], v[24:25], v[210:211], v[0:1]
	v_max_f32_e32 v108, 0, v216
	v_max_f32_e32 v109, 0, v217
	v_pk_fma_f32 v[0:1], v[26:27], v[108:109], v[0:1]
	v_mfma_f32_32x32x16_bf16 v[6:21], v[90:93], v[42:45], v[6:21]
	v_max_f32_e32 v210, 0, v218
	v_max_f32_e32 v211, 0, v219
	v_pk_fma_f32 v[0:1], v[28:29], v[210:211], v[0:1]
	v_max_f32_e32 v108, 0, v220
	v_max_f32_e32 v109, 0, v221
	v_pk_fma_f32 v[0:1], v[30:31], v[108:109], v[0:1]
	v_max_f32_e32 v210, 0, v222
	v_max_f32_e32 v211, 0, v223
	v_pk_fma_f32 v[0:1], v[32:33], v[210:211], v[0:1]
	v_mfma_f32_32x32x16_bf16 v[6:21], v[94:97], v[46:49], v[6:21]
	v_max_f32_e32 v108, 0, v224
	v_max_f32_e32 v109, 0, v225
	v_pk_fma_f32 v[0:1], v[34:35], v[108:109], v[0:1]
	v_max_f32_e32 v210, 0, v226
	v_max_f32_e32 v211, 0, v227
	v_pk_fma_f32 v[0:1], v[36:37], v[210:211], v[0:1]
	v_add_f32_e32 v0, v0, v1
	v_ashrrev_i32_e32 v1, 31, v0
	v_mfma_f32_32x32x16_bf16 v[6:21], v[98:101], v[196:199], v[6:21]
	s_waitcnt vmcnt(10)
	ds_read_b128 v[38:41], v5 offset:10496
	ds_read_b128 v[42:45], v52 offset:10496
	ds_read_b128 v[46:49], v55 offset:10496
	ds_read_b128 v[196:199], v56 offset:10496
	v_or_b32_e32 v1, 0x80000000, v1
	s_cmpk_gt_i32 s11, 248
	s_cselect_b64 vcc, -1, 0
	v_xor_b32_e32 v0, v1, v0
	v_cndmask_b32_e32 v152, v123, v0, vcc
	s_nop 3
	v_max_f32_e32 v108, 0, v6
	v_max_f32_e32 v109, 0, v7
	v_pk_mul_f32 v[50:51], v[244:245], v[108:109]
	v_max_f32_e32 v210, 0, v8
	v_max_f32_e32 v211, 0, v9
	v_pk_fma_f32 v[50:51], v[246:247], v[210:211], v[50:51]
	v_max_f32_e32 v108, 0, v10
	v_max_f32_e32 v109, 0, v11
	v_pk_fma_f32 v[50:51], v[248:249], v[108:109], v[50:51]
	v_max_f32_e32 v210, 0, v12
	v_max_f32_e32 v211, 0, v13
	v_pk_fma_f32 v[50:51], v[250:251], v[210:211], v[50:51]
	v_max_f32_e32 v108, 0, v14
	v_max_f32_e32 v109, 0, v15
	v_pk_fma_f32 v[50:51], v[252:253], v[108:109], v[50:51]
	v_max_f32_e32 v210, 0, v16
	v_max_f32_e32 v211, 0, v17
	v_pk_fma_f32 v[50:51], v[254:255], v[210:211], v[50:51]
	v_max_f32_e32 v108, 0, v18
	v_max_f32_e32 v109, 0, v19
	v_pk_fma_f32 v[50:51], v[200:201], v[108:109], v[50:51]
	v_max_f32_e32 v210, 0, v20
	v_max_f32_e32 v211, 0, v21
	v_pk_fma_f32 v[50:51], v[202:203], v[210:211], v[50:51]
	v_add_f32_e32 v50, v50, v51
	v_ashrrev_i32_e32 v51, 31, v50
	v_or_b32_e32 v51, 0x80000000, v51
	s_cmpk_gt_i32 s11, 248
	s_cselect_b64 vcc, -1, 0
	v_xor_b32_e32 v50, v51, v50
	v_cndmask_b32_e32 v50, v123, v50, vcc
	global_store_dword v243, v50, s[8:9] offset:2048
	s_add_u32 s8, s8, 0x1000
	s_addc_u32 s9, s9, 0
	s_cmpk_gt_i32 s81, 32
	s_cbranch_scc0 .Lix_fill_4
	s_waitcnt lgkmcnt(3)
	v_mfma_f32_32x32x16_bf16 v[212:227], v[70:73], v[38:41], 0
	s_add_i32 m0, s10, 98304
	s_nop 0
	global_load_lds_dwordx4 v102, s[6:7]
	s_waitcnt lgkmcnt(2)
	v_mfma_f32_32x32x16_bf16 v[212:227], v[74:77], v[42:45], v[212:227]
	s_add_i32 m0, s10, 99328
	s_nop 0
	global_load_lds_dwordx4 v110, s[6:7]
	s_waitcnt lgkmcnt(1)
	v_mfma_f32_32x32x16_bf16 v[212:227], v[78:81], v[46:49], v[212:227]
	s_add_i32 m0, s10, 100352
	s_nop 0
	global_load_lds_dwordx4 v112, s[6:7]
	s_waitcnt lgkmcnt(0)
	v_mfma_f32_32x32x16_bf16 v[212:227], v[82:85], v[196:199], v[212:227]
	s_add_i32 m0, s10, 101376
	s_nop 0
	global_load_lds_dwordx4 v193, s[6:7]
	s_add_u32 s6, s6, 0x8000
	s_addc_u32 s7, s7, 0
	v_mfma_f32_32x32x16_bf16 v[6:21], v[86:89], v[38:41], 0
	s_nop 7
	s_nop 2
	v_max_f32_e32 v108, 0, v212
	v_max_f32_e32 v109, 0, v213
	v_pk_mul_f32 v[0:1], v[22:23], v[108:109]
	v_max_f32_e32 v210, 0, v214
	v_max_f32_e32 v211, 0, v215
	v_pk_fma_f32 v[0:1], v[24:25], v[210:211], v[0:1]
	v_max_f32_e32 v108, 0, v216
	v_max_f32_e32 v109, 0, v217
	v_pk_fma_f32 v[0:1], v[26:27], v[108:109], v[0:1]
	v_mfma_f32_32x32x16_bf16 v[6:21], v[90:93], v[42:45], v[6:21]
	v_max_f32_e32 v210, 0, v218
	v_max_f32_e32 v211, 0, v219
	v_pk_fma_f32 v[0:1], v[28:29], v[210:211], v[0:1]
	v_max_f32_e32 v108, 0, v220
	v_max_f32_e32 v109, 0, v221
	v_pk_fma_f32 v[0:1], v[30:31], v[108:109], v[0:1]
	v_max_f32_e32 v210, 0, v222
	v_max_f32_e32 v211, 0, v223
	v_pk_fma_f32 v[0:1], v[32:33], v[210:211], v[0:1]
	v_mfma_f32_32x32x16_bf16 v[6:21], v[94:97], v[46:49], v[6:21]
	v_max_f32_e32 v108, 0, v224
	v_max_f32_e32 v109, 0, v225
	v_pk_fma_f32 v[0:1], v[34:35], v[108:109], v[0:1]
	v_max_f32_e32 v210, 0, v226
	v_max_f32_e32 v211, 0, v227
	v_pk_fma_f32 v[0:1], v[36:37], v[210:211], v[0:1]
	v_add_f32_e32 v0, v0, v1
	v_ashrrev_i32_e32 v1, 31, v0
	v_mfma_f32_32x32x16_bf16 v[6:21], v[98:101], v[196:199], v[6:21]
	s_waitcnt vmcnt(10)
	ds_read_b128 v[38:41], v5 offset:43264
	ds_read_b128 v[42:45], v52 offset:43264
	ds_read_b128 v[46:49], v55 offset:43264
	ds_read_b128 v[196:199], v56 offset:43264
	v_or_b32_e32 v1, 0x80000000, v1
	s_cmpk_gt_i32 s11, 256
	s_cselect_b64 vcc, -1, 0
	v_xor_b32_e32 v0, v1, v0
	v_cndmask_b32_e32 v165, v123, v0, vcc
	s_nop 3
	s_waitcnt lgkmcnt(3)
	v_mfma_f32_32x32x16_bf16 v[212:227], v[70:73], v[38:41], 0
	v_max_f32_e32 v108, 0, v6
	v_max_f32_e32 v109, 0, v7
	v_pk_mul_f32 v[50:51], v[244:245], v[108:109]
	v_max_f32_e32 v210, 0, v8
	v_max_f32_e32 v211, 0, v9
	v_pk_fma_f32 v[50:51], v[246:247], v[210:211], v[50:51]
	v_max_f32_e32 v108, 0, v10
	v_max_f32_e32 v109, 0, v11
	v_pk_fma_f32 v[50:51], v[248:249], v[108:109], v[50:51]
	s_waitcnt lgkmcnt(2)
	v_mfma_f32_32x32x16_bf16 v[212:227], v[74:77], v[42:45], v[212:227]
	v_max_f32_e32 v210, 0, v12
	v_max_f32_e32 v211, 0, v13
	v_pk_fma_f32 v[50:51], v[250:251], v[210:211], v[50:51]
	v_max_f32_e32 v108, 0, v14
	v_max_f32_e32 v109, 0, v15
	v_pk_fma_f32 v[50:51], v[252:253], v[108:109], v[50:51]
	v_max_f32_e32 v210, 0, v16
	v_max_f32_e32 v211, 0, v17
	v_pk_fma_f32 v[50:51], v[254:255], v[210:211], v[50:51]
	s_waitcnt lgkmcnt(1)
	v_mfma_f32_32x32x16_bf16 v[212:227], v[78:81], v[46:49], v[212:227]
	v_max_f32_e32 v108, 0, v18
	v_max_f32_e32 v109, 0, v19
	v_pk_fma_f32 v[50:51], v[200:201], v[108:109], v[50:51]
	v_max_f32_e32 v210, 0, v20
	v_max_f32_e32 v211, 0, v21
	v_pk_fma_f32 v[50:51], v[202:203], v[210:211], v[50:51]
	v_add_f32_e32 v50, v50, v51
	v_ashrrev_i32_e32 v51, 31, v50
	s_waitcnt lgkmcnt(0)
	v_mfma_f32_32x32x16_bf16 v[212:227], v[82:85], v[196:199], v[212:227]
	v_or_b32_e32 v51, 0x80000000, v51
	s_cmpk_gt_i32 s11, 256
	s_cselect_b64 vcc, -1, 0
	v_xor_b32_e32 v50, v51, v50
	v_cndmask_b32_e32 v50, v123, v50, vcc
	global_store_dword v243, v50, s[8:9]
	v_mfma_f32_32x32x16_bf16 v[6:21], v[86:89], v[38:41], 0
	s_add_i32 m0, s10, 0
	s_nop 0
	global_load_lds_dwordx4 v102, s[6:7]
	s_add_i32 m0, s10, 1024
	s_nop 0
	global_load_lds_dwordx4 v110, s[6:7]
	s_add_i32 m0, s10, 2048
	s_nop 0
	global_load_lds_dwordx4 v112, s[6:7]
	s_add_i32 m0, s10, 3072
	s_nop 0
	global_load_lds_dwordx4 v193, s[6:7]
	s_add_u32 s6, s6, 0x8000
	s_addc_u32 s7, s7, 0
	v_max_f32_e32 v108, 0, v212
	v_max_f32_e32 v109, 0, v213
	v_pk_mul_f32 v[0:1], v[22:23], v[108:109]
	v_max_f32_e32 v210, 0, v214
	v_max_f32_e32 v211, 0, v215
	v_pk_fma_f32 v[0:1], v[24:25], v[210:211], v[0:1]
	v_max_f32_e32 v108, 0, v216
	v_max_f32_e32 v109, 0, v217
	v_pk_fma_f32 v[0:1], v[26:27], v[108:109], v[0:1]
	v_mfma_f32_32x32x16_bf16 v[6:21], v[90:93], v[42:45], v[6:21]
	v_max_f32_e32 v210, 0, v218
	v_max_f32_e32 v211, 0, v219
	v_pk_fma_f32 v[0:1], v[28:29], v[210:211], v[0:1]
	v_max_f32_e32 v108, 0, v220
	v_max_f32_e32 v109, 0, v221
	v_pk_fma_f32 v[0:1], v[30:31], v[108:109], v[0:1]
	v_max_f32_e32 v210, 0, v222
	v_max_f32_e32 v211, 0, v223
	v_pk_fma_f32 v[0:1], v[32:33], v[210:211], v[0:1]
	v_mfma_f32_32x32x16_bf16 v[6:21], v[94:97], v[46:49], v[6:21]
	v_max_f32_e32 v108, 0, v224
	v_max_f32_e32 v109, 0, v225
	v_pk_fma_f32 v[0:1], v[34:35], v[108:109], v[0:1]
	v_max_f32_e32 v210, 0, v226
	v_max_f32_e32 v211, 0, v227
	v_pk_fma_f32 v[0:1], v[36:37], v[210:211], v[0:1]
	v_add_f32_e32 v0, v0, v1
	v_ashrrev_i32_e32 v1, 31, v0
	v_mfma_f32_32x32x16_bf16 v[6:21], v[98:101], v[196:199], v[6:21]
	s_waitcnt vmcnt(10)
	v_add_u32_e32 v228, 0x10000, v5
	ds_read_b128 v[38:41], v228 offset:10496
	v_add_u32_e32 v228, 0x10000, v52
	ds_read_b128 v[42:45], v228 offset:10496
	v_add_u32_e32 v228, 0x10000, v55
	ds_read_b128 v[46:49], v228 offset:10496
	v_add_u32_e32 v228, 0x10000, v56
	ds_read_b128 v[196:199], v228 offset:10496
	v_or_b32_e32 v1, 0x80000000, v1
	s_cmpk_gt_i32 s11, 264
	s_cselect_b64 vcc, -1, 0
	v_xor_b32_e32 v0, v1, v0
	v_cndmask_b32_e32 v164, v123, v0, vcc
	s_nop 3
	s_waitcnt lgkmcnt(3)
	v_mfma_f32_32x32x16_bf16 v[212:227], v[70:73], v[38:41], 0
	v_max_f32_e32 v108, 0, v6
	v_max_f32_e32 v109, 0, v7
	v_pk_mul_f32 v[50:51], v[244:245], v[108:109]
	v_max_f32_e32 v210, 0, v8
	v_max_f32_e32 v211, 0, v9
	v_pk_fma_f32 v[50:51], v[246:247], v[210:211], v[50:51]
	v_max_f32_e32 v108, 0, v10
	v_max_f32_e32 v109, 0, v11
	v_pk_fma_f32 v[50:51], v[248:249], v[108:109], v[50:51]
	s_waitcnt lgkmcnt(2)
	v_mfma_f32_32x32x16_bf16 v[212:227], v[74:77], v[42:45], v[212:227]
	v_max_f32_e32 v210, 0, v12
	v_max_f32_e32 v211, 0, v13
	v_pk_fma_f32 v[50:51], v[250:251], v[210:211], v[50:51]
	v_max_f32_e32 v108, 0, v14
	v_max_f32_e32 v109, 0, v15
	v_pk_fma_f32 v[50:51], v[252:253], v[108:109], v[50:51]
	v_max_f32_e32 v210, 0, v16
	v_max_f32_e32 v211, 0, v17
	v_pk_fma_f32 v[50:51], v[254:255], v[210:211], v[50:51]
	s_waitcnt lgkmcnt(1)
	v_mfma_f32_32x32x16_bf16 v[212:227], v[78:81], v[46:49], v[212:227]
	v_max_f32_e32 v108, 0, v18
	v_max_f32_e32 v109, 0, v19
	v_pk_fma_f32 v[50:51], v[200:201], v[108:109], v[50:51]
	v_max_f32_e32 v210, 0, v20
	v_max_f32_e32 v211, 0, v21
	v_pk_fma_f32 v[50:51], v[202:203], v[210:211], v[50:51]
	v_add_f32_e32 v50, v50, v51
	v_ashrrev_i32_e32 v51, 31, v50
	s_waitcnt lgkmcnt(0)
	v_mfma_f32_32x32x16_bf16 v[212:227], v[82:85], v[196:199], v[212:227]
	v_or_b32_e32 v51, 0x80000000, v51
	s_cmpk_gt_i32 s11, 264
	s_cselect_b64 vcc, -1, 0
	v_xor_b32_e32 v50, v51, v50
	v_cndmask_b32_e32 v50, v123, v50, vcc
	global_store_dword v243, v50, s[8:9] offset:2048
	s_add_u32 s8, s8, 0x1000
	s_addc_u32 s9, s9, 0
	v_mfma_f32_32x32x16_bf16 v[6:21], v[86:89], v[38:41], 0
	s_add_i32 m0, s10, 32768
	s_nop 0
	global_load_lds_dwordx4 v102, s[6:7]
	s_add_i32 m0, s10, 33792
	s_nop 0
	global_load_lds_dwordx4 v110, s[6:7]
	s_add_i32 m0, s10, 34816
	s_nop 0
	global_load_lds_dwordx4 v112, s[6:7]
	s_add_i32 m0, s10, 35840
	s_nop 0
	global_load_lds_dwordx4 v193, s[6:7]
	s_add_u32 s6, s6, 0x8000
	s_addc_u32 s7, s7, 0
	v_max_f32_e32 v108, 0, v212
	v_max_f32_e32 v109, 0, v213
	v_pk_mul_f32 v[0:1], v[22:23], v[108:109]
	v_max_f32_e32 v210, 0, v214
	v_max_f32_e32 v211, 0, v215
	v_pk_fma_f32 v[0:1], v[24:25], v[210:211], v[0:1]
	v_max_f32_e32 v108, 0, v216
	v_max_f32_e32 v109, 0, v217
	v_pk_fma_f32 v[0:1], v[26:27], v[108:109], v[0:1]
	v_mfma_f32_32x32x16_bf16 v[6:21], v[90:93], v[42:45], v[6:21]
	v_max_f32_e32 v210, 0, v218
	v_max_f32_e32 v211, 0, v219
	v_pk_fma_f32 v[0:1], v[28:29], v[210:211], v[0:1]
	v_max_f32_e32 v108, 0, v220
	v_max_f32_e32 v109, 0, v221
	v_pk_fma_f32 v[0:1], v[30:31], v[108:109], v[0:1]
	v_max_f32_e32 v210, 0, v222
	v_max_f32_e32 v211, 0, v223
	v_pk_fma_f32 v[0:1], v[32:33], v[210:211], v[0:1]
	v_mfma_f32_32x32x16_bf16 v[6:21], v[94:97], v[46:49], v[6:21]
	v_max_f32_e32 v108, 0, v224
	v_max_f32_e32 v109, 0, v225
	v_pk_fma_f32 v[0:1], v[34:35], v[108:109], v[0:1]
	v_max_f32_e32 v210, 0, v226
	v_max_f32_e32 v211, 0, v227
	v_pk_fma_f32 v[0:1], v[36:37], v[210:211], v[0:1]
	v_add_f32_e32 v0, v0, v1
	v_ashrrev_i32_e32 v1, 31, v0
	v_mfma_f32_32x32x16_bf16 v[6:21], v[98:101], v[196:199], v[6:21]
	s_waitcnt vmcnt(10)
	v_add_u32_e32 v228, 0x10000, v5
	ds_read_b128 v[38:41], v228 offset:43264
	v_add_u32_e32 v228, 0x10000, v52
	ds_read_b128 v[42:45], v228 offset:43264
	v_add_u32_e32 v228, 0x10000, v55
	ds_read_b128 v[46:49], v228 offset:43264
	v_add_u32_e32 v228, 0x10000, v56
	ds_read_b128 v[196:199], v228 offset:43264
	v_or_b32_e32 v1, 0x80000000, v1
	s_cmpk_gt_i32 s11, 272
	s_cselect_b64 vcc, -1, 0
	v_xor_b32_e32 v0, v1, v0
	v_cndmask_b32_e32 v167, v123, v0, vcc
	s_nop 3
	s_waitcnt lgkmcnt(3)
	v_mfma_f32_32x32x16_bf16 v[212:227], v[70:73], v[38:41], 0
	v_max_f32_e32 v108, 0, v6
	v_max_f32_e32 v109, 0, v7
	v_pk_mul_f32 v[50:51], v[244:245], v[108:109]
	v_max_f32_e32 v210, 0, v8
	v_max_f32_e32 v211, 0, v9
	v_pk_fma_f32 v[50:51], v[246:247], v[210:211], v[50:51]
	v_max_f32_e32 v108, 0, v10
	v_max_f32_e32 v109, 0, v11
	v_pk_fma_f32 v[50:51], v[248:249], v[108:109], v[50:51]
	s_waitcnt lgkmcnt(2)
	v_mfma_f32_32x32x16_bf16 v[212:227], v[74:77], v[42:45], v[212:227]
	v_max_f32_e32 v210, 0, v12
	v_max_f32_e32 v211, 0, v13
	v_pk_fma_f32 v[50:51], v[250:251], v[210:211], v[50:51]
	v_max_f32_e32 v108, 0, v14
	v_max_f32_e32 v109, 0, v15
	v_pk_fma_f32 v[50:51], v[252:253], v[108:109], v[50:51]
	v_max_f32_e32 v210, 0, v16
	v_max_f32_e32 v211, 0, v17
	v_pk_fma_f32 v[50:51], v[254:255], v[210:211], v[50:51]
	s_waitcnt lgkmcnt(1)
	v_mfma_f32_32x32x16_bf16 v[212:227], v[78:81], v[46:49], v[212:227]
	v_max_f32_e32 v108, 0, v18
	v_max_f32_e32 v109, 0, v19
	v_pk_fma_f32 v[50:51], v[200:201], v[108:109], v[50:51]
	v_max_f32_e32 v210, 0, v20
	v_max_f32_e32 v211, 0, v21
	v_pk_fma_f32 v[50:51], v[202:203], v[210:211], v[50:51]
	v_add_f32_e32 v50, v50, v51
	v_ashrrev_i32_e32 v51, 31, v50
	s_waitcnt lgkmcnt(0)
	v_mfma_f32_32x32x16_bf16 v[212:227], v[82:85], v[196:199], v[212:227]
	v_or_b32_e32 v51, 0x80000000, v51
	s_cmpk_gt_i32 s11, 272
	s_cselect_b64 vcc, -1, 0
	v_xor_b32_e32 v50, v51, v50
	v_cndmask_b32_e32 v50, v123, v50, vcc
	global_store_dword v243, v50, s[8:9]
	v_mfma_f32_32x32x16_bf16 v[6:21], v[86:89], v[38:41], 0
	s_add_i32 m0, s10, 65536
	s_nop 0
	global_load_lds_dwordx4 v102, s[6:7]
	s_add_i32 m0, s10, 66560
	s_nop 0
	global_load_lds_dwordx4 v110, s[6:7]
	s_add_i32 m0, s10, 67584
	s_nop 0
	global_load_lds_dwordx4 v112, s[6:7]
	s_add_i32 m0, s10, 68608
	s_nop 0
	global_load_lds_dwordx4 v193, s[6:7]
	s_add_u32 s6, s6, 0x8000
	s_addc_u32 s7, s7, 0
	v_max_f32_e32 v108, 0, v212
	v_max_f32_e32 v109, 0, v213
	v_pk_mul_f32 v[0:1], v[22:23], v[108:109]
	v_max_f32_e32 v210, 0, v214
	v_max_f32_e32 v211, 0, v215
	v_pk_fma_f32 v[0:1], v[24:25], v[210:211], v[0:1]
	v_max_f32_e32 v108, 0, v216
	v_max_f32_e32 v109, 0, v217
	v_pk_fma_f32 v[0:1], v[26:27], v[108:109], v[0:1]
	v_mfma_f32_32x32x16_bf16 v[6:21], v[90:93], v[42:45], v[6:21]
	v_max_f32_e32 v210, 0, v218
	v_max_f32_e32 v211, 0, v219
	v_pk_fma_f32 v[0:1], v[28:29], v[210:211], v[0:1]
	v_max_f32_e32 v108, 0, v220
	v_max_f32_e32 v109, 0, v221
	v_pk_fma_f32 v[0:1], v[30:31], v[108:109], v[0:1]
	v_max_f32_e32 v210, 0, v222
	v_max_f32_e32 v211, 0, v223
	v_pk_fma_f32 v[0:1], v[32:33], v[210:211], v[0:1]
	v_mfma_f32_32x32x16_bf16 v[6:21], v[94:97], v[46:49], v[6:21]
	v_max_f32_e32 v108, 0, v224
	v_max_f32_e32 v109, 0, v225
	v_pk_fma_f32 v[0:1], v[34:35], v[108:109], v[0:1]
	v_max_f32_e32 v210, 0, v226
	v_max_f32_e32 v211, 0, v227
	v_pk_fma_f32 v[0:1], v[36:37], v[210:211], v[0:1]
	v_add_f32_e32 v0, v0, v1
	v_ashrrev_i32_e32 v1, 31, v0
	v_mfma_f32_32x32x16_bf16 v[6:21], v[98:101], v[196:199], v[6:21]
	s_waitcnt vmcnt(10)
	ds_read_b128 v[38:41], v5 offset:10496
	ds_read_b128 v[42:45], v52 offset:10496
	ds_read_b128 v[46:49], v55 offset:10496
	ds_read_b128 v[196:199], v56 offset:10496
	v_or_b32_e32 v1, 0x80000000, v1
	s_cmpk_gt_i32 s11, 280
	s_cselect_b64 vcc, -1, 0
	v_xor_b32_e32 v0, v1, v0
	v_cndmask_b32_e32 v166, v123, v0, vcc
	s_nop 3
	s_waitcnt lgkmcnt(3)
	v_mfma_f32_32x32x16_bf16 v[212:227], v[70:73], v[38:41], 0
	v_max_f32_e32 v108, 0, v6
	v_max_f32_e32 v109, 0, v7
	v_pk_mul_f32 v[50:51], v[244:245], v[108:109]
	v_max_f32_e32 v210, 0, v8
	v_max_f32_e32 v211, 0, v9
	v_pk_fma_f32 v[50:51], v[246:247], v[210:211], v[50:51]
	v_max_f32_e32 v108, 0, v10
	v_max_f32_e32 v109, 0, v11
	v_pk_fma_f32 v[50:51], v[248:249], v[108:109], v[50:51]
	s_waitcnt lgkmcnt(2)
	v_mfma_f32_32x32x16_bf16 v[212:227], v[74:77], v[42:45], v[212:227]
	v_max_f32_e32 v210, 0, v12
	v_max_f32_e32 v211, 0, v13
	v_pk_fma_f32 v[50:51], v[250:251], v[210:211], v[50:51]
	v_max_f32_e32 v108, 0, v14
	v_max_f32_e32 v109, 0, v15
	v_pk_fma_f32 v[50:51], v[252:253], v[108:109], v[50:51]
	v_max_f32_e32 v210, 0, v16
	v_max_f32_e32 v211, 0, v17
	v_pk_fma_f32 v[50:51], v[254:255], v[210:211], v[50:51]
	s_waitcnt lgkmcnt(1)
	v_mfma_f32_32x32x16_bf16 v[212:227], v[78:81], v[46:49], v[212:227]
	v_max_f32_e32 v108, 0, v18
	v_max_f32_e32 v109, 0, v19
	v_pk_fma_f32 v[50:51], v[200:201], v[108:109], v[50:51]
	v_max_f32_e32 v210, 0, v20
	v_max_f32_e32 v211, 0, v21
	v_pk_fma_f32 v[50:51], v[202:203], v[210:211], v[50:51]
	v_add_f32_e32 v50, v50, v51
	v_ashrrev_i32_e32 v51, 31, v50
	s_waitcnt lgkmcnt(0)
	v_mfma_f32_32x32x16_bf16 v[212:227], v[82:85], v[196:199], v[212:227]
	v_or_b32_e32 v51, 0x80000000, v51
	s_cmpk_gt_i32 s11, 280
	s_cselect_b64 vcc, -1, 0
	v_xor_b32_e32 v50, v51, v50
	v_cndmask_b32_e32 v50, v123, v50, vcc
	global_store_dword v243, v50, s[8:9] offset:2048
	s_add_u32 s8, s8, 0x1000
	s_addc_u32 s9, s9, 0
	v_mfma_f32_32x32x16_bf16 v[6:21], v[86:89], v[38:41], 0
	s_add_i32 m0, s10, 98304
	s_nop 0
	global_load_lds_dwordx4 v102, s[6:7]
	s_add_i32 m0, s10, 99328
	s_nop 0
	global_load_lds_dwordx4 v110, s[6:7]
	s_add_i32 m0, s10, 100352
	s_nop 0
	global_load_lds_dwordx4 v112, s[6:7]
	s_add_i32 m0, s10, 101376
	s_nop 0
	global_load_lds_dwordx4 v193, s[6:7]
	s_add_u32 s6, s6, 0x8000
	s_addc_u32 s7, s7, 0
	v_max_f32_e32 v108, 0, v212
	v_max_f32_e32 v109, 0, v213
	v_pk_mul_f32 v[0:1], v[22:23], v[108:109]
	v_max_f32_e32 v210, 0, v214
	v_max_f32_e32 v211, 0, v215
	v_pk_fma_f32 v[0:1], v[24:25], v[210:211], v[0:1]
	v_max_f32_e32 v108, 0, v216
	v_max_f32_e32 v109, 0, v217
	v_pk_fma_f32 v[0:1], v[26:27], v[108:109], v[0:1]
	v_mfma_f32_32x32x16_bf16 v[6:21], v[90:93], v[42:45], v[6:21]
	v_max_f32_e32 v210, 0, v218
	v_max_f32_e32 v211, 0, v219
	v_pk_fma_f32 v[0:1], v[28:29], v[210:211], v[0:1]
	v_max_f32_e32 v108, 0, v220
	v_max_f32_e32 v109, 0, v221
	v_pk_fma_f32 v[0:1], v[30:31], v[108:109], v[0:1]
	v_max_f32_e32 v210, 0, v222
	v_max_f32_e32 v211, 0, v223
	v_pk_fma_f32 v[0:1], v[32:33], v[210:211], v[0:1]
	v_mfma_f32_32x32x16_bf16 v[6:21], v[94:97], v[46:49], v[6:21]
	v_max_f32_e32 v108, 0, v224
	v_max_f32_e32 v109, 0, v225
	v_pk_fma_f32 v[0:1], v[34:35], v[108:109], v[0:1]
	v_max_f32_e32 v210, 0, v226
	v_max_f32_e32 v211, 0, v227
	v_pk_fma_f32 v[0:1], v[36:37], v[210:211], v[0:1]
	v_add_f32_e32 v0, v0, v1
	v_ashrrev_i32_e32 v1, 31, v0
	v_mfma_f32_32x32x16_bf16 v[6:21], v[98:101], v[196:199], v[6:21]
	s_waitcnt vmcnt(10)
	ds_read_b128 v[38:41], v5 offset:43264
	ds_read_b128 v[42:45], v52 offset:43264
	ds_read_b128 v[46:49], v55 offset:43264
	ds_read_b128 v[196:199], v56 offset:43264
	v_or_b32_e32 v1, 0x80000000, v1
	s_cmpk_gt_i32 s11, 288
	s_cselect_b64 vcc, -1, 0
	v_xor_b32_e32 v0, v1, v0
	v_cndmask_b32_e32 v170, v123, v0, vcc
	s_nop 3
	s_waitcnt lgkmcnt(3)
	v_mfma_f32_32x32x16_bf16 v[212:227], v[70:73], v[38:41], 0
	v_max_f32_e32 v108, 0, v6
	v_max_f32_e32 v109, 0, v7
	v_pk_mul_f32 v[50:51], v[244:245], v[108:109]
	v_max_f32_e32 v210, 0, v8
	v_max_f32_e32 v211, 0, v9
	v_pk_fma_f32 v[50:51], v[246:247], v[210:211], v[50:51]
	v_max_f32_e32 v108, 0, v10
	v_max_f32_e32 v109, 0, v11
	v_pk_fma_f32 v[50:51], v[248:249], v[108:109], v[50:51]
	s_waitcnt lgkmcnt(2)
	v_mfma_f32_32x32x16_bf16 v[212:227], v[74:77], v[42:45], v[212:227]
	v_max_f32_e32 v210, 0, v12
	v_max_f32_e32 v211, 0, v13
	v_pk_fma_f32 v[50:51], v[250:251], v[210:211], v[50:51]
	v_max_f32_e32 v108, 0, v14
	v_max_f32_e32 v109, 0, v15
	v_pk_fma_f32 v[50:51], v[252:253], v[108:109], v[50:51]
	v_max_f32_e32 v210, 0, v16
	v_max_f32_e32 v211, 0, v17
	v_pk_fma_f32 v[50:51], v[254:255], v[210:211], v[50:51]
	s_waitcnt lgkmcnt(1)
	v_mfma_f32_32x32x16_bf16 v[212:227], v[78:81], v[46:49], v[212:227]
	v_max_f32_e32 v108, 0, v18
	v_max_f32_e32 v109, 0, v19
	v_pk_fma_f32 v[50:51], v[200:201], v[108:109], v[50:51]
	v_max_f32_e32 v210, 0, v20
	v_max_f32_e32 v211, 0, v21
	v_pk_fma_f32 v[50:51], v[202:203], v[210:211], v[50:51]
	v_add_f32_e32 v50, v50, v51
	v_ashrrev_i32_e32 v51, 31, v50
	s_waitcnt lgkmcnt(0)
	v_mfma_f32_32x32x16_bf16 v[212:227], v[82:85], v[196:199], v[212:227]
	v_or_b32_e32 v51, 0x80000000, v51
	s_cmpk_gt_i32 s11, 288
	s_cselect_b64 vcc, -1, 0
	v_xor_b32_e32 v50, v51, v50
	v_cndmask_b32_e32 v50, v123, v50, vcc
	global_store_dword v243, v50, s[8:9]
	v_mfma_f32_32x32x16_bf16 v[6:21], v[86:89], v[38:41], 0
	s_add_i32 m0, s10, 0
	s_nop 0
	global_load_lds_dwordx4 v102, s[6:7]
	s_add_i32 m0, s10, 1024
	s_nop 0
	global_load_lds_dwordx4 v110, s[6:7]
	s_add_i32 m0, s10, 2048
	s_nop 0
	global_load_lds_dwordx4 v112, s[6:7]
	s_add_i32 m0, s10, 3072
	s_nop 0
	global_load_lds_dwordx4 v193, s[6:7]
	s_add_u32 s6, s6, 0x8000
	s_addc_u32 s7, s7, 0
	v_max_f32_e32 v108, 0, v212
	v_max_f32_e32 v109, 0, v213
	v_pk_mul_f32 v[0:1], v[22:23], v[108:109]
	v_max_f32_e32 v210, 0, v214
	v_max_f32_e32 v211, 0, v215
	v_pk_fma_f32 v[0:1], v[24:25], v[210:211], v[0:1]
	v_max_f32_e32 v108, 0, v216
	v_max_f32_e32 v109, 0, v217
	v_pk_fma_f32 v[0:1], v[26:27], v[108:109], v[0:1]
	v_mfma_f32_32x32x16_bf16 v[6:21], v[90:93], v[42:45], v[6:21]
	v_max_f32_e32 v210, 0, v218
	v_max_f32_e32 v211, 0, v219
	v_pk_fma_f32 v[0:1], v[28:29], v[210:211], v[0:1]
	v_max_f32_e32 v108, 0, v220
	v_max_f32_e32 v109, 0, v221
	v_pk_fma_f32 v[0:1], v[30:31], v[108:109], v[0:1]
	v_max_f32_e32 v210, 0, v222
	v_max_f32_e32 v211, 0, v223
	v_pk_fma_f32 v[0:1], v[32:33], v[210:211], v[0:1]
	v_mfma_f32_32x32x16_bf16 v[6:21], v[94:97], v[46:49], v[6:21]
	v_max_f32_e32 v108, 0, v224
	v_max_f32_e32 v109, 0, v225
	v_pk_fma_f32 v[0:1], v[34:35], v[108:109], v[0:1]
	v_max_f32_e32 v210, 0, v226
	v_max_f32_e32 v211, 0, v227
	v_pk_fma_f32 v[0:1], v[36:37], v[210:211], v[0:1]
	v_add_f32_e32 v0, v0, v1
	v_ashrrev_i32_e32 v1, 31, v0
	v_mfma_f32_32x32x16_bf16 v[6:21], v[98:101], v[196:199], v[6:21]
	s_waitcnt vmcnt(10)
	v_add_u32_e32 v228, 0x10000, v5
	ds_read_b128 v[38:41], v228 offset:10496
	v_add_u32_e32 v228, 0x10000, v52
	ds_read_b128 v[42:45], v228 offset:10496
	v_add_u32_e32 v228, 0x10000, v55
	ds_read_b128 v[46:49], v228 offset:10496
	v_add_u32_e32 v228, 0x10000, v56
	ds_read_b128 v[196:199], v228 offset:10496
	v_or_b32_e32 v1, 0x80000000, v1
	s_cmpk_gt_i32 s11, 296
	s_cselect_b64 vcc, -1, 0
	v_xor_b32_e32 v0, v1, v0
	v_cndmask_b32_e32 v169, v123, v0, vcc
	s_nop 3
	s_waitcnt lgkmcnt(3)
	v_mfma_f32_32x32x16_bf16 v[212:227], v[70:73], v[38:41], 0
	v_max_f32_e32 v108, 0, v6
	v_max_f32_e32 v109, 0, v7
	v_pk_mul_f32 v[50:51], v[244:245], v[108:109]
	v_max_f32_e32 v210, 0, v8
	v_max_f32_e32 v211, 0, v9
	v_pk_fma_f32 v[50:51], v[246:247], v[210:211], v[50:51]
	v_max_f32_e32 v108, 0, v10
	v_max_f32_e32 v109, 0, v11
	v_pk_fma_f32 v[50:51], v[248:249], v[108:109], v[50:51]
	s_waitcnt lgkmcnt(2)
	v_mfma_f32_32x32x16_bf16 v[212:227], v[74:77], v[42:45], v[212:227]
	v_max_f32_e32 v210, 0, v12
	v_max_f32_e32 v211, 0, v13
	v_pk_fma_f32 v[50:51], v[250:251], v[210:211], v[50:51]
	v_max_f32_e32 v108, 0, v14
	v_max_f32_e32 v109, 0, v15
	v_pk_fma_f32 v[50:51], v[252:253], v[108:109], v[50:51]
	v_max_f32_e32 v210, 0, v16
	v_max_f32_e32 v211, 0, v17
	v_pk_fma_f32 v[50:51], v[254:255], v[210:211], v[50:51]
	s_waitcnt lgkmcnt(1)
	v_mfma_f32_32x32x16_bf16 v[212:227], v[78:81], v[46:49], v[212:227]
	v_max_f32_e32 v108, 0, v18
	v_max_f32_e32 v109, 0, v19
	v_pk_fma_f32 v[50:51], v[200:201], v[108:109], v[50:51]
	v_max_f32_e32 v210, 0, v20
	v_max_f32_e32 v211, 0, v21
	v_pk_fma_f32 v[50:51], v[202:203], v[210:211], v[50:51]
	v_add_f32_e32 v50, v50, v51
	v_ashrrev_i32_e32 v51, 31, v50
	s_waitcnt lgkmcnt(0)
	v_mfma_f32_32x32x16_bf16 v[212:227], v[82:85], v[196:199], v[212:227]
	v_or_b32_e32 v51, 0x80000000, v51
	s_cmpk_gt_i32 s11, 296
	s_cselect_b64 vcc, -1, 0
	v_xor_b32_e32 v50, v51, v50
	v_cndmask_b32_e32 v50, v123, v50, vcc
	global_store_dword v243, v50, s[8:9] offset:2048
	s_add_u32 s8, s8, 0x1000
	s_addc_u32 s9, s9, 0
	v_mfma_f32_32x32x16_bf16 v[6:21], v[86:89], v[38:41], 0
	s_add_i32 m0, s10, 32768
	s_nop 0
	global_load_lds_dwordx4 v102, s[6:7]
	s_add_i32 m0, s10, 33792
	s_nop 0
	global_load_lds_dwordx4 v110, s[6:7]
	s_add_i32 m0, s10, 34816
	s_nop 0
	global_load_lds_dwordx4 v112, s[6:7]
	s_add_i32 m0, s10, 35840
	s_nop 0
	global_load_lds_dwordx4 v193, s[6:7]
	s_add_u32 s6, s6, 0x8000
	s_addc_u32 s7, s7, 0
	v_max_f32_e32 v108, 0, v212
	v_max_f32_e32 v109, 0, v213
	v_pk_mul_f32 v[0:1], v[22:23], v[108:109]
	v_max_f32_e32 v210, 0, v214
	v_max_f32_e32 v211, 0, v215
	v_pk_fma_f32 v[0:1], v[24:25], v[210:211], v[0:1]
	v_max_f32_e32 v108, 0, v216
	v_max_f32_e32 v109, 0, v217
	v_pk_fma_f32 v[0:1], v[26:27], v[108:109], v[0:1]
	v_mfma_f32_32x32x16_bf16 v[6:21], v[90:93], v[42:45], v[6:21]
	v_max_f32_e32 v210, 0, v218
	v_max_f32_e32 v211, 0, v219
	v_pk_fma_f32 v[0:1], v[28:29], v[210:211], v[0:1]
	v_max_f32_e32 v108, 0, v220
	v_max_f32_e32 v109, 0, v221
	v_pk_fma_f32 v[0:1], v[30:31], v[108:109], v[0:1]
	v_max_f32_e32 v210, 0, v222
	v_max_f32_e32 v211, 0, v223
	v_pk_fma_f32 v[0:1], v[32:33], v[210:211], v[0:1]
	v_mfma_f32_32x32x16_bf16 v[6:21], v[94:97], v[46:49], v[6:21]
	v_max_f32_e32 v108, 0, v224
	v_max_f32_e32 v109, 0, v225
	v_pk_fma_f32 v[0:1], v[34:35], v[108:109], v[0:1]
	v_max_f32_e32 v210, 0, v226
	v_max_f32_e32 v211, 0, v227
	v_pk_fma_f32 v[0:1], v[36:37], v[210:211], v[0:1]
	v_add_f32_e32 v0, v0, v1
	v_ashrrev_i32_e32 v1, 31, v0
	v_mfma_f32_32x32x16_bf16 v[6:21], v[98:101], v[196:199], v[6:21]
	s_waitcnt vmcnt(10)
	v_add_u32_e32 v228, 0x10000, v5
	ds_read_b128 v[38:41], v228 offset:43264
	v_add_u32_e32 v228, 0x10000, v52
	ds_read_b128 v[42:45], v228 offset:43264
	v_add_u32_e32 v228, 0x10000, v55
	ds_read_b128 v[46:49], v228 offset:43264
	v_add_u32_e32 v228, 0x10000, v56
	ds_read_b128 v[196:199], v228 offset:43264
	v_or_b32_e32 v1, 0x80000000, v1
	s_cmpk_gt_i32 s11, 304
	s_cselect_b64 vcc, -1, 0
	v_xor_b32_e32 v0, v1, v0
	v_cndmask_b32_e32 v172, v123, v0, vcc
	s_nop 3
	s_waitcnt lgkmcnt(3)
	v_mfma_f32_32x32x16_bf16 v[212:227], v[70:73], v[38:41], 0
	v_max_f32_e32 v108, 0, v6
	v_max_f32_e32 v109, 0, v7
	v_pk_mul_f32 v[50:51], v[244:245], v[108:109]
	v_max_f32_e32 v210, 0, v8
	v_max_f32_e32 v211, 0, v9
	v_pk_fma_f32 v[50:51], v[246:247], v[210:211], v[50:51]
	v_max_f32_e32 v108, 0, v10
	v_max_f32_e32 v109, 0, v11
	v_pk_fma_f32 v[50:51], v[248:249], v[108:109], v[50:51]
	s_waitcnt lgkmcnt(2)
	v_mfma_f32_32x32x16_bf16 v[212:227], v[74:77], v[42:45], v[212:227]
	v_max_f32_e32 v210, 0, v12
	v_max_f32_e32 v211, 0, v13
	v_pk_fma_f32 v[50:51], v[250:251], v[210:211], v[50:51]
	v_max_f32_e32 v108, 0, v14
	v_max_f32_e32 v109, 0, v15
	v_pk_fma_f32 v[50:51], v[252:253], v[108:109], v[50:51]
	v_max_f32_e32 v210, 0, v16
	v_max_f32_e32 v211, 0, v17
	v_pk_fma_f32 v[50:51], v[254:255], v[210:211], v[50:51]
	s_waitcnt lgkmcnt(1)
	v_mfma_f32_32x32x16_bf16 v[212:227], v[78:81], v[46:49], v[212:227]
	v_max_f32_e32 v108, 0, v18
	v_max_f32_e32 v109, 0, v19
	v_pk_fma_f32 v[50:51], v[200:201], v[108:109], v[50:51]
	v_max_f32_e32 v210, 0, v20
	v_max_f32_e32 v211, 0, v21
	v_pk_fma_f32 v[50:51], v[202:203], v[210:211], v[50:51]
	v_add_f32_e32 v50, v50, v51
	v_ashrrev_i32_e32 v51, 31, v50
	s_waitcnt lgkmcnt(0)
	v_mfma_f32_32x32x16_bf16 v[212:227], v[82:85], v[196:199], v[212:227]
	v_or_b32_e32 v51, 0x80000000, v51
	s_cmpk_gt_i32 s11, 304
	s_cselect_b64 vcc, -1, 0
	v_xor_b32_e32 v50, v51, v50
	v_cndmask_b32_e32 v50, v123, v50, vcc
	global_store_dword v243, v50, s[8:9]
	v_mfma_f32_32x32x16_bf16 v[6:21], v[86:89], v[38:41], 0
	s_add_i32 m0, s10, 65536
	s_nop 0
	global_load_lds_dwordx4 v102, s[6:7]
	s_add_i32 m0, s10, 66560
	s_nop 0
	global_load_lds_dwordx4 v110, s[6:7]
	s_add_i32 m0, s10, 67584
	s_nop 0
	global_load_lds_dwordx4 v112, s[6:7]
	s_add_i32 m0, s10, 68608
	s_nop 0
	global_load_lds_dwordx4 v193, s[6:7]
	s_add_u32 s6, s6, 0x8000
	s_addc_u32 s7, s7, 0
	v_max_f32_e32 v108, 0, v212
	v_max_f32_e32 v109, 0, v213
	v_pk_mul_f32 v[0:1], v[22:23], v[108:109]
	v_max_f32_e32 v210, 0, v214
	v_max_f32_e32 v211, 0, v215
	v_pk_fma_f32 v[0:1], v[24:25], v[210:211], v[0:1]
	v_max_f32_e32 v108, 0, v216
	v_max_f32_e32 v109, 0, v217
	v_pk_fma_f32 v[0:1], v[26:27], v[108:109], v[0:1]
	v_mfma_f32_32x32x16_bf16 v[6:21], v[90:93], v[42:45], v[6:21]
	v_max_f32_e32 v210, 0, v218
	v_max_f32_e32 v211, 0, v219
	v_pk_fma_f32 v[0:1], v[28:29], v[210:211], v[0:1]
	v_max_f32_e32 v108, 0, v220
	v_max_f32_e32 v109, 0, v221
	v_pk_fma_f32 v[0:1], v[30:31], v[108:109], v[0:1]
	v_max_f32_e32 v210, 0, v222
	v_max_f32_e32 v211, 0, v223
	v_pk_fma_f32 v[0:1], v[32:33], v[210:211], v[0:1]
	v_mfma_f32_32x32x16_bf16 v[6:21], v[94:97], v[46:49], v[6:21]
	v_max_f32_e32 v108, 0, v224
	v_max_f32_e32 v109, 0, v225
	v_pk_fma_f32 v[0:1], v[34:35], v[108:109], v[0:1]
	v_max_f32_e32 v210, 0, v226
	v_max_f32_e32 v211, 0, v227
	v_pk_fma_f32 v[0:1], v[36:37], v[210:211], v[0:1]
	v_add_f32_e32 v0, v0, v1
	v_ashrrev_i32_e32 v1, 31, v0
	v_mfma_f32_32x32x16_bf16 v[6:21], v[98:101], v[196:199], v[6:21]
	s_waitcnt vmcnt(10)
	ds_read_b128 v[38:41], v5 offset:10496
	ds_read_b128 v[42:45], v52 offset:10496
	ds_read_b128 v[46:49], v55 offset:10496
	ds_read_b128 v[196:199], v56 offset:10496
	v_or_b32_e32 v1, 0x80000000, v1
	s_cmpk_gt_i32 s11, 312
	s_cselect_b64 vcc, -1, 0
	v_xor_b32_e32 v0, v1, v0
	v_cndmask_b32_e32 v171, v123, v0, vcc
	s_nop 3
	v_max_f32_e32 v108, 0, v6
	v_max_f32_e32 v109, 0, v7
	v_pk_mul_f32 v[50:51], v[244:245], v[108:109]
	v_max_f32_e32 v210, 0, v8
	v_max_f32_e32 v211, 0, v9
	v_pk_fma_f32 v[50:51], v[246:247], v[210:211], v[50:51]
	v_max_f32_e32 v108, 0, v10
	v_max_f32_e32 v109, 0, v11
	v_pk_fma_f32 v[50:51], v[248:249], v[108:109], v[50:51]
	v_max_f32_e32 v210, 0, v12
	v_max_f32_e32 v211, 0, v13
	v_pk_fma_f32 v[50:51], v[250:251], v[210:211], v[50:51]
	v_max_f32_e32 v108, 0, v14
	v_max_f32_e32 v109, 0, v15
	v_pk_fma_f32 v[50:51], v[252:253], v[108:109], v[50:51]
	v_max_f32_e32 v210, 0, v16
	v_max_f32_e32 v211, 0, v17
	v_pk_fma_f32 v[50:51], v[254:255], v[210:211], v[50:51]
	v_max_f32_e32 v108, 0, v18
	v_max_f32_e32 v109, 0, v19
	v_pk_fma_f32 v[50:51], v[200:201], v[108:109], v[50:51]
	v_max_f32_e32 v210, 0, v20
	v_max_f32_e32 v211, 0, v21
	v_pk_fma_f32 v[50:51], v[202:203], v[210:211], v[50:51]
	v_add_f32_e32 v50, v50, v51
	v_ashrrev_i32_e32 v51, 31, v50
	v_or_b32_e32 v51, 0x80000000, v51
	s_cmpk_gt_i32 s11, 312
	s_cselect_b64 vcc, -1, 0
	v_xor_b32_e32 v50, v51, v50
	v_cndmask_b32_e32 v50, v123, v50, vcc
	global_store_dword v243, v50, s[8:9] offset:2048
	s_add_u32 s8, s8, 0x1000
	s_addc_u32 s9, s9, 0
	s_cmpk_gt_i32 s81, 40
	s_cbranch_scc0 .Lix_fill_5
	s_waitcnt lgkmcnt(3)
	v_mfma_f32_32x32x16_bf16 v[212:227], v[70:73], v[38:41], 0
	s_add_i32 m0, s10, 98304
	s_nop 0
	global_load_lds_dwordx4 v102, s[6:7]
	s_waitcnt lgkmcnt(2)
	v_mfma_f32_32x32x16_bf16 v[212:227], v[74:77], v[42:45], v[212:227]
	s_add_i32 m0, s10, 99328
	s_nop 0
	global_load_lds_dwordx4 v110, s[6:7]
	s_waitcnt lgkmcnt(1)
	v_mfma_f32_32x32x16_bf16 v[212:227], v[78:81], v[46:49], v[212:227]
	s_add_i32 m0, s10, 100352
	s_nop 0
	global_load_lds_dwordx4 v112, s[6:7]
	s_waitcnt lgkmcnt(0)
	v_mfma_f32_32x32x16_bf16 v[212:227], v[82:85], v[196:199], v[212:227]
	s_add_i32 m0, s10, 101376
	s_nop 0
	global_load_lds_dwordx4 v193, s[6:7]
	s_add_u32 s6, s6, 0x8000
	s_addc_u32 s7, s7, 0
	v_mfma_f32_32x32x16_bf16 v[6:21], v[86:89], v[38:41], 0
	s_nop 7
	s_nop 2
	v_max_f32_e32 v108, 0, v212
	v_max_f32_e32 v109, 0, v213
	v_pk_mul_f32 v[0:1], v[22:23], v[108:109]
	v_max_f32_e32 v210, 0, v214
	v_max_f32_e32 v211, 0, v215
	v_pk_fma_f32 v[0:1], v[24:25], v[210:211], v[0:1]
	v_max_f32_e32 v108, 0, v216
	v_max_f32_e32 v109, 0, v217
	v_pk_fma_f32 v[0:1], v[26:27], v[108:109], v[0:1]
	v_mfma_f32_32x32x16_bf16 v[6:21], v[90:93], v[42:45], v[6:21]
	v_max_f32_e32 v210, 0, v218
	v_max_f32_e32 v211, 0, v219
	v_pk_fma_f32 v[0:1], v[28:29], v[210:211], v[0:1]
	v_max_f32_e32 v108, 0, v220
	v_max_f32_e32 v109, 0, v221
	v_pk_fma_f32 v[0:1], v[30:31], v[108:109], v[0:1]
	v_max_f32_e32 v210, 0, v222
	v_max_f32_e32 v211, 0, v223
	v_pk_fma_f32 v[0:1], v[32:33], v[210:211], v[0:1]
	v_mfma_f32_32x32x16_bf16 v[6:21], v[94:97], v[46:49], v[6:21]
	v_max_f32_e32 v108, 0, v224
	v_max_f32_e32 v109, 0, v225
	v_pk_fma_f32 v[0:1], v[34:35], v[108:109], v[0:1]
	v_max_f32_e32 v210, 0, v226
	v_max_f32_e32 v211, 0, v227
	v_pk_fma_f32 v[0:1], v[36:37], v[210:211], v[0:1]
	v_add_f32_e32 v0, v0, v1
	v_ashrrev_i32_e32 v1, 31, v0
	v_mfma_f32_32x32x16_bf16 v[6:21], v[98:101], v[196:199], v[6:21]
	s_waitcnt vmcnt(10)
	ds_read_b128 v[38:41], v5 offset:43264
	ds_read_b128 v[42:45], v52 offset:43264
	ds_read_b128 v[46:49], v55 offset:43264
	ds_read_b128 v[196:199], v56 offset:43264
	v_or_b32_e32 v1, 0x80000000, v1
	s_cmpk_gt_i32 s11, 320
	s_cselect_b64 vcc, -1, 0
	v_xor_b32_e32 v0, v1, v0
	v_cndmask_b32_e32 v174, v123, v0, vcc
	s_nop 3
	s_waitcnt lgkmcnt(3)
	v_mfma_f32_32x32x16_bf16 v[212:227], v[70:73], v[38:41], 0
	v_max_f32_e32 v108, 0, v6
	v_max_f32_e32 v109, 0, v7
	v_pk_mul_f32 v[50:51], v[244:245], v[108:109]
	v_max_f32_e32 v210, 0, v8
	v_max_f32_e32 v211, 0, v9
	v_pk_fma_f32 v[50:51], v[246:247], v[210:211], v[50:51]
	v_max_f32_e32 v108, 0, v10
	v_max_f32_e32 v109, 0, v11
	v_pk_fma_f32 v[50:51], v[248:249], v[108:109], v[50:51]
	s_waitcnt lgkmcnt(2)
	v_mfma_f32_32x32x16_bf16 v[212:227], v[74:77], v[42:45], v[212:227]
	v_max_f32_e32 v210, 0, v12
	v_max_f32_e32 v211, 0, v13
	v_pk_fma_f32 v[50:51], v[250:251], v[210:211], v[50:51]
	v_max_f32_e32 v108, 0, v14
	v_max_f32_e32 v109, 0, v15
	v_pk_fma_f32 v[50:51], v[252:253], v[108:109], v[50:51]
	v_max_f32_e32 v210, 0, v16
	v_max_f32_e32 v211, 0, v17
	v_pk_fma_f32 v[50:51], v[254:255], v[210:211], v[50:51]
	s_waitcnt lgkmcnt(1)
	v_mfma_f32_32x32x16_bf16 v[212:227], v[78:81], v[46:49], v[212:227]
	v_max_f32_e32 v108, 0, v18
	v_max_f32_e32 v109, 0, v19
	v_pk_fma_f32 v[50:51], v[200:201], v[108:109], v[50:51]
	v_max_f32_e32 v210, 0, v20
	v_max_f32_e32 v211, 0, v21
	v_pk_fma_f32 v[50:51], v[202:203], v[210:211], v[50:51]
	v_add_f32_e32 v50, v50, v51
	v_ashrrev_i32_e32 v51, 31, v50
	s_waitcnt lgkmcnt(0)
	v_mfma_f32_32x32x16_bf16 v[212:227], v[82:85], v[196:199], v[212:227]
	v_or_b32_e32 v51, 0x80000000, v51
	s_cmpk_gt_i32 s11, 320
	s_cselect_b64 vcc, -1, 0
	v_xor_b32_e32 v50, v51, v50
	v_cndmask_b32_e32 v50, v123, v50, vcc
	global_store_dword v243, v50, s[8:9]
	v_mfma_f32_32x32x16_bf16 v[6:21], v[86:89], v[38:41], 0
	s_add_i32 m0, s10, 0
	s_nop 0
	global_load_lds_dwordx4 v102, s[6:7]
	s_add_i32 m0, s10, 1024
	s_nop 0
	global_load_lds_dwordx4 v110, s[6:7]
	s_add_i32 m0, s10, 2048
	s_nop 0
	global_load_lds_dwordx4 v112, s[6:7]
	s_add_i32 m0, s10, 3072
	s_nop 0
	global_load_lds_dwordx4 v193, s[6:7]
	s_add_u32 s6, s6, 0x8000
	s_addc_u32 s7, s7, 0
	v_max_f32_e32 v108, 0, v212
	v_max_f32_e32 v109, 0, v213
	v_pk_mul_f32 v[0:1], v[22:23], v[108:109]
	v_max_f32_e32 v210, 0, v214
	v_max_f32_e32 v211, 0, v215
	v_pk_fma_f32 v[0:1], v[24:25], v[210:211], v[0:1]
	v_max_f32_e32 v108, 0, v216
	v_max_f32_e32 v109, 0, v217
	v_pk_fma_f32 v[0:1], v[26:27], v[108:109], v[0:1]
	v_mfma_f32_32x32x16_bf16 v[6:21], v[90:93], v[42:45], v[6:21]
	v_max_f32_e32 v210, 0, v218
	v_max_f32_e32 v211, 0, v219
	v_pk_fma_f32 v[0:1], v[28:29], v[210:211], v[0:1]
	v_max_f32_e32 v108, 0, v220
	v_max_f32_e32 v109, 0, v221
	v_pk_fma_f32 v[0:1], v[30:31], v[108:109], v[0:1]
	v_max_f32_e32 v210, 0, v222
	v_max_f32_e32 v211, 0, v223
	v_pk_fma_f32 v[0:1], v[32:33], v[210:211], v[0:1]
	v_mfma_f32_32x32x16_bf16 v[6:21], v[94:97], v[46:49], v[6:21]
	v_max_f32_e32 v108, 0, v224
	v_max_f32_e32 v109, 0, v225
	v_pk_fma_f32 v[0:1], v[34:35], v[108:109], v[0:1]
	v_max_f32_e32 v210, 0, v226
	v_max_f32_e32 v211, 0, v227
	v_pk_fma_f32 v[0:1], v[36:37], v[210:211], v[0:1]
	v_add_f32_e32 v0, v0, v1
	v_ashrrev_i32_e32 v1, 31, v0
	v_mfma_f32_32x32x16_bf16 v[6:21], v[98:101], v[196:199], v[6:21]
	s_waitcnt vmcnt(10)
	v_add_u32_e32 v228, 0x10000, v5
	ds_read_b128 v[38:41], v228 offset:10496
	v_add_u32_e32 v228, 0x10000, v52
	ds_read_b128 v[42:45], v228 offset:10496
	v_add_u32_e32 v228, 0x10000, v55
	ds_read_b128 v[46:49], v228 offset:10496
	v_add_u32_e32 v228, 0x10000, v56
	ds_read_b128 v[196:199], v228 offset:10496
	v_or_b32_e32 v1, 0x80000000, v1
	s_cmpk_gt_i32 s11, 328
	s_cselect_b64 vcc, -1, 0
	v_xor_b32_e32 v0, v1, v0
	v_cndmask_b32_e32 v173, v123, v0, vcc
	s_nop 3
	s_waitcnt lgkmcnt(3)
	v_mfma_f32_32x32x16_bf16 v[212:227], v[70:73], v[38:41], 0
	v_max_f32_e32 v108, 0, v6
	v_max_f32_e32 v109, 0, v7
	v_pk_mul_f32 v[50:51], v[244:245], v[108:109]
	v_max_f32_e32 v210, 0, v8
	v_max_f32_e32 v211, 0, v9
	v_pk_fma_f32 v[50:51], v[246:247], v[210:211], v[50:51]
	v_max_f32_e32 v108, 0, v10
	v_max_f32_e32 v109, 0, v11
	v_pk_fma_f32 v[50:51], v[248:249], v[108:109], v[50:51]
	s_waitcnt lgkmcnt(2)
	v_mfma_f32_32x32x16_bf16 v[212:227], v[74:77], v[42:45], v[212:227]
	v_max_f32_e32 v210, 0, v12
	v_max_f32_e32 v211, 0, v13
	v_pk_fma_f32 v[50:51], v[250:251], v[210:211], v[50:51]
	v_max_f32_e32 v108, 0, v14
	v_max_f32_e32 v109, 0, v15
	v_pk_fma_f32 v[50:51], v[252:253], v[108:109], v[50:51]
	v_max_f32_e32 v210, 0, v16
	v_max_f32_e32 v211, 0, v17
	v_pk_fma_f32 v[50:51], v[254:255], v[210:211], v[50:51]
	s_waitcnt lgkmcnt(1)
	v_mfma_f32_32x32x16_bf16 v[212:227], v[78:81], v[46:49], v[212:227]
	v_max_f32_e32 v108, 0, v18
	v_max_f32_e32 v109, 0, v19
	v_pk_fma_f32 v[50:51], v[200:201], v[108:109], v[50:51]
	v_max_f32_e32 v210, 0, v20
	v_max_f32_e32 v211, 0, v21
	v_pk_fma_f32 v[50:51], v[202:203], v[210:211], v[50:51]
	v_add_f32_e32 v50, v50, v51
	v_ashrrev_i32_e32 v51, 31, v50
	s_waitcnt lgkmcnt(0)
	v_mfma_f32_32x32x16_bf16 v[212:227], v[82:85], v[196:199], v[212:227]
	v_or_b32_e32 v51, 0x80000000, v51
	s_cmpk_gt_i32 s11, 328
	s_cselect_b64 vcc, -1, 0
	v_xor_b32_e32 v50, v51, v50
	v_cndmask_b32_e32 v50, v123, v50, vcc
	global_store_dword v243, v50, s[8:9] offset:2048
	s_add_u32 s8, s8, 0x1000
	s_addc_u32 s9, s9, 0
	v_mfma_f32_32x32x16_bf16 v[6:21], v[86:89], v[38:41], 0
	s_add_i32 m0, s10, 32768
	s_nop 0
	global_load_lds_dwordx4 v102, s[6:7]
	s_add_i32 m0, s10, 33792
	s_nop 0
	global_load_lds_dwordx4 v110, s[6:7]
	s_add_i32 m0, s10, 34816
	s_nop 0
	global_load_lds_dwordx4 v112, s[6:7]
	s_add_i32 m0, s10, 35840
	s_nop 0
	global_load_lds_dwordx4 v193, s[6:7]
	s_add_u32 s6, s6, 0x8000
	s_addc_u32 s7, s7, 0
	v_max_f32_e32 v108, 0, v212
	v_max_f32_e32 v109, 0, v213
	v_pk_mul_f32 v[0:1], v[22:23], v[108:109]
	v_max_f32_e32 v210, 0, v214
	v_max_f32_e32 v211, 0, v215
	v_pk_fma_f32 v[0:1], v[24:25], v[210:211], v[0:1]
	v_max_f32_e32 v108, 0, v216
	v_max_f32_e32 v109, 0, v217
	v_pk_fma_f32 v[0:1], v[26:27], v[108:109], v[0:1]
	v_mfma_f32_32x32x16_bf16 v[6:21], v[90:93], v[42:45], v[6:21]
	v_max_f32_e32 v210, 0, v218
	v_max_f32_e32 v211, 0, v219
	v_pk_fma_f32 v[0:1], v[28:29], v[210:211], v[0:1]
	v_max_f32_e32 v108, 0, v220
	v_max_f32_e32 v109, 0, v221
	v_pk_fma_f32 v[0:1], v[30:31], v[108:109], v[0:1]
	v_max_f32_e32 v210, 0, v222
	v_max_f32_e32 v211, 0, v223
	v_pk_fma_f32 v[0:1], v[32:33], v[210:211], v[0:1]
	v_mfma_f32_32x32x16_bf16 v[6:21], v[94:97], v[46:49], v[6:21]
	v_max_f32_e32 v108, 0, v224
	v_max_f32_e32 v109, 0, v225
	v_pk_fma_f32 v[0:1], v[34:35], v[108:109], v[0:1]
	v_max_f32_e32 v210, 0, v226
	v_max_f32_e32 v211, 0, v227
	v_pk_fma_f32 v[0:1], v[36:37], v[210:211], v[0:1]
	v_add_f32_e32 v0, v0, v1
	v_ashrrev_i32_e32 v1, 31, v0
	v_mfma_f32_32x32x16_bf16 v[6:21], v[98:101], v[196:199], v[6:21]
	s_waitcnt vmcnt(10)
	v_add_u32_e32 v228, 0x10000, v5
	ds_read_b128 v[38:41], v228 offset:43264
	v_add_u32_e32 v228, 0x10000, v52
	ds_read_b128 v[42:45], v228 offset:43264
	v_add_u32_e32 v228, 0x10000, v55
	ds_read_b128 v[46:49], v228 offset:43264
	v_add_u32_e32 v228, 0x10000, v56
	ds_read_b128 v[196:199], v228 offset:43264
	v_or_b32_e32 v1, 0x80000000, v1
	s_cmpk_gt_i32 s11, 336
	s_cselect_b64 vcc, -1, 0
	v_xor_b32_e32 v0, v1, v0
	v_cndmask_b32_e32 v176, v123, v0, vcc
	s_nop 3
	s_waitcnt lgkmcnt(3)
	v_mfma_f32_32x32x16_bf16 v[212:227], v[70:73], v[38:41], 0
	v_max_f32_e32 v108, 0, v6
	v_max_f32_e32 v109, 0, v7
	v_pk_mul_f32 v[50:51], v[244:245], v[108:109]
	v_max_f32_e32 v210, 0, v8
	v_max_f32_e32 v211, 0, v9
	v_pk_fma_f32 v[50:51], v[246:247], v[210:211], v[50:51]
	v_max_f32_e32 v108, 0, v10
	v_max_f32_e32 v109, 0, v11
	v_pk_fma_f32 v[50:51], v[248:249], v[108:109], v[50:51]
	s_waitcnt lgkmcnt(2)
	v_mfma_f32_32x32x16_bf16 v[212:227], v[74:77], v[42:45], v[212:227]
	v_max_f32_e32 v210, 0, v12
	v_max_f32_e32 v211, 0, v13
	v_pk_fma_f32 v[50:51], v[250:251], v[210:211], v[50:51]
	v_max_f32_e32 v108, 0, v14
	v_max_f32_e32 v109, 0, v15
	v_pk_fma_f32 v[50:51], v[252:253], v[108:109], v[50:51]
	v_max_f32_e32 v210, 0, v16
	v_max_f32_e32 v211, 0, v17
	v_pk_fma_f32 v[50:51], v[254:255], v[210:211], v[50:51]
	s_waitcnt lgkmcnt(1)
	v_mfma_f32_32x32x16_bf16 v[212:227], v[78:81], v[46:49], v[212:227]
	v_max_f32_e32 v108, 0, v18
	v_max_f32_e32 v109, 0, v19
	v_pk_fma_f32 v[50:51], v[200:201], v[108:109], v[50:51]
	v_max_f32_e32 v210, 0, v20
	v_max_f32_e32 v211, 0, v21
	v_pk_fma_f32 v[50:51], v[202:203], v[210:211], v[50:51]
	v_add_f32_e32 v50, v50, v51
	v_ashrrev_i32_e32 v51, 31, v50
	s_waitcnt lgkmcnt(0)
	v_mfma_f32_32x32x16_bf16 v[212:227], v[82:85], v[196:199], v[212:227]
	v_or_b32_e32 v51, 0x80000000, v51
	s_cmpk_gt_i32 s11, 336
	s_cselect_b64 vcc, -1, 0
	v_xor_b32_e32 v50, v51, v50
	v_cndmask_b32_e32 v50, v123, v50, vcc
	global_store_dword v243, v50, s[8:9]
	v_mfma_f32_32x32x16_bf16 v[6:21], v[86:89], v[38:41], 0
	s_add_i32 m0, s10, 65536
	s_nop 0
	global_load_lds_dwordx4 v102, s[6:7]
	s_add_i32 m0, s10, 66560
	s_nop 0
	global_load_lds_dwordx4 v110, s[6:7]
	s_add_i32 m0, s10, 67584
	s_nop 0
	global_load_lds_dwordx4 v112, s[6:7]
	s_add_i32 m0, s10, 68608
	s_nop 0
	global_load_lds_dwordx4 v193, s[6:7]
	s_add_u32 s6, s6, 0x8000
	s_addc_u32 s7, s7, 0
	v_max_f32_e32 v108, 0, v212
	v_max_f32_e32 v109, 0, v213
	v_pk_mul_f32 v[0:1], v[22:23], v[108:109]
	v_max_f32_e32 v210, 0, v214
	v_max_f32_e32 v211, 0, v215
	v_pk_fma_f32 v[0:1], v[24:25], v[210:211], v[0:1]
	v_max_f32_e32 v108, 0, v216
	v_max_f32_e32 v109, 0, v217
	v_pk_fma_f32 v[0:1], v[26:27], v[108:109], v[0:1]
	v_mfma_f32_32x32x16_bf16 v[6:21], v[90:93], v[42:45], v[6:21]
	v_max_f32_e32 v210, 0, v218
	v_max_f32_e32 v211, 0, v219
	v_pk_fma_f32 v[0:1], v[28:29], v[210:211], v[0:1]
	v_max_f32_e32 v108, 0, v220
	v_max_f32_e32 v109, 0, v221
	v_pk_fma_f32 v[0:1], v[30:31], v[108:109], v[0:1]
	v_max_f32_e32 v210, 0, v222
	v_max_f32_e32 v211, 0, v223
	v_pk_fma_f32 v[0:1], v[32:33], v[210:211], v[0:1]
	v_mfma_f32_32x32x16_bf16 v[6:21], v[94:97], v[46:49], v[6:21]
	v_max_f32_e32 v108, 0, v224
	v_max_f32_e32 v109, 0, v225
	v_pk_fma_f32 v[0:1], v[34:35], v[108:109], v[0:1]
	v_max_f32_e32 v210, 0, v226
	v_max_f32_e32 v211, 0, v227
	v_pk_fma_f32 v[0:1], v[36:37], v[210:211], v[0:1]
	v_add_f32_e32 v0, v0, v1
	v_ashrrev_i32_e32 v1, 31, v0
	v_mfma_f32_32x32x16_bf16 v[6:21], v[98:101], v[196:199], v[6:21]
	s_waitcnt vmcnt(10)
	ds_read_b128 v[38:41], v5 offset:10496
	ds_read_b128 v[42:45], v52 offset:10496
	ds_read_b128 v[46:49], v55 offset:10496
	ds_read_b128 v[196:199], v56 offset:10496
	v_or_b32_e32 v1, 0x80000000, v1
	s_cmpk_gt_i32 s11, 344
	s_cselect_b64 vcc, -1, 0
	v_xor_b32_e32 v0, v1, v0
	v_cndmask_b32_e32 v175, v123, v0, vcc
	s_nop 3
	s_waitcnt lgkmcnt(3)
	v_mfma_f32_32x32x16_bf16 v[212:227], v[70:73], v[38:41], 0
	v_max_f32_e32 v108, 0, v6
	v_max_f32_e32 v109, 0, v7
	v_pk_mul_f32 v[50:51], v[244:245], v[108:109]
	v_max_f32_e32 v210, 0, v8
	v_max_f32_e32 v211, 0, v9
	v_pk_fma_f32 v[50:51], v[246:247], v[210:211], v[50:51]
	v_max_f32_e32 v108, 0, v10
	v_max_f32_e32 v109, 0, v11
	v_pk_fma_f32 v[50:51], v[248:249], v[108:109], v[50:51]
	s_waitcnt lgkmcnt(2)
	v_mfma_f32_32x32x16_bf16 v[212:227], v[74:77], v[42:45], v[212:227]
	v_max_f32_e32 v210, 0, v12
	v_max_f32_e32 v211, 0, v13
	v_pk_fma_f32 v[50:51], v[250:251], v[210:211], v[50:51]
	v_max_f32_e32 v108, 0, v14
	v_max_f32_e32 v109, 0, v15
	v_pk_fma_f32 v[50:51], v[252:253], v[108:109], v[50:51]
	v_max_f32_e32 v210, 0, v16
	v_max_f32_e32 v211, 0, v17
	v_pk_fma_f32 v[50:51], v[254:255], v[210:211], v[50:51]
	s_waitcnt lgkmcnt(1)
	v_mfma_f32_32x32x16_bf16 v[212:227], v[78:81], v[46:49], v[212:227]
	v_max_f32_e32 v108, 0, v18
	v_max_f32_e32 v109, 0, v19
	v_pk_fma_f32 v[50:51], v[200:201], v[108:109], v[50:51]
	v_max_f32_e32 v210, 0, v20
	v_max_f32_e32 v211, 0, v21
	v_pk_fma_f32 v[50:51], v[202:203], v[210:211], v[50:51]
	v_add_f32_e32 v50, v50, v51
	v_ashrrev_i32_e32 v51, 31, v50
	s_waitcnt lgkmcnt(0)
	v_mfma_f32_32x32x16_bf16 v[212:227], v[82:85], v[196:199], v[212:227]
	v_or_b32_e32 v51, 0x80000000, v51
	s_cmpk_gt_i32 s11, 344
	s_cselect_b64 vcc, -1, 0
	v_xor_b32_e32 v50, v51, v50
	v_cndmask_b32_e32 v50, v123, v50, vcc
	global_store_dword v243, v50, s[8:9] offset:2048
	s_add_u32 s8, s8, 0x1000
	s_addc_u32 s9, s9, 0
	v_mfma_f32_32x32x16_bf16 v[6:21], v[86:89], v[38:41], 0
	s_add_i32 m0, s10, 98304
	s_nop 0
	global_load_lds_dwordx4 v102, s[6:7]
	s_add_i32 m0, s10, 99328
	s_nop 0
	global_load_lds_dwordx4 v110, s[6:7]
	s_add_i32 m0, s10, 100352
	s_nop 0
	global_load_lds_dwordx4 v112, s[6:7]
	s_add_i32 m0, s10, 101376
	s_nop 0
	global_load_lds_dwordx4 v193, s[6:7]
	s_add_u32 s6, s6, 0x8000
	s_addc_u32 s7, s7, 0
	v_max_f32_e32 v108, 0, v212
	v_max_f32_e32 v109, 0, v213
	v_pk_mul_f32 v[0:1], v[22:23], v[108:109]
	v_max_f32_e32 v210, 0, v214
	v_max_f32_e32 v211, 0, v215
	v_pk_fma_f32 v[0:1], v[24:25], v[210:211], v[0:1]
	v_max_f32_e32 v108, 0, v216
	v_max_f32_e32 v109, 0, v217
	v_pk_fma_f32 v[0:1], v[26:27], v[108:109], v[0:1]
	v_mfma_f32_32x32x16_bf16 v[6:21], v[90:93], v[42:45], v[6:21]
	v_max_f32_e32 v210, 0, v218
	v_max_f32_e32 v211, 0, v219
	v_pk_fma_f32 v[0:1], v[28:29], v[210:211], v[0:1]
	v_max_f32_e32 v108, 0, v220
	v_max_f32_e32 v109, 0, v221
	v_pk_fma_f32 v[0:1], v[30:31], v[108:109], v[0:1]
	v_max_f32_e32 v210, 0, v222
	v_max_f32_e32 v211, 0, v223
	v_pk_fma_f32 v[0:1], v[32:33], v[210:211], v[0:1]
	v_mfma_f32_32x32x16_bf16 v[6:21], v[94:97], v[46:49], v[6:21]
	v_max_f32_e32 v108, 0, v224
	v_max_f32_e32 v109, 0, v225
	v_pk_fma_f32 v[0:1], v[34:35], v[108:109], v[0:1]
	v_max_f32_e32 v210, 0, v226
	v_max_f32_e32 v211, 0, v227
	v_pk_fma_f32 v[0:1], v[36:37], v[210:211], v[0:1]
	v_add_f32_e32 v0, v0, v1
	v_ashrrev_i32_e32 v1, 31, v0
	v_mfma_f32_32x32x16_bf16 v[6:21], v[98:101], v[196:199], v[6:21]
	s_waitcnt vmcnt(10)
	ds_read_b128 v[38:41], v5 offset:43264
	ds_read_b128 v[42:45], v52 offset:43264
	ds_read_b128 v[46:49], v55 offset:43264
	ds_read_b128 v[196:199], v56 offset:43264
	v_or_b32_e32 v1, 0x80000000, v1
	s_cmpk_gt_i32 s11, 352
	s_cselect_b64 vcc, -1, 0
	v_xor_b32_e32 v0, v1, v0
	v_cndmask_b32_e32 v178, v123, v0, vcc
	s_nop 3
	s_waitcnt lgkmcnt(3)
	v_mfma_f32_32x32x16_bf16 v[212:227], v[70:73], v[38:41], 0
	v_max_f32_e32 v108, 0, v6
	v_max_f32_e32 v109, 0, v7
	v_pk_mul_f32 v[50:51], v[244:245], v[108:109]
	v_max_f32_e32 v210, 0, v8
	v_max_f32_e32 v211, 0, v9
	v_pk_fma_f32 v[50:51], v[246:247], v[210:211], v[50:51]
	v_max_f32_e32 v108, 0, v10
	v_max_f32_e32 v109, 0, v11
	v_pk_fma_f32 v[50:51], v[248:249], v[108:109], v[50:51]
	s_waitcnt lgkmcnt(2)
	v_mfma_f32_32x32x16_bf16 v[212:227], v[74:77], v[42:45], v[212:227]
	v_max_f32_e32 v210, 0, v12
	v_max_f32_e32 v211, 0, v13
	v_pk_fma_f32 v[50:51], v[250:251], v[210:211], v[50:51]
	v_max_f32_e32 v108, 0, v14
	v_max_f32_e32 v109, 0, v15
	v_pk_fma_f32 v[50:51], v[252:253], v[108:109], v[50:51]
	v_max_f32_e32 v210, 0, v16
	v_max_f32_e32 v211, 0, v17
	v_pk_fma_f32 v[50:51], v[254:255], v[210:211], v[50:51]
	s_waitcnt lgkmcnt(1)
	v_mfma_f32_32x32x16_bf16 v[212:227], v[78:81], v[46:49], v[212:227]
	v_max_f32_e32 v108, 0, v18
	v_max_f32_e32 v109, 0, v19
	v_pk_fma_f32 v[50:51], v[200:201], v[108:109], v[50:51]
	v_max_f32_e32 v210, 0, v20
	v_max_f32_e32 v211, 0, v21
	v_pk_fma_f32 v[50:51], v[202:203], v[210:211], v[50:51]
	v_add_f32_e32 v50, v50, v51
	v_ashrrev_i32_e32 v51, 31, v50
	s_waitcnt lgkmcnt(0)
	v_mfma_f32_32x32x16_bf16 v[212:227], v[82:85], v[196:199], v[212:227]
	v_or_b32_e32 v51, 0x80000000, v51
	s_cmpk_gt_i32 s11, 352
	s_cselect_b64 vcc, -1, 0
	v_xor_b32_e32 v50, v51, v50
	v_cndmask_b32_e32 v50, v123, v50, vcc
	global_store_dword v243, v50, s[8:9]
	v_mfma_f32_32x32x16_bf16 v[6:21], v[86:89], v[38:41], 0
	s_add_i32 m0, s10, 0
	s_nop 0
	global_load_lds_dwordx4 v102, s[6:7]
	s_add_i32 m0, s10, 1024
	s_nop 0
	global_load_lds_dwordx4 v110, s[6:7]
	s_add_i32 m0, s10, 2048
	s_nop 0
	global_load_lds_dwordx4 v112, s[6:7]
	s_add_i32 m0, s10, 3072
	s_nop 0
	global_load_lds_dwordx4 v193, s[6:7]
	s_add_u32 s6, s6, 0x8000
	s_addc_u32 s7, s7, 0
	v_max_f32_e32 v108, 0, v212
	v_max_f32_e32 v109, 0, v213
	v_pk_mul_f32 v[0:1], v[22:23], v[108:109]
	v_max_f32_e32 v210, 0, v214
	v_max_f32_e32 v211, 0, v215
	v_pk_fma_f32 v[0:1], v[24:25], v[210:211], v[0:1]
	v_max_f32_e32 v108, 0, v216
	v_max_f32_e32 v109, 0, v217
	v_pk_fma_f32 v[0:1], v[26:27], v[108:109], v[0:1]
	v_mfma_f32_32x32x16_bf16 v[6:21], v[90:93], v[42:45], v[6:21]
	v_max_f32_e32 v210, 0, v218
	v_max_f32_e32 v211, 0, v219
	v_pk_fma_f32 v[0:1], v[28:29], v[210:211], v[0:1]
	v_max_f32_e32 v108, 0, v220
	v_max_f32_e32 v109, 0, v221
	v_pk_fma_f32 v[0:1], v[30:31], v[108:109], v[0:1]
	v_max_f32_e32 v210, 0, v222
	v_max_f32_e32 v211, 0, v223
	v_pk_fma_f32 v[0:1], v[32:33], v[210:211], v[0:1]
	v_mfma_f32_32x32x16_bf16 v[6:21], v[94:97], v[46:49], v[6:21]
	v_max_f32_e32 v108, 0, v224
	v_max_f32_e32 v109, 0, v225
	v_pk_fma_f32 v[0:1], v[34:35], v[108:109], v[0:1]
	v_max_f32_e32 v210, 0, v226
	v_max_f32_e32 v211, 0, v227
	v_pk_fma_f32 v[0:1], v[36:37], v[210:211], v[0:1]
	v_add_f32_e32 v0, v0, v1
	v_ashrrev_i32_e32 v1, 31, v0
	v_mfma_f32_32x32x16_bf16 v[6:21], v[98:101], v[196:199], v[6:21]
	s_waitcnt vmcnt(10)
	v_add_u32_e32 v228, 0x10000, v5
	ds_read_b128 v[38:41], v228 offset:10496
	v_add_u32_e32 v228, 0x10000, v52
	ds_read_b128 v[42:45], v228 offset:10496
	v_add_u32_e32 v228, 0x10000, v55
	ds_read_b128 v[46:49], v228 offset:10496
	v_add_u32_e32 v228, 0x10000, v56
	ds_read_b128 v[196:199], v228 offset:10496
	v_or_b32_e32 v1, 0x80000000, v1
	s_cmpk_gt_i32 s11, 360
	s_cselect_b64 vcc, -1, 0
	v_xor_b32_e32 v0, v1, v0
	v_cndmask_b32_e32 v177, v123, v0, vcc
	s_nop 3
	s_waitcnt lgkmcnt(3)
	v_mfma_f32_32x32x16_bf16 v[212:227], v[70:73], v[38:41], 0
	v_max_f32_e32 v108, 0, v6
	v_max_f32_e32 v109, 0, v7
	v_pk_mul_f32 v[50:51], v[244:245], v[108:109]
	v_max_f32_e32 v210, 0, v8
	v_max_f32_e32 v211, 0, v9
	v_pk_fma_f32 v[50:51], v[246:247], v[210:211], v[50:51]
	v_max_f32_e32 v108, 0, v10
	v_max_f32_e32 v109, 0, v11
	v_pk_fma_f32 v[50:51], v[248:249], v[108:109], v[50:51]
	s_waitcnt lgkmcnt(2)
	v_mfma_f32_32x32x16_bf16 v[212:227], v[74:77], v[42:45], v[212:227]
	v_max_f32_e32 v210, 0, v12
	v_max_f32_e32 v211, 0, v13
	v_pk_fma_f32 v[50:51], v[250:251], v[210:211], v[50:51]
	v_max_f32_e32 v108, 0, v14
	v_max_f32_e32 v109, 0, v15
	v_pk_fma_f32 v[50:51], v[252:253], v[108:109], v[50:51]
	v_max_f32_e32 v210, 0, v16
	v_max_f32_e32 v211, 0, v17
	v_pk_fma_f32 v[50:51], v[254:255], v[210:211], v[50:51]
	s_waitcnt lgkmcnt(1)
	v_mfma_f32_32x32x16_bf16 v[212:227], v[78:81], v[46:49], v[212:227]
	v_max_f32_e32 v108, 0, v18
	v_max_f32_e32 v109, 0, v19
	v_pk_fma_f32 v[50:51], v[200:201], v[108:109], v[50:51]
	v_max_f32_e32 v210, 0, v20
	v_max_f32_e32 v211, 0, v21
	v_pk_fma_f32 v[50:51], v[202:203], v[210:211], v[50:51]
	v_add_f32_e32 v50, v50, v51
	v_ashrrev_i32_e32 v51, 31, v50
	s_waitcnt lgkmcnt(0)
	v_mfma_f32_32x32x16_bf16 v[212:227], v[82:85], v[196:199], v[212:227]
	v_or_b32_e32 v51, 0x80000000, v51
	s_cmpk_gt_i32 s11, 360
	s_cselect_b64 vcc, -1, 0
	v_xor_b32_e32 v50, v51, v50
	v_cndmask_b32_e32 v50, v123, v50, vcc
	global_store_dword v243, v50, s[8:9] offset:2048
	s_add_u32 s8, s8, 0x1000
	s_addc_u32 s9, s9, 0
	v_mfma_f32_32x32x16_bf16 v[6:21], v[86:89], v[38:41], 0
	s_add_i32 m0, s10, 32768
	s_nop 0
	global_load_lds_dwordx4 v102, s[6:7]
	s_add_i32 m0, s10, 33792
	s_nop 0
	global_load_lds_dwordx4 v110, s[6:7]
	s_add_i32 m0, s10, 34816
	s_nop 0
	global_load_lds_dwordx4 v112, s[6:7]
	s_add_i32 m0, s10, 35840
	s_nop 0
	global_load_lds_dwordx4 v193, s[6:7]
	s_add_u32 s6, s6, 0x8000
	s_addc_u32 s7, s7, 0
	v_max_f32_e32 v108, 0, v212
	v_max_f32_e32 v109, 0, v213
	v_pk_mul_f32 v[0:1], v[22:23], v[108:109]
	v_max_f32_e32 v210, 0, v214
	v_max_f32_e32 v211, 0, v215
	v_pk_fma_f32 v[0:1], v[24:25], v[210:211], v[0:1]
	v_max_f32_e32 v108, 0, v216
	v_max_f32_e32 v109, 0, v217
	v_pk_fma_f32 v[0:1], v[26:27], v[108:109], v[0:1]
	v_mfma_f32_32x32x16_bf16 v[6:21], v[90:93], v[42:45], v[6:21]
	v_max_f32_e32 v210, 0, v218
	v_max_f32_e32 v211, 0, v219
	v_pk_fma_f32 v[0:1], v[28:29], v[210:211], v[0:1]
	v_max_f32_e32 v108, 0, v220
	v_max_f32_e32 v109, 0, v221
	v_pk_fma_f32 v[0:1], v[30:31], v[108:109], v[0:1]
	v_max_f32_e32 v210, 0, v222
	v_max_f32_e32 v211, 0, v223
	v_pk_fma_f32 v[0:1], v[32:33], v[210:211], v[0:1]
	v_mfma_f32_32x32x16_bf16 v[6:21], v[94:97], v[46:49], v[6:21]
	v_max_f32_e32 v108, 0, v224
	v_max_f32_e32 v109, 0, v225
	v_pk_fma_f32 v[0:1], v[34:35], v[108:109], v[0:1]
	v_max_f32_e32 v210, 0, v226
	v_max_f32_e32 v211, 0, v227
	v_pk_fma_f32 v[0:1], v[36:37], v[210:211], v[0:1]
	v_add_f32_e32 v0, v0, v1
	v_ashrrev_i32_e32 v1, 31, v0
	v_mfma_f32_32x32x16_bf16 v[6:21], v[98:101], v[196:199], v[6:21]
	s_waitcnt vmcnt(10)
	v_add_u32_e32 v228, 0x10000, v5
	ds_read_b128 v[38:41], v228 offset:43264
	v_add_u32_e32 v228, 0x10000, v52
	ds_read_b128 v[42:45], v228 offset:43264
	v_add_u32_e32 v228, 0x10000, v55
	ds_read_b128 v[46:49], v228 offset:43264
	v_add_u32_e32 v228, 0x10000, v56
	ds_read_b128 v[196:199], v228 offset:43264
	v_or_b32_e32 v1, 0x80000000, v1
	s_cmpk_gt_i32 s11, 368
	s_cselect_b64 vcc, -1, 0
	v_xor_b32_e32 v0, v1, v0
	v_cndmask_b32_e32 v179, v123, v0, vcc
	s_nop 3
	s_waitcnt lgkmcnt(3)
	v_mfma_f32_32x32x16_bf16 v[212:227], v[70:73], v[38:41], 0
	v_max_f32_e32 v108, 0, v6
	v_max_f32_e32 v109, 0, v7
	v_pk_mul_f32 v[50:51], v[244:245], v[108:109]
	v_max_f32_e32 v210, 0, v8
	v_max_f32_e32 v211, 0, v9
	v_pk_fma_f32 v[50:51], v[246:247], v[210:211], v[50:51]
	v_max_f32_e32 v108, 0, v10
	v_max_f32_e32 v109, 0, v11
	v_pk_fma_f32 v[50:51], v[248:249], v[108:109], v[50:51]
	s_waitcnt lgkmcnt(2)
	v_mfma_f32_32x32x16_bf16 v[212:227], v[74:77], v[42:45], v[212:227]
	v_max_f32_e32 v210, 0, v12
	v_max_f32_e32 v211, 0, v13
	v_pk_fma_f32 v[50:51], v[250:251], v[210:211], v[50:51]
	v_max_f32_e32 v108, 0, v14
	v_max_f32_e32 v109, 0, v15
	v_pk_fma_f32 v[50:51], v[252:253], v[108:109], v[50:51]
	v_max_f32_e32 v210, 0, v16
	v_max_f32_e32 v211, 0, v17
	v_pk_fma_f32 v[50:51], v[254:255], v[210:211], v[50:51]
	s_waitcnt lgkmcnt(1)
	v_mfma_f32_32x32x16_bf16 v[212:227], v[78:81], v[46:49], v[212:227]
	v_max_f32_e32 v108, 0, v18
	v_max_f32_e32 v109, 0, v19
	v_pk_fma_f32 v[50:51], v[200:201], v[108:109], v[50:51]
	v_max_f32_e32 v210, 0, v20
	v_max_f32_e32 v211, 0, v21
	v_pk_fma_f32 v[50:51], v[202:203], v[210:211], v[50:51]
	v_add_f32_e32 v50, v50, v51
	v_ashrrev_i32_e32 v51, 31, v50
	s_waitcnt lgkmcnt(0)
	v_mfma_f32_32x32x16_bf16 v[212:227], v[82:85], v[196:199], v[212:227]
	v_or_b32_e32 v51, 0x80000000, v51
	s_cmpk_gt_i32 s11, 368
	s_cselect_b64 vcc, -1, 0
	v_xor_b32_e32 v50, v51, v50
	v_cndmask_b32_e32 v50, v123, v50, vcc
	global_store_dword v243, v50, s[8:9]
	v_mfma_f32_32x32x16_bf16 v[6:21], v[86:89], v[38:41], 0
	s_add_i32 m0, s10, 65536
	s_nop 0
	global_load_lds_dwordx4 v102, s[6:7]
	s_add_i32 m0, s10, 66560
	s_nop 0
	global_load_lds_dwordx4 v110, s[6:7]
	s_add_i32 m0, s10, 67584
	s_nop 0
	global_load_lds_dwordx4 v112, s[6:7]
	s_add_i32 m0, s10, 68608
	s_nop 0
	global_load_lds_dwordx4 v193, s[6:7]
	s_add_u32 s6, s6, 0x8000
	s_addc_u32 s7, s7, 0
	v_max_f32_e32 v108, 0, v212
	v_max_f32_e32 v109, 0, v213
	v_pk_mul_f32 v[0:1], v[22:23], v[108:109]
	v_max_f32_e32 v210, 0, v214
	v_max_f32_e32 v211, 0, v215
	v_pk_fma_f32 v[0:1], v[24:25], v[210:211], v[0:1]
	v_max_f32_e32 v108, 0, v216
	v_max_f32_e32 v109, 0, v217
	v_pk_fma_f32 v[0:1], v[26:27], v[108:109], v[0:1]
	v_mfma_f32_32x32x16_bf16 v[6:21], v[90:93], v[42:45], v[6:21]
	v_max_f32_e32 v210, 0, v218
	v_max_f32_e32 v211, 0, v219
	v_pk_fma_f32 v[0:1], v[28:29], v[210:211], v[0:1]
	v_max_f32_e32 v108, 0, v220
	v_max_f32_e32 v109, 0, v221
	v_pk_fma_f32 v[0:1], v[30:31], v[108:109], v[0:1]
	v_max_f32_e32 v210, 0, v222
	v_max_f32_e32 v211, 0, v223
	v_pk_fma_f32 v[0:1], v[32:33], v[210:211], v[0:1]
	v_mfma_f32_32x32x16_bf16 v[6:21], v[94:97], v[46:49], v[6:21]
	v_max_f32_e32 v108, 0, v224
	v_max_f32_e32 v109, 0, v225
	v_pk_fma_f32 v[0:1], v[34:35], v[108:109], v[0:1]
	v_max_f32_e32 v210, 0, v226
	v_max_f32_e32 v211, 0, v227
	v_pk_fma_f32 v[0:1], v[36:37], v[210:211], v[0:1]
	v_add_f32_e32 v0, v0, v1
	v_ashrrev_i32_e32 v1, 31, v0
	v_mfma_f32_32x32x16_bf16 v[6:21], v[98:101], v[196:199], v[6:21]
	s_waitcnt vmcnt(10)
	ds_read_b128 v[38:41], v5 offset:10496
	ds_read_b128 v[42:45], v52 offset:10496
	ds_read_b128 v[46:49], v55 offset:10496
	ds_read_b128 v[196:199], v56 offset:10496
	v_or_b32_e32 v1, 0x80000000, v1
	s_cmpk_gt_i32 s11, 376
	s_cselect_b64 vcc, -1, 0
	v_xor_b32_e32 v0, v1, v0
	v_cndmask_b32_e32 v168, v123, v0, vcc
	s_nop 3
	v_max_f32_e32 v108, 0, v6
	v_max_f32_e32 v109, 0, v7
	v_pk_mul_f32 v[50:51], v[244:245], v[108:109]
	v_max_f32_e32 v210, 0, v8
	v_max_f32_e32 v211, 0, v9
	v_pk_fma_f32 v[50:51], v[246:247], v[210:211], v[50:51]
	v_max_f32_e32 v108, 0, v10
	v_max_f32_e32 v109, 0, v11
	v_pk_fma_f32 v[50:51], v[248:249], v[108:109], v[50:51]
	v_max_f32_e32 v210, 0, v12
	v_max_f32_e32 v211, 0, v13
	v_pk_fma_f32 v[50:51], v[250:251], v[210:211], v[50:51]
	v_max_f32_e32 v108, 0, v14
	v_max_f32_e32 v109, 0, v15
	v_pk_fma_f32 v[50:51], v[252:253], v[108:109], v[50:51]
	v_max_f32_e32 v210, 0, v16
	v_max_f32_e32 v211, 0, v17
	v_pk_fma_f32 v[50:51], v[254:255], v[210:211], v[50:51]
	v_max_f32_e32 v108, 0, v18
	v_max_f32_e32 v109, 0, v19
	v_pk_fma_f32 v[50:51], v[200:201], v[108:109], v[50:51]
	v_max_f32_e32 v210, 0, v20
	v_max_f32_e32 v211, 0, v21
	v_pk_fma_f32 v[50:51], v[202:203], v[210:211], v[50:51]
	v_add_f32_e32 v50, v50, v51
	v_ashrrev_i32_e32 v51, 31, v50
	v_or_b32_e32 v51, 0x80000000, v51
	s_cmpk_gt_i32 s11, 376
	s_cselect_b64 vcc, -1, 0
	v_xor_b32_e32 v50, v51, v50
	v_cndmask_b32_e32 v50, v123, v50, vcc
	global_store_dword v243, v50, s[8:9] offset:2048
	s_add_u32 s8, s8, 0x1000
	s_addc_u32 s9, s9, 0
	s_cmpk_gt_i32 s81, 48
	s_cbranch_scc0 .Lix_fill_6
	s_waitcnt lgkmcnt(3)
	v_mfma_f32_32x32x16_bf16 v[212:227], v[70:73], v[38:41], 0
	s_add_i32 m0, s10, 98304
	s_nop 0
	global_load_lds_dwordx4 v102, s[6:7]
	s_waitcnt lgkmcnt(2)
	v_mfma_f32_32x32x16_bf16 v[212:227], v[74:77], v[42:45], v[212:227]
	s_add_i32 m0, s10, 99328
	s_nop 0
	global_load_lds_dwordx4 v110, s[6:7]
	s_waitcnt lgkmcnt(1)
	v_mfma_f32_32x32x16_bf16 v[212:227], v[78:81], v[46:49], v[212:227]
	s_add_i32 m0, s10, 100352
	s_nop 0
	global_load_lds_dwordx4 v112, s[6:7]
	s_waitcnt lgkmcnt(0)
	v_mfma_f32_32x32x16_bf16 v[212:227], v[82:85], v[196:199], v[212:227]
	s_add_i32 m0, s10, 101376
	s_nop 0
	global_load_lds_dwordx4 v193, s[6:7]
	s_add_u32 s6, s6, 0x8000
	s_addc_u32 s7, s7, 0
	v_mfma_f32_32x32x16_bf16 v[6:21], v[86:89], v[38:41], 0
	s_nop 7
	s_nop 2
	v_max_f32_e32 v108, 0, v212
	v_max_f32_e32 v109, 0, v213
	v_pk_mul_f32 v[0:1], v[22:23], v[108:109]
	v_max_f32_e32 v210, 0, v214
	v_max_f32_e32 v211, 0, v215
	v_pk_fma_f32 v[0:1], v[24:25], v[210:211], v[0:1]
	v_max_f32_e32 v108, 0, v216
	v_max_f32_e32 v109, 0, v217
	v_pk_fma_f32 v[0:1], v[26:27], v[108:109], v[0:1]
	v_mfma_f32_32x32x16_bf16 v[6:21], v[90:93], v[42:45], v[6:21]
	v_max_f32_e32 v210, 0, v218
	v_max_f32_e32 v211, 0, v219
	v_pk_fma_f32 v[0:1], v[28:29], v[210:211], v[0:1]
	v_max_f32_e32 v108, 0, v220
	v_max_f32_e32 v109, 0, v221
	v_pk_fma_f32 v[0:1], v[30:31], v[108:109], v[0:1]
	v_max_f32_e32 v210, 0, v222
	v_max_f32_e32 v211, 0, v223
	v_pk_fma_f32 v[0:1], v[32:33], v[210:211], v[0:1]
	v_mfma_f32_32x32x16_bf16 v[6:21], v[94:97], v[46:49], v[6:21]
	v_max_f32_e32 v108, 0, v224
	v_max_f32_e32 v109, 0, v225
	v_pk_fma_f32 v[0:1], v[34:35], v[108:109], v[0:1]
	v_max_f32_e32 v210, 0, v226
	v_max_f32_e32 v211, 0, v227
	v_pk_fma_f32 v[0:1], v[36:37], v[210:211], v[0:1]
	v_add_f32_e32 v0, v0, v1
	v_ashrrev_i32_e32 v1, 31, v0
	v_mfma_f32_32x32x16_bf16 v[6:21], v[98:101], v[196:199], v[6:21]
	s_waitcnt vmcnt(10)
	ds_read_b128 v[38:41], v5 offset:43264
	ds_read_b128 v[42:45], v52 offset:43264
	ds_read_b128 v[46:49], v55 offset:43264
	ds_read_b128 v[196:199], v56 offset:43264
	v_or_b32_e32 v1, 0x80000000, v1
	s_cmpk_gt_i32 s11, 384
	s_cselect_b64 vcc, -1, 0
	v_xor_b32_e32 v0, v1, v0
	v_cndmask_b32_e32 v182, v123, v0, vcc
	s_nop 3
	s_waitcnt lgkmcnt(3)
	v_mfma_f32_32x32x16_bf16 v[212:227], v[70:73], v[38:41], 0
	v_max_f32_e32 v108, 0, v6
	v_max_f32_e32 v109, 0, v7
	v_pk_mul_f32 v[50:51], v[244:245], v[108:109]
	v_max_f32_e32 v210, 0, v8
	v_max_f32_e32 v211, 0, v9
	v_pk_fma_f32 v[50:51], v[246:247], v[210:211], v[50:51]
	v_max_f32_e32 v108, 0, v10
	v_max_f32_e32 v109, 0, v11
	v_pk_fma_f32 v[50:51], v[248:249], v[108:109], v[50:51]
	s_waitcnt lgkmcnt(2)
	v_mfma_f32_32x32x16_bf16 v[212:227], v[74:77], v[42:45], v[212:227]
	v_max_f32_e32 v210, 0, v12
	v_max_f32_e32 v211, 0, v13
	v_pk_fma_f32 v[50:51], v[250:251], v[210:211], v[50:51]
	v_max_f32_e32 v108, 0, v14
	v_max_f32_e32 v109, 0, v15
	v_pk_fma_f32 v[50:51], v[252:253], v[108:109], v[50:51]
	v_max_f32_e32 v210, 0, v16
	v_max_f32_e32 v211, 0, v17
	v_pk_fma_f32 v[50:51], v[254:255], v[210:211], v[50:51]
	s_waitcnt lgkmcnt(1)
	v_mfma_f32_32x32x16_bf16 v[212:227], v[78:81], v[46:49], v[212:227]
	v_max_f32_e32 v108, 0, v18
	v_max_f32_e32 v109, 0, v19
	v_pk_fma_f32 v[50:51], v[200:201], v[108:109], v[50:51]
	v_max_f32_e32 v210, 0, v20
	v_max_f32_e32 v211, 0, v21
	v_pk_fma_f32 v[50:51], v[202:203], v[210:211], v[50:51]
	v_add_f32_e32 v50, v50, v51
	v_ashrrev_i32_e32 v51, 31, v50
	s_waitcnt lgkmcnt(0)
	v_mfma_f32_32x32x16_bf16 v[212:227], v[82:85], v[196:199], v[212:227]
	v_or_b32_e32 v51, 0x80000000, v51
	s_cmpk_gt_i32 s11, 384
	s_cselect_b64 vcc, -1, 0
	v_xor_b32_e32 v50, v51, v50
	v_cndmask_b32_e32 v50, v123, v50, vcc
	global_store_dword v243, v50, s[8:9]
	v_mfma_f32_32x32x16_bf16 v[6:21], v[86:89], v[38:41], 0
	s_add_i32 m0, s10, 0
	s_nop 0
	global_load_lds_dwordx4 v102, s[6:7]
	s_add_i32 m0, s10, 1024
	s_nop 0
	global_load_lds_dwordx4 v110, s[6:7]
	s_add_i32 m0, s10, 2048
	s_nop 0
	global_load_lds_dwordx4 v112, s[6:7]
	s_add_i32 m0, s10, 3072
	s_nop 0
	global_load_lds_dwordx4 v193, s[6:7]
	s_add_u32 s6, s6, 0x8000
	s_addc_u32 s7, s7, 0
	v_max_f32_e32 v108, 0, v212
	v_max_f32_e32 v109, 0, v213
	v_pk_mul_f32 v[0:1], v[22:23], v[108:109]
	v_max_f32_e32 v210, 0, v214
	v_max_f32_e32 v211, 0, v215
	v_pk_fma_f32 v[0:1], v[24:25], v[210:211], v[0:1]
	v_max_f32_e32 v108, 0, v216
	v_max_f32_e32 v109, 0, v217
	v_pk_fma_f32 v[0:1], v[26:27], v[108:109], v[0:1]
	v_mfma_f32_32x32x16_bf16 v[6:21], v[90:93], v[42:45], v[6:21]
	v_max_f32_e32 v210, 0, v218
	v_max_f32_e32 v211, 0, v219
	v_pk_fma_f32 v[0:1], v[28:29], v[210:211], v[0:1]
	v_max_f32_e32 v108, 0, v220
	v_max_f32_e32 v109, 0, v221
	v_pk_fma_f32 v[0:1], v[30:31], v[108:109], v[0:1]
	v_max_f32_e32 v210, 0, v222
	v_max_f32_e32 v211, 0, v223
	v_pk_fma_f32 v[0:1], v[32:33], v[210:211], v[0:1]
	v_mfma_f32_32x32x16_bf16 v[6:21], v[94:97], v[46:49], v[6:21]
	v_max_f32_e32 v108, 0, v224
	v_max_f32_e32 v109, 0, v225
	v_pk_fma_f32 v[0:1], v[34:35], v[108:109], v[0:1]
	v_max_f32_e32 v210, 0, v226
	v_max_f32_e32 v211, 0, v227
	v_pk_fma_f32 v[0:1], v[36:37], v[210:211], v[0:1]
	v_add_f32_e32 v0, v0, v1
	v_ashrrev_i32_e32 v1, 31, v0
	v_mfma_f32_32x32x16_bf16 v[6:21], v[98:101], v[196:199], v[6:21]
	s_waitcnt vmcnt(10)
	v_add_u32_e32 v228, 0x10000, v5
	ds_read_b128 v[38:41], v228 offset:10496
	v_add_u32_e32 v228, 0x10000, v52
	ds_read_b128 v[42:45], v228 offset:10496
	v_add_u32_e32 v228, 0x10000, v55
	ds_read_b128 v[46:49], v228 offset:10496
	v_add_u32_e32 v228, 0x10000, v56
	ds_read_b128 v[196:199], v228 offset:10496
	v_or_b32_e32 v1, 0x80000000, v1
	s_cmpk_gt_i32 s11, 392
	s_cselect_b64 vcc, -1, 0
	v_xor_b32_e32 v0, v1, v0
	v_cndmask_b32_e32 v181, v123, v0, vcc
	s_nop 3
	s_waitcnt lgkmcnt(3)
	v_mfma_f32_32x32x16_bf16 v[212:227], v[70:73], v[38:41], 0
	v_max_f32_e32 v108, 0, v6
	v_max_f32_e32 v109, 0, v7
	v_pk_mul_f32 v[50:51], v[244:245], v[108:109]
	v_max_f32_e32 v210, 0, v8
	v_max_f32_e32 v211, 0, v9
	v_pk_fma_f32 v[50:51], v[246:247], v[210:211], v[50:51]
	v_max_f32_e32 v108, 0, v10
	v_max_f32_e32 v109, 0, v11
	v_pk_fma_f32 v[50:51], v[248:249], v[108:109], v[50:51]
	s_waitcnt lgkmcnt(2)
	v_mfma_f32_32x32x16_bf16 v[212:227], v[74:77], v[42:45], v[212:227]
	v_max_f32_e32 v210, 0, v12
	v_max_f32_e32 v211, 0, v13
	v_pk_fma_f32 v[50:51], v[250:251], v[210:211], v[50:51]
	v_max_f32_e32 v108, 0, v14
	v_max_f32_e32 v109, 0, v15
	v_pk_fma_f32 v[50:51], v[252:253], v[108:109], v[50:51]
	v_max_f32_e32 v210, 0, v16
	v_max_f32_e32 v211, 0, v17
	v_pk_fma_f32 v[50:51], v[254:255], v[210:211], v[50:51]
	s_waitcnt lgkmcnt(1)
	v_mfma_f32_32x32x16_bf16 v[212:227], v[78:81], v[46:49], v[212:227]
	v_max_f32_e32 v108, 0, v18
	v_max_f32_e32 v109, 0, v19
	v_pk_fma_f32 v[50:51], v[200:201], v[108:109], v[50:51]
	v_max_f32_e32 v210, 0, v20
	v_max_f32_e32 v211, 0, v21
	v_pk_fma_f32 v[50:51], v[202:203], v[210:211], v[50:51]
	v_add_f32_e32 v50, v50, v51
	v_ashrrev_i32_e32 v51, 31, v50
	s_waitcnt lgkmcnt(0)
	v_mfma_f32_32x32x16_bf16 v[212:227], v[82:85], v[196:199], v[212:227]
	v_or_b32_e32 v51, 0x80000000, v51
	s_cmpk_gt_i32 s11, 392
	s_cselect_b64 vcc, -1, 0
	v_xor_b32_e32 v50, v51, v50
	v_cndmask_b32_e32 v50, v123, v50, vcc
	global_store_dword v243, v50, s[8:9] offset:2048
	s_add_u32 s8, s8, 0x1000
	s_addc_u32 s9, s9, 0
	v_mfma_f32_32x32x16_bf16 v[6:21], v[86:89], v[38:41], 0
	s_add_i32 m0, s10, 32768
	s_nop 0
	global_load_lds_dwordx4 v102, s[6:7]
	s_add_i32 m0, s10, 33792
	s_nop 0
	global_load_lds_dwordx4 v110, s[6:7]
	s_add_i32 m0, s10, 34816
	s_nop 0
	global_load_lds_dwordx4 v112, s[6:7]
	s_add_i32 m0, s10, 35840
	s_nop 0
	global_load_lds_dwordx4 v193, s[6:7]
	s_add_u32 s6, s6, 0x8000
	s_addc_u32 s7, s7, 0
	v_max_f32_e32 v108, 0, v212
	v_max_f32_e32 v109, 0, v213
	v_pk_mul_f32 v[0:1], v[22:23], v[108:109]
	v_max_f32_e32 v210, 0, v214
	v_max_f32_e32 v211, 0, v215
	v_pk_fma_f32 v[0:1], v[24:25], v[210:211], v[0:1]
	v_max_f32_e32 v108, 0, v216
	v_max_f32_e32 v109, 0, v217
	v_pk_fma_f32 v[0:1], v[26:27], v[108:109], v[0:1]
	v_mfma_f32_32x32x16_bf16 v[6:21], v[90:93], v[42:45], v[6:21]
	v_max_f32_e32 v210, 0, v218
	v_max_f32_e32 v211, 0, v219
	v_pk_fma_f32 v[0:1], v[28:29], v[210:211], v[0:1]
	v_max_f32_e32 v108, 0, v220
	v_max_f32_e32 v109, 0, v221
	v_pk_fma_f32 v[0:1], v[30:31], v[108:109], v[0:1]
	v_max_f32_e32 v210, 0, v222
	v_max_f32_e32 v211, 0, v223
	v_pk_fma_f32 v[0:1], v[32:33], v[210:211], v[0:1]
	v_mfma_f32_32x32x16_bf16 v[6:21], v[94:97], v[46:49], v[6:21]
	v_max_f32_e32 v108, 0, v224
	v_max_f32_e32 v109, 0, v225
	v_pk_fma_f32 v[0:1], v[34:35], v[108:109], v[0:1]
	v_max_f32_e32 v210, 0, v226
	v_max_f32_e32 v211, 0, v227
	v_pk_fma_f32 v[0:1], v[36:37], v[210:211], v[0:1]
	v_add_f32_e32 v0, v0, v1
	v_ashrrev_i32_e32 v1, 31, v0
	v_mfma_f32_32x32x16_bf16 v[6:21], v[98:101], v[196:199], v[6:21]
	s_waitcnt vmcnt(10)
	v_add_u32_e32 v228, 0x10000, v5
	ds_read_b128 v[38:41], v228 offset:43264
	v_add_u32_e32 v228, 0x10000, v52
	ds_read_b128 v[42:45], v228 offset:43264
	v_add_u32_e32 v228, 0x10000, v55
	ds_read_b128 v[46:49], v228 offset:43264
	v_add_u32_e32 v228, 0x10000, v56
	ds_read_b128 v[196:199], v228 offset:43264
	v_or_b32_e32 v1, 0x80000000, v1
	s_cmpk_gt_i32 s11, 400
	s_cselect_b64 vcc, -1, 0
	v_xor_b32_e32 v0, v1, v0
	v_cndmask_b32_e32 v184, v123, v0, vcc
	s_nop 3
	s_waitcnt lgkmcnt(3)
	v_mfma_f32_32x32x16_bf16 v[212:227], v[70:73], v[38:41], 0
	v_max_f32_e32 v108, 0, v6
	v_max_f32_e32 v109, 0, v7
	v_pk_mul_f32 v[50:51], v[244:245], v[108:109]
	v_max_f32_e32 v210, 0, v8
	v_max_f32_e32 v211, 0, v9
	v_pk_fma_f32 v[50:51], v[246:247], v[210:211], v[50:51]
	v_max_f32_e32 v108, 0, v10
	v_max_f32_e32 v109, 0, v11
	v_pk_fma_f32 v[50:51], v[248:249], v[108:109], v[50:51]
	s_waitcnt lgkmcnt(2)
	v_mfma_f32_32x32x16_bf16 v[212:227], v[74:77], v[42:45], v[212:227]
	v_max_f32_e32 v210, 0, v12
	v_max_f32_e32 v211, 0, v13
	v_pk_fma_f32 v[50:51], v[250:251], v[210:211], v[50:51]
	v_max_f32_e32 v108, 0, v14
	v_max_f32_e32 v109, 0, v15
	v_pk_fma_f32 v[50:51], v[252:253], v[108:109], v[50:51]
	v_max_f32_e32 v210, 0, v16
	v_max_f32_e32 v211, 0, v17
	v_pk_fma_f32 v[50:51], v[254:255], v[210:211], v[50:51]
	s_waitcnt lgkmcnt(1)
	v_mfma_f32_32x32x16_bf16 v[212:227], v[78:81], v[46:49], v[212:227]
	v_max_f32_e32 v108, 0, v18
	v_max_f32_e32 v109, 0, v19
	v_pk_fma_f32 v[50:51], v[200:201], v[108:109], v[50:51]
	v_max_f32_e32 v210, 0, v20
	v_max_f32_e32 v211, 0, v21
	v_pk_fma_f32 v[50:51], v[202:203], v[210:211], v[50:51]
	v_add_f32_e32 v50, v50, v51
	v_ashrrev_i32_e32 v51, 31, v50
	s_waitcnt lgkmcnt(0)
	v_mfma_f32_32x32x16_bf16 v[212:227], v[82:85], v[196:199], v[212:227]
	v_or_b32_e32 v51, 0x80000000, v51
	s_cmpk_gt_i32 s11, 400
	s_cselect_b64 vcc, -1, 0
	v_xor_b32_e32 v50, v51, v50
	v_cndmask_b32_e32 v50, v123, v50, vcc
	global_store_dword v243, v50, s[8:9]
	v_mfma_f32_32x32x16_bf16 v[6:21], v[86:89], v[38:41], 0
	s_add_i32 m0, s10, 65536
	s_nop 0
	global_load_lds_dwordx4 v102, s[6:7]
	s_add_i32 m0, s10, 66560
	s_nop 0
	global_load_lds_dwordx4 v110, s[6:7]
	s_add_i32 m0, s10, 67584
	s_nop 0
	global_load_lds_dwordx4 v112, s[6:7]
	s_add_i32 m0, s10, 68608
	s_nop 0
	global_load_lds_dwordx4 v193, s[6:7]
	s_add_u32 s6, s6, 0x8000
	s_addc_u32 s7, s7, 0
	v_max_f32_e32 v108, 0, v212
	v_max_f32_e32 v109, 0, v213
	v_pk_mul_f32 v[0:1], v[22:23], v[108:109]
	v_max_f32_e32 v210, 0, v214
	v_max_f32_e32 v211, 0, v215
	v_pk_fma_f32 v[0:1], v[24:25], v[210:211], v[0:1]
	v_max_f32_e32 v108, 0, v216
	v_max_f32_e32 v109, 0, v217
	v_pk_fma_f32 v[0:1], v[26:27], v[108:109], v[0:1]
	v_mfma_f32_32x32x16_bf16 v[6:21], v[90:93], v[42:45], v[6:21]
	v_max_f32_e32 v210, 0, v218
	v_max_f32_e32 v211, 0, v219
	v_pk_fma_f32 v[0:1], v[28:29], v[210:211], v[0:1]
	v_max_f32_e32 v108, 0, v220
	v_max_f32_e32 v109, 0, v221
	v_pk_fma_f32 v[0:1], v[30:31], v[108:109], v[0:1]
	v_max_f32_e32 v210, 0, v222
	v_max_f32_e32 v211, 0, v223
	v_pk_fma_f32 v[0:1], v[32:33], v[210:211], v[0:1]
	v_mfma_f32_32x32x16_bf16 v[6:21], v[94:97], v[46:49], v[6:21]
	v_max_f32_e32 v108, 0, v224
	v_max_f32_e32 v109, 0, v225
	v_pk_fma_f32 v[0:1], v[34:35], v[108:109], v[0:1]
	v_max_f32_e32 v210, 0, v226
	v_max_f32_e32 v211, 0, v227
	v_pk_fma_f32 v[0:1], v[36:37], v[210:211], v[0:1]
	v_add_f32_e32 v0, v0, v1
	v_ashrrev_i32_e32 v1, 31, v0
	v_mfma_f32_32x32x16_bf16 v[6:21], v[98:101], v[196:199], v[6:21]
	s_waitcnt vmcnt(10)
	ds_read_b128 v[38:41], v5 offset:10496
	ds_read_b128 v[42:45], v52 offset:10496
	ds_read_b128 v[46:49], v55 offset:10496
	ds_read_b128 v[196:199], v56 offset:10496
	v_or_b32_e32 v1, 0x80000000, v1
	s_cmpk_gt_i32 s11, 408
	s_cselect_b64 vcc, -1, 0
	v_xor_b32_e32 v0, v1, v0
	v_cndmask_b32_e32 v183, v123, v0, vcc
	s_nop 3
	s_waitcnt lgkmcnt(3)
	v_mfma_f32_32x32x16_bf16 v[212:227], v[70:73], v[38:41], 0
	v_max_f32_e32 v108, 0, v6
	v_max_f32_e32 v109, 0, v7
	v_pk_mul_f32 v[50:51], v[244:245], v[108:109]
	v_max_f32_e32 v210, 0, v8
	v_max_f32_e32 v211, 0, v9
	v_pk_fma_f32 v[50:51], v[246:247], v[210:211], v[50:51]
	v_max_f32_e32 v108, 0, v10
	v_max_f32_e32 v109, 0, v11
	v_pk_fma_f32 v[50:51], v[248:249], v[108:109], v[50:51]
	s_waitcnt lgkmcnt(2)
	v_mfma_f32_32x32x16_bf16 v[212:227], v[74:77], v[42:45], v[212:227]
	v_max_f32_e32 v210, 0, v12
	v_max_f32_e32 v211, 0, v13
	v_pk_fma_f32 v[50:51], v[250:251], v[210:211], v[50:51]
	v_max_f32_e32 v108, 0, v14
	v_max_f32_e32 v109, 0, v15
	v_pk_fma_f32 v[50:51], v[252:253], v[108:109], v[50:51]
	v_max_f32_e32 v210, 0, v16
	v_max_f32_e32 v211, 0, v17
	v_pk_fma_f32 v[50:51], v[254:255], v[210:211], v[50:51]
	s_waitcnt lgkmcnt(1)
	v_mfma_f32_32x32x16_bf16 v[212:227], v[78:81], v[46:49], v[212:227]
	v_max_f32_e32 v108, 0, v18
	v_max_f32_e32 v109, 0, v19
	v_pk_fma_f32 v[50:51], v[200:201], v[108:109], v[50:51]
	v_max_f32_e32 v210, 0, v20
	v_max_f32_e32 v211, 0, v21
	v_pk_fma_f32 v[50:51], v[202:203], v[210:211], v[50:51]
	v_add_f32_e32 v50, v50, v51
	v_ashrrev_i32_e32 v51, 31, v50
	s_waitcnt lgkmcnt(0)
	v_mfma_f32_32x32x16_bf16 v[212:227], v[82:85], v[196:199], v[212:227]
	v_or_b32_e32 v51, 0x80000000, v51
	s_cmpk_gt_i32 s11, 408
	s_cselect_b64 vcc, -1, 0
	v_xor_b32_e32 v50, v51, v50
	v_cndmask_b32_e32 v50, v123, v50, vcc
	global_store_dword v243, v50, s[8:9] offset:2048
	s_add_u32 s8, s8, 0x1000
	s_addc_u32 s9, s9, 0
	v_mfma_f32_32x32x16_bf16 v[6:21], v[86:89], v[38:41], 0
	s_add_i32 m0, s10, 98304
	s_nop 0
	global_load_lds_dwordx4 v102, s[6:7]
	s_add_i32 m0, s10, 99328
	s_nop 0
	global_load_lds_dwordx4 v110, s[6:7]
	s_add_i32 m0, s10, 100352
	s_nop 0
	global_load_lds_dwordx4 v112, s[6:7]
	s_add_i32 m0, s10, 101376
	s_nop 0
	global_load_lds_dwordx4 v193, s[6:7]
	s_add_u32 s6, s6, 0x8000
	s_addc_u32 s7, s7, 0
	v_max_f32_e32 v108, 0, v212
	v_max_f32_e32 v109, 0, v213
	v_pk_mul_f32 v[0:1], v[22:23], v[108:109]
	v_max_f32_e32 v210, 0, v214
	v_max_f32_e32 v211, 0, v215
	v_pk_fma_f32 v[0:1], v[24:25], v[210:211], v[0:1]
	v_max_f32_e32 v108, 0, v216
	v_max_f32_e32 v109, 0, v217
	v_pk_fma_f32 v[0:1], v[26:27], v[108:109], v[0:1]
	v_mfma_f32_32x32x16_bf16 v[6:21], v[90:93], v[42:45], v[6:21]
	v_max_f32_e32 v210, 0, v218
	v_max_f32_e32 v211, 0, v219
	v_pk_fma_f32 v[0:1], v[28:29], v[210:211], v[0:1]
	v_max_f32_e32 v108, 0, v220
	v_max_f32_e32 v109, 0, v221
	v_pk_fma_f32 v[0:1], v[30:31], v[108:109], v[0:1]
	v_max_f32_e32 v210, 0, v222
	v_max_f32_e32 v211, 0, v223
	v_pk_fma_f32 v[0:1], v[32:33], v[210:211], v[0:1]
	v_mfma_f32_32x32x16_bf16 v[6:21], v[94:97], v[46:49], v[6:21]
	v_max_f32_e32 v108, 0, v224
	v_max_f32_e32 v109, 0, v225
	v_pk_fma_f32 v[0:1], v[34:35], v[108:109], v[0:1]
	v_max_f32_e32 v210, 0, v226
	v_max_f32_e32 v211, 0, v227
	v_pk_fma_f32 v[0:1], v[36:37], v[210:211], v[0:1]
	v_add_f32_e32 v0, v0, v1
	v_ashrrev_i32_e32 v1, 31, v0
	v_mfma_f32_32x32x16_bf16 v[6:21], v[98:101], v[196:199], v[6:21]
	s_waitcnt vmcnt(10)
	ds_read_b128 v[38:41], v5 offset:43264
	ds_read_b128 v[42:45], v52 offset:43264
	ds_read_b128 v[46:49], v55 offset:43264
	ds_read_b128 v[196:199], v56 offset:43264
	v_or_b32_e32 v1, 0x80000000, v1
	s_cmpk_gt_i32 s11, 416
	s_cselect_b64 vcc, -1, 0
	v_xor_b32_e32 v0, v1, v0
	v_cndmask_b32_e32 v187, v123, v0, vcc
	s_nop 3
	s_waitcnt lgkmcnt(3)
	v_mfma_f32_32x32x16_bf16 v[212:227], v[70:73], v[38:41], 0
	v_max_f32_e32 v108, 0, v6
	v_max_f32_e32 v109, 0, v7
	v_pk_mul_f32 v[50:51], v[244:245], v[108:109]
	v_max_f32_e32 v210, 0, v8
	v_max_f32_e32 v211, 0, v9
	v_pk_fma_f32 v[50:51], v[246:247], v[210:211], v[50:51]
	v_max_f32_e32 v108, 0, v10
	v_max_f32_e32 v109, 0, v11
	v_pk_fma_f32 v[50:51], v[248:249], v[108:109], v[50:51]
	s_waitcnt lgkmcnt(2)
	v_mfma_f32_32x32x16_bf16 v[212:227], v[74:77], v[42:45], v[212:227]
	v_max_f32_e32 v210, 0, v12
	v_max_f32_e32 v211, 0, v13
	v_pk_fma_f32 v[50:51], v[250:251], v[210:211], v[50:51]
	v_max_f32_e32 v108, 0, v14
	v_max_f32_e32 v109, 0, v15
	v_pk_fma_f32 v[50:51], v[252:253], v[108:109], v[50:51]
	v_max_f32_e32 v210, 0, v16
	v_max_f32_e32 v211, 0, v17
	v_pk_fma_f32 v[50:51], v[254:255], v[210:211], v[50:51]
	s_waitcnt lgkmcnt(1)
	v_mfma_f32_32x32x16_bf16 v[212:227], v[78:81], v[46:49], v[212:227]
	v_max_f32_e32 v108, 0, v18
	v_max_f32_e32 v109, 0, v19
	v_pk_fma_f32 v[50:51], v[200:201], v[108:109], v[50:51]
	v_max_f32_e32 v210, 0, v20
	v_max_f32_e32 v211, 0, v21
	v_pk_fma_f32 v[50:51], v[202:203], v[210:211], v[50:51]
	v_add_f32_e32 v50, v50, v51
	v_ashrrev_i32_e32 v51, 31, v50
	s_waitcnt lgkmcnt(0)
	v_mfma_f32_32x32x16_bf16 v[212:227], v[82:85], v[196:199], v[212:227]
	v_or_b32_e32 v51, 0x80000000, v51
	s_cmpk_gt_i32 s11, 416
	s_cselect_b64 vcc, -1, 0
	v_xor_b32_e32 v50, v51, v50
	v_cndmask_b32_e32 v50, v123, v50, vcc
	global_store_dword v243, v50, s[8:9]
	v_mfma_f32_32x32x16_bf16 v[6:21], v[86:89], v[38:41], 0
	s_add_i32 m0, s10, 0
	s_nop 0
	global_load_lds_dwordx4 v102, s[6:7]
	s_add_i32 m0, s10, 1024
	s_nop 0
	global_load_lds_dwordx4 v110, s[6:7]
	s_add_i32 m0, s10, 2048
	s_nop 0
	global_load_lds_dwordx4 v112, s[6:7]
	s_add_i32 m0, s10, 3072
	s_nop 0
	global_load_lds_dwordx4 v193, s[6:7]
	s_add_u32 s6, s6, 0x8000
	s_addc_u32 s7, s7, 0
	v_max_f32_e32 v108, 0, v212
	v_max_f32_e32 v109, 0, v213
	v_pk_mul_f32 v[0:1], v[22:23], v[108:109]
	v_max_f32_e32 v210, 0, v214
	v_max_f32_e32 v211, 0, v215
	v_pk_fma_f32 v[0:1], v[24:25], v[210:211], v[0:1]
	v_max_f32_e32 v108, 0, v216
	v_max_f32_e32 v109, 0, v217
	v_pk_fma_f32 v[0:1], v[26:27], v[108:109], v[0:1]
	v_mfma_f32_32x32x16_bf16 v[6:21], v[90:93], v[42:45], v[6:21]
	v_max_f32_e32 v210, 0, v218
	v_max_f32_e32 v211, 0, v219
	v_pk_fma_f32 v[0:1], v[28:29], v[210:211], v[0:1]
	v_max_f32_e32 v108, 0, v220
	v_max_f32_e32 v109, 0, v221
	v_pk_fma_f32 v[0:1], v[30:31], v[108:109], v[0:1]
	v_max_f32_e32 v210, 0, v222
	v_max_f32_e32 v211, 0, v223
	v_pk_fma_f32 v[0:1], v[32:33], v[210:211], v[0:1]
	v_mfma_f32_32x32x16_bf16 v[6:21], v[94:97], v[46:49], v[6:21]
	v_max_f32_e32 v108, 0, v224
	v_max_f32_e32 v109, 0, v225
	v_pk_fma_f32 v[0:1], v[34:35], v[108:109], v[0:1]
	v_max_f32_e32 v210, 0, v226
	v_max_f32_e32 v211, 0, v227
	v_pk_fma_f32 v[0:1], v[36:37], v[210:211], v[0:1]
	v_add_f32_e32 v0, v0, v1
	v_ashrrev_i32_e32 v1, 31, v0
	v_mfma_f32_32x32x16_bf16 v[6:21], v[98:101], v[196:199], v[6:21]
	s_waitcnt vmcnt(10)
	v_add_u32_e32 v228, 0x10000, v5
	ds_read_b128 v[38:41], v228 offset:10496
	v_add_u32_e32 v228, 0x10000, v52
	ds_read_b128 v[42:45], v228 offset:10496
	v_add_u32_e32 v228, 0x10000, v55
	ds_read_b128 v[46:49], v228 offset:10496
	v_add_u32_e32 v228, 0x10000, v56
	ds_read_b128 v[196:199], v228 offset:10496
	v_or_b32_e32 v1, 0x80000000, v1
	s_cmpk_gt_i32 s11, 424
	s_cselect_b64 vcc, -1, 0
	v_xor_b32_e32 v0, v1, v0
	v_cndmask_b32_e32 v186, v123, v0, vcc
	s_nop 3
	s_waitcnt lgkmcnt(3)
	v_mfma_f32_32x32x16_bf16 v[212:227], v[70:73], v[38:41], 0
	v_max_f32_e32 v108, 0, v6
	v_max_f32_e32 v109, 0, v7
	v_pk_mul_f32 v[50:51], v[244:245], v[108:109]
	v_max_f32_e32 v210, 0, v8
	v_max_f32_e32 v211, 0, v9
	v_pk_fma_f32 v[50:51], v[246:247], v[210:211], v[50:51]
	v_max_f32_e32 v108, 0, v10
	v_max_f32_e32 v109, 0, v11
	v_pk_fma_f32 v[50:51], v[248:249], v[108:109], v[50:51]
	s_waitcnt lgkmcnt(2)
	v_mfma_f32_32x32x16_bf16 v[212:227], v[74:77], v[42:45], v[212:227]
	v_max_f32_e32 v210, 0, v12
	v_max_f32_e32 v211, 0, v13
	v_pk_fma_f32 v[50:51], v[250:251], v[210:211], v[50:51]
	v_max_f32_e32 v108, 0, v14
	v_max_f32_e32 v109, 0, v15
	v_pk_fma_f32 v[50:51], v[252:253], v[108:109], v[50:51]
	v_max_f32_e32 v210, 0, v16
	v_max_f32_e32 v211, 0, v17
	v_pk_fma_f32 v[50:51], v[254:255], v[210:211], v[50:51]
	s_waitcnt lgkmcnt(1)
	v_mfma_f32_32x32x16_bf16 v[212:227], v[78:81], v[46:49], v[212:227]
	v_max_f32_e32 v108, 0, v18
	v_max_f32_e32 v109, 0, v19
	v_pk_fma_f32 v[50:51], v[200:201], v[108:109], v[50:51]
	v_max_f32_e32 v210, 0, v20
	v_max_f32_e32 v211, 0, v21
	v_pk_fma_f32 v[50:51], v[202:203], v[210:211], v[50:51]
	v_add_f32_e32 v50, v50, v51
	v_ashrrev_i32_e32 v51, 31, v50
	s_waitcnt lgkmcnt(0)
	v_mfma_f32_32x32x16_bf16 v[212:227], v[82:85], v[196:199], v[212:227]
	v_or_b32_e32 v51, 0x80000000, v51
	s_cmpk_gt_i32 s11, 424
	s_cselect_b64 vcc, -1, 0
	v_xor_b32_e32 v50, v51, v50
	v_cndmask_b32_e32 v50, v123, v50, vcc
	global_store_dword v243, v50, s[8:9] offset:2048
	s_add_u32 s8, s8, 0x1000
	s_addc_u32 s9, s9, 0
	v_mfma_f32_32x32x16_bf16 v[6:21], v[86:89], v[38:41], 0
	s_add_i32 m0, s10, 32768
	s_nop 0
	global_load_lds_dwordx4 v102, s[6:7]
	s_add_i32 m0, s10, 33792
	s_nop 0
	global_load_lds_dwordx4 v110, s[6:7]
	s_add_i32 m0, s10, 34816
	s_nop 0
	global_load_lds_dwordx4 v112, s[6:7]
	s_add_i32 m0, s10, 35840
	s_nop 0
	global_load_lds_dwordx4 v193, s[6:7]
	s_add_u32 s6, s6, 0x8000
	s_addc_u32 s7, s7, 0
	v_max_f32_e32 v108, 0, v212
	v_max_f32_e32 v109, 0, v213
	v_pk_mul_f32 v[0:1], v[22:23], v[108:109]
	v_max_f32_e32 v210, 0, v214
	v_max_f32_e32 v211, 0, v215
	v_pk_fma_f32 v[0:1], v[24:25], v[210:211], v[0:1]
	v_max_f32_e32 v108, 0, v216
	v_max_f32_e32 v109, 0, v217
	v_pk_fma_f32 v[0:1], v[26:27], v[108:109], v[0:1]
	v_mfma_f32_32x32x16_bf16 v[6:21], v[90:93], v[42:45], v[6:21]
	v_max_f32_e32 v210, 0, v218
	v_max_f32_e32 v211, 0, v219
	v_pk_fma_f32 v[0:1], v[28:29], v[210:211], v[0:1]
	v_max_f32_e32 v108, 0, v220
	v_max_f32_e32 v109, 0, v221
	v_pk_fma_f32 v[0:1], v[30:31], v[108:109], v[0:1]
	v_max_f32_e32 v210, 0, v222
	v_max_f32_e32 v211, 0, v223
	v_pk_fma_f32 v[0:1], v[32:33], v[210:211], v[0:1]
	v_mfma_f32_32x32x16_bf16 v[6:21], v[94:97], v[46:49], v[6:21]
	v_max_f32_e32 v108, 0, v224
	v_max_f32_e32 v109, 0, v225
	v_pk_fma_f32 v[0:1], v[34:35], v[108:109], v[0:1]
	v_max_f32_e32 v210, 0, v226
	v_max_f32_e32 v211, 0, v227
	v_pk_fma_f32 v[0:1], v[36:37], v[210:211], v[0:1]
	v_add_f32_e32 v0, v0, v1
	v_ashrrev_i32_e32 v1, 31, v0
	v_mfma_f32_32x32x16_bf16 v[6:21], v[98:101], v[196:199], v[6:21]
	s_waitcnt vmcnt(10)
	v_add_u32_e32 v228, 0x10000, v5
	ds_read_b128 v[38:41], v228 offset:43264
	v_add_u32_e32 v228, 0x10000, v52
	ds_read_b128 v[42:45], v228 offset:43264
	v_add_u32_e32 v228, 0x10000, v55
	ds_read_b128 v[46:49], v228 offset:43264
	v_add_u32_e32 v228, 0x10000, v56
	ds_read_b128 v[196:199], v228 offset:43264
	v_or_b32_e32 v1, 0x80000000, v1
	s_cmpk_gt_i32 s11, 432
	s_cselect_b64 vcc, -1, 0
	v_xor_b32_e32 v0, v1, v0
	v_cndmask_b32_e32 v189, v123, v0, vcc
	s_nop 3
	s_waitcnt lgkmcnt(3)
	v_mfma_f32_32x32x16_bf16 v[212:227], v[70:73], v[38:41], 0
	v_max_f32_e32 v108, 0, v6
	v_max_f32_e32 v109, 0, v7
	v_pk_mul_f32 v[50:51], v[244:245], v[108:109]
	v_max_f32_e32 v210, 0, v8
	v_max_f32_e32 v211, 0, v9
	v_pk_fma_f32 v[50:51], v[246:247], v[210:211], v[50:51]
	v_max_f32_e32 v108, 0, v10
	v_max_f32_e32 v109, 0, v11
	v_pk_fma_f32 v[50:51], v[248:249], v[108:109], v[50:51]
	s_waitcnt lgkmcnt(2)
	v_mfma_f32_32x32x16_bf16 v[212:227], v[74:77], v[42:45], v[212:227]
	v_max_f32_e32 v210, 0, v12
	v_max_f32_e32 v211, 0, v13
	v_pk_fma_f32 v[50:51], v[250:251], v[210:211], v[50:51]
	v_max_f32_e32 v108, 0, v14
	v_max_f32_e32 v109, 0, v15
	v_pk_fma_f32 v[50:51], v[252:253], v[108:109], v[50:51]
	v_max_f32_e32 v210, 0, v16
	v_max_f32_e32 v211, 0, v17
	v_pk_fma_f32 v[50:51], v[254:255], v[210:211], v[50:51]
	s_waitcnt lgkmcnt(1)
	v_mfma_f32_32x32x16_bf16 v[212:227], v[78:81], v[46:49], v[212:227]
	v_max_f32_e32 v108, 0, v18
	v_max_f32_e32 v109, 0, v19
	v_pk_fma_f32 v[50:51], v[200:201], v[108:109], v[50:51]
	v_max_f32_e32 v210, 0, v20
	v_max_f32_e32 v211, 0, v21
	v_pk_fma_f32 v[50:51], v[202:203], v[210:211], v[50:51]
	v_add_f32_e32 v50, v50, v51
	v_ashrrev_i32_e32 v51, 31, v50
	s_waitcnt lgkmcnt(0)
	v_mfma_f32_32x32x16_bf16 v[212:227], v[82:85], v[196:199], v[212:227]
	v_or_b32_e32 v51, 0x80000000, v51
	s_cmpk_gt_i32 s11, 432
	s_cselect_b64 vcc, -1, 0
	v_xor_b32_e32 v50, v51, v50
	v_cndmask_b32_e32 v50, v123, v50, vcc
	global_store_dword v243, v50, s[8:9]
	v_mfma_f32_32x32x16_bf16 v[6:21], v[86:89], v[38:41], 0
	s_add_i32 m0, s10, 65536
	s_nop 0
	global_load_lds_dwordx4 v102, s[6:7]
	s_add_i32 m0, s10, 66560
	s_nop 0
	global_load_lds_dwordx4 v110, s[6:7]
	s_add_i32 m0, s10, 67584
	s_nop 0
	global_load_lds_dwordx4 v112, s[6:7]
	s_add_i32 m0, s10, 68608
	s_nop 0
	global_load_lds_dwordx4 v193, s[6:7]
	s_add_u32 s6, s6, 0x8000
	s_addc_u32 s7, s7, 0
	v_max_f32_e32 v108, 0, v212
	v_max_f32_e32 v109, 0, v213
	v_pk_mul_f32 v[0:1], v[22:23], v[108:109]
	v_max_f32_e32 v210, 0, v214
	v_max_f32_e32 v211, 0, v215
	v_pk_fma_f32 v[0:1], v[24:25], v[210:211], v[0:1]
	v_max_f32_e32 v108, 0, v216
	v_max_f32_e32 v109, 0, v217
	v_pk_fma_f32 v[0:1], v[26:27], v[108:109], v[0:1]
	v_mfma_f32_32x32x16_bf16 v[6:21], v[90:93], v[42:45], v[6:21]
	v_max_f32_e32 v210, 0, v218
	v_max_f32_e32 v211, 0, v219
	v_pk_fma_f32 v[0:1], v[28:29], v[210:211], v[0:1]
	v_max_f32_e32 v108, 0, v220
	v_max_f32_e32 v109, 0, v221
	v_pk_fma_f32 v[0:1], v[30:31], v[108:109], v[0:1]
	v_max_f32_e32 v210, 0, v222
	v_max_f32_e32 v211, 0, v223
	v_pk_fma_f32 v[0:1], v[32:33], v[210:211], v[0:1]
	v_mfma_f32_32x32x16_bf16 v[6:21], v[94:97], v[46:49], v[6:21]
	v_max_f32_e32 v108, 0, v224
	v_max_f32_e32 v109, 0, v225
	v_pk_fma_f32 v[0:1], v[34:35], v[108:109], v[0:1]
	v_max_f32_e32 v210, 0, v226
	v_max_f32_e32 v211, 0, v227
	v_pk_fma_f32 v[0:1], v[36:37], v[210:211], v[0:1]
	v_add_f32_e32 v0, v0, v1
	v_ashrrev_i32_e32 v1, 31, v0
	v_mfma_f32_32x32x16_bf16 v[6:21], v[98:101], v[196:199], v[6:21]
	s_waitcnt vmcnt(10)
	ds_read_b128 v[38:41], v5 offset:10496
	ds_read_b128 v[42:45], v52 offset:10496
	ds_read_b128 v[46:49], v55 offset:10496
	ds_read_b128 v[196:199], v56 offset:10496
	v_or_b32_e32 v1, 0x80000000, v1
	s_cmpk_gt_i32 s11, 440
	s_cselect_b64 vcc, -1, 0
	v_xor_b32_e32 v0, v1, v0
	v_cndmask_b32_e32 v188, v123, v0, vcc
	s_nop 3
	v_max_f32_e32 v108, 0, v6
	v_max_f32_e32 v109, 0, v7
	v_pk_mul_f32 v[50:51], v[244:245], v[108:109]
	v_max_f32_e32 v210, 0, v8
	v_max_f32_e32 v211, 0, v9
	v_pk_fma_f32 v[50:51], v[246:247], v[210:211], v[50:51]
	v_max_f32_e32 v108, 0, v10
	v_max_f32_e32 v109, 0, v11
	v_pk_fma_f32 v[50:51], v[248:249], v[108:109], v[50:51]
	v_max_f32_e32 v210, 0, v12
	v_max_f32_e32 v211, 0, v13
	v_pk_fma_f32 v[50:51], v[250:251], v[210:211], v[50:51]
	v_max_f32_e32 v108, 0, v14
	v_max_f32_e32 v109, 0, v15
	v_pk_fma_f32 v[50:51], v[252:253], v[108:109], v[50:51]
	v_max_f32_e32 v210, 0, v16
	v_max_f32_e32 v211, 0, v17
	v_pk_fma_f32 v[50:51], v[254:255], v[210:211], v[50:51]
	v_max_f32_e32 v108, 0, v18
	v_max_f32_e32 v109, 0, v19
	v_pk_fma_f32 v[50:51], v[200:201], v[108:109], v[50:51]
	v_max_f32_e32 v210, 0, v20
	v_max_f32_e32 v211, 0, v21
	v_pk_fma_f32 v[50:51], v[202:203], v[210:211], v[50:51]
	v_add_f32_e32 v50, v50, v51
	v_ashrrev_i32_e32 v51, 31, v50
	v_or_b32_e32 v51, 0x80000000, v51
	s_cmpk_gt_i32 s11, 440
	s_cselect_b64 vcc, -1, 0
	v_xor_b32_e32 v50, v51, v50
	v_cndmask_b32_e32 v50, v123, v50, vcc
	global_store_dword v243, v50, s[8:9] offset:2048
	s_add_u32 s8, s8, 0x1000
	s_addc_u32 s9, s9, 0
	s_cmpk_gt_i32 s81, 56
	s_cbranch_scc0 .Lix_fill_7
	s_waitcnt lgkmcnt(3)
	v_mfma_f32_32x32x16_bf16 v[212:227], v[70:73], v[38:41], 0
	s_add_i32 m0, s10, 98304
	s_nop 0
	global_load_lds_dwordx4 v102, s[6:7]
	s_waitcnt lgkmcnt(2)
	v_mfma_f32_32x32x16_bf16 v[212:227], v[74:77], v[42:45], v[212:227]
	s_add_i32 m0, s10, 99328
	s_nop 0
	global_load_lds_dwordx4 v110, s[6:7]
	s_waitcnt lgkmcnt(1)
	v_mfma_f32_32x32x16_bf16 v[212:227], v[78:81], v[46:49], v[212:227]
	s_add_i32 m0, s10, 100352
	s_nop 0
	global_load_lds_dwordx4 v112, s[6:7]
	s_waitcnt lgkmcnt(0)
	v_mfma_f32_32x32x16_bf16 v[212:227], v[82:85], v[196:199], v[212:227]
	s_add_i32 m0, s10, 101376
	s_nop 0
	global_load_lds_dwordx4 v193, s[6:7]
	s_add_u32 s6, s6, 0x8000
	s_addc_u32 s7, s7, 0
	v_mfma_f32_32x32x16_bf16 v[6:21], v[86:89], v[38:41], 0
	s_nop 7
	s_nop 2
	v_max_f32_e32 v108, 0, v212
	v_max_f32_e32 v109, 0, v213
	v_pk_mul_f32 v[0:1], v[22:23], v[108:109]
	v_max_f32_e32 v210, 0, v214
	v_max_f32_e32 v211, 0, v215
	v_pk_fma_f32 v[0:1], v[24:25], v[210:211], v[0:1]
	v_max_f32_e32 v108, 0, v216
	v_max_f32_e32 v109, 0, v217
	v_pk_fma_f32 v[0:1], v[26:27], v[108:109], v[0:1]
	v_mfma_f32_32x32x16_bf16 v[6:21], v[90:93], v[42:45], v[6:21]
	v_max_f32_e32 v210, 0, v218
	v_max_f32_e32 v211, 0, v219
	v_pk_fma_f32 v[0:1], v[28:29], v[210:211], v[0:1]
	v_max_f32_e32 v108, 0, v220
	v_max_f32_e32 v109, 0, v221
	v_pk_fma_f32 v[0:1], v[30:31], v[108:109], v[0:1]
	v_max_f32_e32 v210, 0, v222
	v_max_f32_e32 v211, 0, v223
	v_pk_fma_f32 v[0:1], v[32:33], v[210:211], v[0:1]
	v_mfma_f32_32x32x16_bf16 v[6:21], v[94:97], v[46:49], v[6:21]
	v_max_f32_e32 v108, 0, v224
	v_max_f32_e32 v109, 0, v225
	v_pk_fma_f32 v[0:1], v[34:35], v[108:109], v[0:1]
	v_max_f32_e32 v210, 0, v226
	v_max_f32_e32 v211, 0, v227
	v_pk_fma_f32 v[0:1], v[36:37], v[210:211], v[0:1]
	v_add_f32_e32 v0, v0, v1
	v_ashrrev_i32_e32 v1, 31, v0
	v_mfma_f32_32x32x16_bf16 v[6:21], v[98:101], v[196:199], v[6:21]
	s_waitcnt vmcnt(10)
	ds_read_b128 v[38:41], v5 offset:43264
	ds_read_b128 v[42:45], v52 offset:43264
	ds_read_b128 v[46:49], v55 offset:43264
	ds_read_b128 v[196:199], v56 offset:43264
	v_or_b32_e32 v1, 0x80000000, v1
	s_cmpk_gt_i32 s11, 448
	s_cselect_b64 vcc, -1, 0
	v_xor_b32_e32 v0, v1, v0
	v_cndmask_b32_e32 v190, v123, v0, vcc
	s_nop 3
	s_waitcnt lgkmcnt(3)
	v_mfma_f32_32x32x16_bf16 v[212:227], v[70:73], v[38:41], 0
	v_max_f32_e32 v108, 0, v6
	v_max_f32_e32 v109, 0, v7
	v_pk_mul_f32 v[50:51], v[244:245], v[108:109]
	v_max_f32_e32 v210, 0, v8
	v_max_f32_e32 v211, 0, v9
	v_pk_fma_f32 v[50:51], v[246:247], v[210:211], v[50:51]
	v_max_f32_e32 v108, 0, v10
	v_max_f32_e32 v109, 0, v11
	v_pk_fma_f32 v[50:51], v[248:249], v[108:109], v[50:51]
	s_waitcnt lgkmcnt(2)
	v_mfma_f32_32x32x16_bf16 v[212:227], v[74:77], v[42:45], v[212:227]
	v_max_f32_e32 v210, 0, v12
	v_max_f32_e32 v211, 0, v13
	v_pk_fma_f32 v[50:51], v[250:251], v[210:211], v[50:51]
	v_max_f32_e32 v108, 0, v14
	v_max_f32_e32 v109, 0, v15
	v_pk_fma_f32 v[50:51], v[252:253], v[108:109], v[50:51]
	v_max_f32_e32 v210, 0, v16
	v_max_f32_e32 v211, 0, v17
	v_pk_fma_f32 v[50:51], v[254:255], v[210:211], v[50:51]
	s_waitcnt lgkmcnt(1)
	v_mfma_f32_32x32x16_bf16 v[212:227], v[78:81], v[46:49], v[212:227]
	v_max_f32_e32 v108, 0, v18
	v_max_f32_e32 v109, 0, v19
	v_pk_fma_f32 v[50:51], v[200:201], v[108:109], v[50:51]
	v_max_f32_e32 v210, 0, v20
	v_max_f32_e32 v211, 0, v21
	v_pk_fma_f32 v[50:51], v[202:203], v[210:211], v[50:51]
	v_add_f32_e32 v50, v50, v51
	v_ashrrev_i32_e32 v51, 31, v50
	s_waitcnt lgkmcnt(0)
	v_mfma_f32_32x32x16_bf16 v[212:227], v[82:85], v[196:199], v[212:227]
	v_or_b32_e32 v51, 0x80000000, v51
	s_cmpk_gt_i32 s11, 448
	s_cselect_b64 vcc, -1, 0
	v_xor_b32_e32 v50, v51, v50
	v_cndmask_b32_e32 v50, v123, v50, vcc
	global_store_dword v243, v50, s[8:9]
	v_mfma_f32_32x32x16_bf16 v[6:21], v[86:89], v[38:41], 0
	s_add_i32 m0, s10, 0
	s_nop 0
	global_load_lds_dwordx4 v102, s[6:7]
	s_add_i32 m0, s10, 1024
	s_nop 0
	global_load_lds_dwordx4 v110, s[6:7]
	s_add_i32 m0, s10, 2048
	s_nop 0
	global_load_lds_dwordx4 v112, s[6:7]
	s_add_i32 m0, s10, 3072
	s_nop 0
	global_load_lds_dwordx4 v193, s[6:7]
	s_add_u32 s6, s6, 0x8000
	s_addc_u32 s7, s7, 0
	v_max_f32_e32 v108, 0, v212
	v_max_f32_e32 v109, 0, v213
	v_pk_mul_f32 v[0:1], v[22:23], v[108:109]
	v_max_f32_e32 v210, 0, v214
	v_max_f32_e32 v211, 0, v215
	v_pk_fma_f32 v[0:1], v[24:25], v[210:211], v[0:1]
	v_max_f32_e32 v108, 0, v216
	v_max_f32_e32 v109, 0, v217
	v_pk_fma_f32 v[0:1], v[26:27], v[108:109], v[0:1]
	v_mfma_f32_32x32x16_bf16 v[6:21], v[90:93], v[42:45], v[6:21]
	v_max_f32_e32 v210, 0, v218
	v_max_f32_e32 v211, 0, v219
	v_pk_fma_f32 v[0:1], v[28:29], v[210:211], v[0:1]
	v_max_f32_e32 v108, 0, v220
	v_max_f32_e32 v109, 0, v221
	v_pk_fma_f32 v[0:1], v[30:31], v[108:109], v[0:1]
	v_max_f32_e32 v210, 0, v222
	v_max_f32_e32 v211, 0, v223
	v_pk_fma_f32 v[0:1], v[32:33], v[210:211], v[0:1]
	v_mfma_f32_32x32x16_bf16 v[6:21], v[94:97], v[46:49], v[6:21]
	v_max_f32_e32 v108, 0, v224
	v_max_f32_e32 v109, 0, v225
	v_pk_fma_f32 v[0:1], v[34:35], v[108:109], v[0:1]
	v_max_f32_e32 v210, 0, v226
	v_max_f32_e32 v211, 0, v227
	v_pk_fma_f32 v[0:1], v[36:37], v[210:211], v[0:1]
	v_add_f32_e32 v0, v0, v1
	v_ashrrev_i32_e32 v1, 31, v0
	v_mfma_f32_32x32x16_bf16 v[6:21], v[98:101], v[196:199], v[6:21]
	s_waitcnt vmcnt(10)
	v_add_u32_e32 v228, 0x10000, v5
	ds_read_b128 v[38:41], v228 offset:10496
	v_add_u32_e32 v228, 0x10000, v52
	ds_read_b128 v[42:45], v228 offset:10496
	v_add_u32_e32 v228, 0x10000, v55
	ds_read_b128 v[46:49], v228 offset:10496
	v_add_u32_e32 v228, 0x10000, v56
	ds_read_b128 v[196:199], v228 offset:10496
	v_or_b32_e32 v1, 0x80000000, v1
	s_cmpk_gt_i32 s11, 456
	s_cselect_b64 vcc, -1, 0
	v_xor_b32_e32 v0, v1, v0
	v_cndmask_b32_e32 v53, v123, v0, vcc
	s_nop 3
	s_waitcnt lgkmcnt(3)
	v_mfma_f32_32x32x16_bf16 v[212:227], v[70:73], v[38:41], 0
	v_max_f32_e32 v108, 0, v6
	v_max_f32_e32 v109, 0, v7
	v_pk_mul_f32 v[50:51], v[244:245], v[108:109]
	v_max_f32_e32 v210, 0, v8
	v_max_f32_e32 v211, 0, v9
	v_pk_fma_f32 v[50:51], v[246:247], v[210:211], v[50:51]
	v_max_f32_e32 v108, 0, v10
	v_max_f32_e32 v109, 0, v11
	v_pk_fma_f32 v[50:51], v[248:249], v[108:109], v[50:51]
	s_waitcnt lgkmcnt(2)
	v_mfma_f32_32x32x16_bf16 v[212:227], v[74:77], v[42:45], v[212:227]
	v_max_f32_e32 v210, 0, v12
	v_max_f32_e32 v211, 0, v13
	v_pk_fma_f32 v[50:51], v[250:251], v[210:211], v[50:51]
	v_max_f32_e32 v108, 0, v14
	v_max_f32_e32 v109, 0, v15
	v_pk_fma_f32 v[50:51], v[252:253], v[108:109], v[50:51]
	v_max_f32_e32 v210, 0, v16
	v_max_f32_e32 v211, 0, v17
	v_pk_fma_f32 v[50:51], v[254:255], v[210:211], v[50:51]
	s_waitcnt lgkmcnt(1)
	v_mfma_f32_32x32x16_bf16 v[212:227], v[78:81], v[46:49], v[212:227]
	v_max_f32_e32 v108, 0, v18
	v_max_f32_e32 v109, 0, v19
	v_pk_fma_f32 v[50:51], v[200:201], v[108:109], v[50:51]
	v_max_f32_e32 v210, 0, v20
	v_max_f32_e32 v211, 0, v21
	v_pk_fma_f32 v[50:51], v[202:203], v[210:211], v[50:51]
	v_add_f32_e32 v50, v50, v51
	v_ashrrev_i32_e32 v51, 31, v50
	s_waitcnt lgkmcnt(0)
	v_mfma_f32_32x32x16_bf16 v[212:227], v[82:85], v[196:199], v[212:227]
	v_or_b32_e32 v51, 0x80000000, v51
	s_cmpk_gt_i32 s11, 456
	s_cselect_b64 vcc, -1, 0
	v_xor_b32_e32 v50, v51, v50
	v_cndmask_b32_e32 v50, v123, v50, vcc
	global_store_dword v243, v50, s[8:9] offset:2048
	s_add_u32 s8, s8, 0x1000
	s_addc_u32 s9, s9, 0
	v_mfma_f32_32x32x16_bf16 v[6:21], v[86:89], v[38:41], 0
	s_add_i32 m0, s10, 32768
	s_nop 0
	global_load_lds_dwordx4 v102, s[6:7]
	s_add_i32 m0, s10, 33792
	s_nop 0
	global_load_lds_dwordx4 v110, s[6:7]
	s_add_i32 m0, s10, 34816
	s_nop 0
	global_load_lds_dwordx4 v112, s[6:7]
	s_add_i32 m0, s10, 35840
	s_nop 0
	global_load_lds_dwordx4 v193, s[6:7]
	s_add_u32 s6, s6, 0x8000
	s_addc_u32 s7, s7, 0
	v_max_f32_e32 v108, 0, v212
	v_max_f32_e32 v109, 0, v213
	v_pk_mul_f32 v[0:1], v[22:23], v[108:109]
	v_max_f32_e32 v210, 0, v214
	v_max_f32_e32 v211, 0, v215
	v_pk_fma_f32 v[0:1], v[24:25], v[210:211], v[0:1]
	v_max_f32_e32 v108, 0, v216
	v_max_f32_e32 v109, 0, v217
	v_pk_fma_f32 v[0:1], v[26:27], v[108:109], v[0:1]
	v_mfma_f32_32x32x16_bf16 v[6:21], v[90:93], v[42:45], v[6:21]
	v_max_f32_e32 v210, 0, v218
	v_max_f32_e32 v211, 0, v219
	v_pk_fma_f32 v[0:1], v[28:29], v[210:211], v[0:1]
	v_max_f32_e32 v108, 0, v220
	v_max_f32_e32 v109, 0, v221
	v_pk_fma_f32 v[0:1], v[30:31], v[108:109], v[0:1]
	v_max_f32_e32 v210, 0, v222
	v_max_f32_e32 v211, 0, v223
	v_pk_fma_f32 v[0:1], v[32:33], v[210:211], v[0:1]
	v_mfma_f32_32x32x16_bf16 v[6:21], v[94:97], v[46:49], v[6:21]
	v_max_f32_e32 v108, 0, v224
	v_max_f32_e32 v109, 0, v225
	v_pk_fma_f32 v[0:1], v[34:35], v[108:109], v[0:1]
	v_max_f32_e32 v210, 0, v226
	v_max_f32_e32 v211, 0, v227
	v_pk_fma_f32 v[0:1], v[36:37], v[210:211], v[0:1]
	v_add_f32_e32 v0, v0, v1
	v_ashrrev_i32_e32 v1, 31, v0
	v_mfma_f32_32x32x16_bf16 v[6:21], v[98:101], v[196:199], v[6:21]
	s_waitcnt vmcnt(10)
	v_add_u32_e32 v228, 0x10000, v5
	ds_read_b128 v[38:41], v228 offset:43264
	v_add_u32_e32 v228, 0x10000, v52
	ds_read_b128 v[42:45], v228 offset:43264
	v_add_u32_e32 v228, 0x10000, v55
	ds_read_b128 v[46:49], v228 offset:43264
	v_add_u32_e32 v228, 0x10000, v56
	ds_read_b128 v[196:199], v228 offset:43264
	v_or_b32_e32 v1, 0x80000000, v1
	s_cmpk_gt_i32 s11, 464
	s_cselect_b64 vcc, -1, 0
	v_xor_b32_e32 v0, v1, v0
	v_cndmask_b32_e32 v192, v123, v0, vcc
	s_nop 3
	s_waitcnt lgkmcnt(3)
	v_mfma_f32_32x32x16_bf16 v[212:227], v[70:73], v[38:41], 0
	v_max_f32_e32 v108, 0, v6
	v_max_f32_e32 v109, 0, v7
	v_pk_mul_f32 v[50:51], v[244:245], v[108:109]
	v_max_f32_e32 v210, 0, v8
	v_max_f32_e32 v211, 0, v9
	v_pk_fma_f32 v[50:51], v[246:247], v[210:211], v[50:51]
	v_max_f32_e32 v108, 0, v10
	v_max_f32_e32 v109, 0, v11
	v_pk_fma_f32 v[50:51], v[248:249], v[108:109], v[50:51]
	s_waitcnt lgkmcnt(2)
	v_mfma_f32_32x32x16_bf16 v[212:227], v[74:77], v[42:45], v[212:227]
	v_max_f32_e32 v210, 0, v12
	v_max_f32_e32 v211, 0, v13
	v_pk_fma_f32 v[50:51], v[250:251], v[210:211], v[50:51]
	v_max_f32_e32 v108, 0, v14
	v_max_f32_e32 v109, 0, v15
	v_pk_fma_f32 v[50:51], v[252:253], v[108:109], v[50:51]
	v_max_f32_e32 v210, 0, v16
	v_max_f32_e32 v211, 0, v17
	v_pk_fma_f32 v[50:51], v[254:255], v[210:211], v[50:51]
	s_waitcnt lgkmcnt(1)
	v_mfma_f32_32x32x16_bf16 v[212:227], v[78:81], v[46:49], v[212:227]
	v_max_f32_e32 v108, 0, v18
	v_max_f32_e32 v109, 0, v19
	v_pk_fma_f32 v[50:51], v[200:201], v[108:109], v[50:51]
	v_max_f32_e32 v210, 0, v20
	v_max_f32_e32 v211, 0, v21
	v_pk_fma_f32 v[50:51], v[202:203], v[210:211], v[50:51]
	v_add_f32_e32 v50, v50, v51
	v_ashrrev_i32_e32 v51, 31, v50
	s_waitcnt lgkmcnt(0)
	v_mfma_f32_32x32x16_bf16 v[212:227], v[82:85], v[196:199], v[212:227]
	v_or_b32_e32 v51, 0x80000000, v51
	s_cmpk_gt_i32 s11, 464
	s_cselect_b64 vcc, -1, 0
	v_xor_b32_e32 v50, v51, v50
	v_cndmask_b32_e32 v50, v123, v50, vcc
	global_store_dword v243, v50, s[8:9]
	v_mfma_f32_32x32x16_bf16 v[6:21], v[86:89], v[38:41], 0
	s_add_i32 m0, s10, 65536
	s_nop 0
	global_load_lds_dwordx4 v102, s[6:7]
	s_add_i32 m0, s10, 66560
	s_nop 0
	global_load_lds_dwordx4 v110, s[6:7]
	s_add_i32 m0, s10, 67584
	s_nop 0
	global_load_lds_dwordx4 v112, s[6:7]
	s_add_i32 m0, s10, 68608
	s_nop 0
	global_load_lds_dwordx4 v193, s[6:7]
	s_add_u32 s6, s6, 0x8000
	s_addc_u32 s7, s7, 0
	v_max_f32_e32 v108, 0, v212
	v_max_f32_e32 v109, 0, v213
	v_pk_mul_f32 v[0:1], v[22:23], v[108:109]
	v_max_f32_e32 v210, 0, v214
	v_max_f32_e32 v211, 0, v215
	v_pk_fma_f32 v[0:1], v[24:25], v[210:211], v[0:1]
	v_max_f32_e32 v108, 0, v216
	v_max_f32_e32 v109, 0, v217
	v_pk_fma_f32 v[0:1], v[26:27], v[108:109], v[0:1]
	v_mfma_f32_32x32x16_bf16 v[6:21], v[90:93], v[42:45], v[6:21]
	v_max_f32_e32 v210, 0, v218
	v_max_f32_e32 v211, 0, v219
	v_pk_fma_f32 v[0:1], v[28:29], v[210:211], v[0:1]
	v_max_f32_e32 v108, 0, v220
	v_max_f32_e32 v109, 0, v221
	v_pk_fma_f32 v[0:1], v[30:31], v[108:109], v[0:1]
	v_max_f32_e32 v210, 0, v222
	v_max_f32_e32 v211, 0, v223
	v_pk_fma_f32 v[0:1], v[32:33], v[210:211], v[0:1]
	v_mfma_f32_32x32x16_bf16 v[6:21], v[94:97], v[46:49], v[6:21]
	v_max_f32_e32 v108, 0, v224
	v_max_f32_e32 v109, 0, v225
	v_pk_fma_f32 v[0:1], v[34:35], v[108:109], v[0:1]
	v_max_f32_e32 v210, 0, v226
	v_max_f32_e32 v211, 0, v227
	v_pk_fma_f32 v[0:1], v[36:37], v[210:211], v[0:1]
	v_add_f32_e32 v0, v0, v1
	v_ashrrev_i32_e32 v1, 31, v0
	v_mfma_f32_32x32x16_bf16 v[6:21], v[98:101], v[196:199], v[6:21]
	s_waitcnt vmcnt(10)
	ds_read_b128 v[38:41], v5 offset:10496
	ds_read_b128 v[42:45], v52 offset:10496
	ds_read_b128 v[46:49], v55 offset:10496
	ds_read_b128 v[196:199], v56 offset:10496
	v_or_b32_e32 v1, 0x80000000, v1
	s_cmpk_gt_i32 s11, 472
	s_cselect_b64 vcc, -1, 0
	v_xor_b32_e32 v0, v1, v0
	v_cndmask_b32_e32 v191, v123, v0, vcc
	s_nop 3
	s_waitcnt lgkmcnt(3)
	v_mfma_f32_32x32x16_bf16 v[212:227], v[70:73], v[38:41], 0
	v_max_f32_e32 v108, 0, v6
	v_max_f32_e32 v109, 0, v7
	v_pk_mul_f32 v[50:51], v[244:245], v[108:109]
	v_max_f32_e32 v210, 0, v8
	v_max_f32_e32 v211, 0, v9
	v_pk_fma_f32 v[50:51], v[246:247], v[210:211], v[50:51]
	v_max_f32_e32 v108, 0, v10
	v_max_f32_e32 v109, 0, v11
	v_pk_fma_f32 v[50:51], v[248:249], v[108:109], v[50:51]
	s_waitcnt lgkmcnt(2)
	v_mfma_f32_32x32x16_bf16 v[212:227], v[74:77], v[42:45], v[212:227]
	v_max_f32_e32 v210, 0, v12
	v_max_f32_e32 v211, 0, v13
	v_pk_fma_f32 v[50:51], v[250:251], v[210:211], v[50:51]
	v_max_f32_e32 v108, 0, v14
	v_max_f32_e32 v109, 0, v15
	v_pk_fma_f32 v[50:51], v[252:253], v[108:109], v[50:51]
	v_max_f32_e32 v210, 0, v16
	v_max_f32_e32 v211, 0, v17
	v_pk_fma_f32 v[50:51], v[254:255], v[210:211], v[50:51]
	s_waitcnt lgkmcnt(1)
	v_mfma_f32_32x32x16_bf16 v[212:227], v[78:81], v[46:49], v[212:227]
	v_max_f32_e32 v108, 0, v18
	v_max_f32_e32 v109, 0, v19
	v_pk_fma_f32 v[50:51], v[200:201], v[108:109], v[50:51]
	v_max_f32_e32 v210, 0, v20
	v_max_f32_e32 v211, 0, v21
	v_pk_fma_f32 v[50:51], v[202:203], v[210:211], v[50:51]
	v_add_f32_e32 v50, v50, v51
	v_ashrrev_i32_e32 v51, 31, v50
	s_waitcnt lgkmcnt(0)
	v_mfma_f32_32x32x16_bf16 v[212:227], v[82:85], v[196:199], v[212:227]
	v_or_b32_e32 v51, 0x80000000, v51
	s_cmpk_gt_i32 s11, 472
	s_cselect_b64 vcc, -1, 0
	v_xor_b32_e32 v50, v51, v50
	v_cndmask_b32_e32 v50, v123, v50, vcc
	global_store_dword v243, v50, s[8:9] offset:2048
	s_add_u32 s8, s8, 0x1000
	s_addc_u32 s9, s9, 0
	v_mfma_f32_32x32x16_bf16 v[6:21], v[86:89], v[38:41], 0
	s_add_i32 m0, s10, 98304
	s_nop 0
	global_load_lds_dwordx4 v102, s[6:7]
	s_add_i32 m0, s10, 99328
	s_nop 0
	global_load_lds_dwordx4 v110, s[6:7]
	s_add_i32 m0, s10, 100352
	s_nop 0
	global_load_lds_dwordx4 v112, s[6:7]
	s_add_i32 m0, s10, 101376
	s_nop 0
	global_load_lds_dwordx4 v193, s[6:7]
	s_add_u32 s6, s6, 0x8000
	s_addc_u32 s7, s7, 0
	v_max_f32_e32 v108, 0, v212
	v_max_f32_e32 v109, 0, v213
	v_pk_mul_f32 v[0:1], v[22:23], v[108:109]
	v_max_f32_e32 v210, 0, v214
	v_max_f32_e32 v211, 0, v215
	v_pk_fma_f32 v[0:1], v[24:25], v[210:211], v[0:1]
	v_max_f32_e32 v108, 0, v216
	v_max_f32_e32 v109, 0, v217
	v_pk_fma_f32 v[0:1], v[26:27], v[108:109], v[0:1]
	v_mfma_f32_32x32x16_bf16 v[6:21], v[90:93], v[42:45], v[6:21]
	v_max_f32_e32 v210, 0, v218
	v_max_f32_e32 v211, 0, v219
	v_pk_fma_f32 v[0:1], v[28:29], v[210:211], v[0:1]
	v_max_f32_e32 v108, 0, v220
	v_max_f32_e32 v109, 0, v221
	v_pk_fma_f32 v[0:1], v[30:31], v[108:109], v[0:1]
	v_max_f32_e32 v210, 0, v222
	v_max_f32_e32 v211, 0, v223
	v_pk_fma_f32 v[0:1], v[32:33], v[210:211], v[0:1]
	v_mfma_f32_32x32x16_bf16 v[6:21], v[94:97], v[46:49], v[6:21]
	v_max_f32_e32 v108, 0, v224
	v_max_f32_e32 v109, 0, v225
	v_pk_fma_f32 v[0:1], v[34:35], v[108:109], v[0:1]
	v_max_f32_e32 v210, 0, v226
	v_max_f32_e32 v211, 0, v227
	v_pk_fma_f32 v[0:1], v[36:37], v[210:211], v[0:1]
	v_add_f32_e32 v0, v0, v1
	v_ashrrev_i32_e32 v1, 31, v0
	v_mfma_f32_32x32x16_bf16 v[6:21], v[98:101], v[196:199], v[6:21]
	s_waitcnt vmcnt(10)
	ds_read_b128 v[38:41], v5 offset:43264
	ds_read_b128 v[42:45], v52 offset:43264
	ds_read_b128 v[46:49], v55 offset:43264
	ds_read_b128 v[196:199], v56 offset:43264
	v_or_b32_e32 v1, 0x80000000, v1
	s_cmpk_gt_i32 s11, 480
	s_cselect_b64 vcc, -1, 0
	v_xor_b32_e32 v0, v1, v0
	v_cndmask_b32_e32 v3, v123, v0, vcc
	s_nop 3
	s_waitcnt lgkmcnt(3)
	v_mfma_f32_32x32x16_bf16 v[212:227], v[70:73], v[38:41], 0
	v_max_f32_e32 v108, 0, v6
	v_max_f32_e32 v109, 0, v7
	v_pk_mul_f32 v[50:51], v[244:245], v[108:109]
	v_max_f32_e32 v210, 0, v8
	v_max_f32_e32 v211, 0, v9
	v_pk_fma_f32 v[50:51], v[246:247], v[210:211], v[50:51]
	v_max_f32_e32 v108, 0, v10
	v_max_f32_e32 v109, 0, v11
	v_pk_fma_f32 v[50:51], v[248:249], v[108:109], v[50:51]
	s_waitcnt lgkmcnt(2)
	v_mfma_f32_32x32x16_bf16 v[212:227], v[74:77], v[42:45], v[212:227]
	v_max_f32_e32 v210, 0, v12
	v_max_f32_e32 v211, 0, v13
	v_pk_fma_f32 v[50:51], v[250:251], v[210:211], v[50:51]
	v_max_f32_e32 v108, 0, v14
	v_max_f32_e32 v109, 0, v15
	v_pk_fma_f32 v[50:51], v[252:253], v[108:109], v[50:51]
	v_max_f32_e32 v210, 0, v16
	v_max_f32_e32 v211, 0, v17
	v_pk_fma_f32 v[50:51], v[254:255], v[210:211], v[50:51]
	s_waitcnt lgkmcnt(1)
	v_mfma_f32_32x32x16_bf16 v[212:227], v[78:81], v[46:49], v[212:227]
	v_max_f32_e32 v108, 0, v18
	v_max_f32_e32 v109, 0, v19
	v_pk_fma_f32 v[50:51], v[200:201], v[108:109], v[50:51]
	v_max_f32_e32 v210, 0, v20
	v_max_f32_e32 v211, 0, v21
	v_pk_fma_f32 v[50:51], v[202:203], v[210:211], v[50:51]
	v_add_f32_e32 v50, v50, v51
	v_ashrrev_i32_e32 v51, 31, v50
	s_waitcnt lgkmcnt(0)
	v_mfma_f32_32x32x16_bf16 v[212:227], v[82:85], v[196:199], v[212:227]
	v_or_b32_e32 v51, 0x80000000, v51
	s_cmpk_gt_i32 s11, 480
	s_cselect_b64 vcc, -1, 0
	v_xor_b32_e32 v50, v51, v50
	v_cndmask_b32_e32 v50, v123, v50, vcc
	global_store_dword v243, v50, s[8:9]
	v_mfma_f32_32x32x16_bf16 v[6:21], v[86:89], v[38:41], 0
	s_add_i32 m0, s10, 0
	s_nop 0
	global_load_lds_dwordx4 v102, s[6:7]
	s_add_i32 m0, s10, 1024
	s_nop 0
	global_load_lds_dwordx4 v110, s[6:7]
	s_add_i32 m0, s10, 2048
	s_nop 0
	global_load_lds_dwordx4 v112, s[6:7]
	s_add_i32 m0, s10, 3072
	s_nop 0
	global_load_lds_dwordx4 v193, s[6:7]
	s_add_u32 s6, s6, 0x8000
	s_addc_u32 s7, s7, 0
	v_max_f32_e32 v108, 0, v212
	v_max_f32_e32 v109, 0, v213
	v_pk_mul_f32 v[0:1], v[22:23], v[108:109]
	v_max_f32_e32 v210, 0, v214
	v_max_f32_e32 v211, 0, v215
	v_pk_fma_f32 v[0:1], v[24:25], v[210:211], v[0:1]
	v_max_f32_e32 v108, 0, v216
	v_max_f32_e32 v109, 0, v217
	v_pk_fma_f32 v[0:1], v[26:27], v[108:109], v[0:1]
	v_mfma_f32_32x32x16_bf16 v[6:21], v[90:93], v[42:45], v[6:21]
	v_max_f32_e32 v210, 0, v218
	v_max_f32_e32 v211, 0, v219
	v_pk_fma_f32 v[0:1], v[28:29], v[210:211], v[0:1]
	v_max_f32_e32 v108, 0, v220
	v_max_f32_e32 v109, 0, v221
	v_pk_fma_f32 v[0:1], v[30:31], v[108:109], v[0:1]
	v_max_f32_e32 v210, 0, v222
	v_max_f32_e32 v211, 0, v223
	v_pk_fma_f32 v[0:1], v[32:33], v[210:211], v[0:1]
	v_mfma_f32_32x32x16_bf16 v[6:21], v[94:97], v[46:49], v[6:21]
	v_max_f32_e32 v108, 0, v224
	v_max_f32_e32 v109, 0, v225
	v_pk_fma_f32 v[0:1], v[34:35], v[108:109], v[0:1]
	v_max_f32_e32 v210, 0, v226
	v_max_f32_e32 v211, 0, v227
	v_pk_fma_f32 v[0:1], v[36:37], v[210:211], v[0:1]
	v_add_f32_e32 v0, v0, v1
	v_ashrrev_i32_e32 v1, 31, v0
	v_mfma_f32_32x32x16_bf16 v[6:21], v[98:101], v[196:199], v[6:21]
	s_waitcnt vmcnt(10)
	v_add_u32_e32 v228, 0x10000, v5
	ds_read_b128 v[38:41], v228 offset:10496
	v_add_u32_e32 v228, 0x10000, v52
	ds_read_b128 v[42:45], v228 offset:10496
	v_add_u32_e32 v228, 0x10000, v55
	ds_read_b128 v[46:49], v228 offset:10496
	v_add_u32_e32 v228, 0x10000, v56
	ds_read_b128 v[196:199], v228 offset:10496
	v_or_b32_e32 v1, 0x80000000, v1
	s_cmpk_gt_i32 s11, 488
	s_cselect_b64 vcc, -1, 0
	v_xor_b32_e32 v0, v1, v0
	v_cndmask_b32_e32 v2, v123, v0, vcc
	s_nop 3
	s_waitcnt lgkmcnt(3)
	v_mfma_f32_32x32x16_bf16 v[212:227], v[70:73], v[38:41], 0
	v_max_f32_e32 v108, 0, v6
	v_max_f32_e32 v109, 0, v7
	v_pk_mul_f32 v[50:51], v[244:245], v[108:109]
	v_max_f32_e32 v210, 0, v8
	v_max_f32_e32 v211, 0, v9
	v_pk_fma_f32 v[50:51], v[246:247], v[210:211], v[50:51]
	v_max_f32_e32 v108, 0, v10
	v_max_f32_e32 v109, 0, v11
	v_pk_fma_f32 v[50:51], v[248:249], v[108:109], v[50:51]
	s_waitcnt lgkmcnt(2)
	v_mfma_f32_32x32x16_bf16 v[212:227], v[74:77], v[42:45], v[212:227]
	v_max_f32_e32 v210, 0, v12
	v_max_f32_e32 v211, 0, v13
	v_pk_fma_f32 v[50:51], v[250:251], v[210:211], v[50:51]
	v_max_f32_e32 v108, 0, v14
	v_max_f32_e32 v109, 0, v15
	v_pk_fma_f32 v[50:51], v[252:253], v[108:109], v[50:51]
	v_max_f32_e32 v210, 0, v16
	v_max_f32_e32 v211, 0, v17
	v_pk_fma_f32 v[50:51], v[254:255], v[210:211], v[50:51]
	s_waitcnt lgkmcnt(1)
	v_mfma_f32_32x32x16_bf16 v[212:227], v[78:81], v[46:49], v[212:227]
	v_max_f32_e32 v108, 0, v18
	v_max_f32_e32 v109, 0, v19
	v_pk_fma_f32 v[50:51], v[200:201], v[108:109], v[50:51]
	v_max_f32_e32 v210, 0, v20
	v_max_f32_e32 v211, 0, v21
	v_pk_fma_f32 v[50:51], v[202:203], v[210:211], v[50:51]
	v_add_f32_e32 v50, v50, v51
	v_ashrrev_i32_e32 v51, 31, v50
	s_waitcnt lgkmcnt(0)
	v_mfma_f32_32x32x16_bf16 v[212:227], v[82:85], v[196:199], v[212:227]
	v_or_b32_e32 v51, 0x80000000, v51
	s_cmpk_gt_i32 s11, 488
	s_cselect_b64 vcc, -1, 0
	v_xor_b32_e32 v50, v51, v50
	v_cndmask_b32_e32 v50, v123, v50, vcc
	global_store_dword v243, v50, s[8:9] offset:2048
	s_add_u32 s8, s8, 0x1000
	s_addc_u32 s9, s9, 0
	v_mfma_f32_32x32x16_bf16 v[6:21], v[86:89], v[38:41], 0
	s_add_i32 m0, s10, 32768
	s_nop 0
	global_load_lds_dwordx4 v102, s[6:7]
	s_add_i32 m0, s10, 33792
	s_nop 0
	global_load_lds_dwordx4 v110, s[6:7]
	s_add_i32 m0, s10, 34816
	s_nop 0
	global_load_lds_dwordx4 v112, s[6:7]
	s_add_i32 m0, s10, 35840
	s_nop 0
	global_load_lds_dwordx4 v193, s[6:7]
	s_add_u32 s6, s6, 0x8000
	s_addc_u32 s7, s7, 0
	v_max_f32_e32 v108, 0, v212
	v_max_f32_e32 v109, 0, v213
	v_pk_mul_f32 v[0:1], v[22:23], v[108:109]
	v_max_f32_e32 v210, 0, v214
	v_max_f32_e32 v211, 0, v215
	v_pk_fma_f32 v[0:1], v[24:25], v[210:211], v[0:1]
	v_max_f32_e32 v108, 0, v216
	v_max_f32_e32 v109, 0, v217
	v_pk_fma_f32 v[0:1], v[26:27], v[108:109], v[0:1]
	v_mfma_f32_32x32x16_bf16 v[6:21], v[90:93], v[42:45], v[6:21]
	v_max_f32_e32 v210, 0, v218
	v_max_f32_e32 v211, 0, v219
	v_pk_fma_f32 v[0:1], v[28:29], v[210:211], v[0:1]
	v_max_f32_e32 v108, 0, v220
	v_max_f32_e32 v109, 0, v221
	v_pk_fma_f32 v[0:1], v[30:31], v[108:109], v[0:1]
	v_max_f32_e32 v210, 0, v222
	v_max_f32_e32 v211, 0, v223
	v_pk_fma_f32 v[0:1], v[32:33], v[210:211], v[0:1]
	v_mfma_f32_32x32x16_bf16 v[6:21], v[94:97], v[46:49], v[6:21]
	v_max_f32_e32 v108, 0, v224
	v_max_f32_e32 v109, 0, v225
	v_pk_fma_f32 v[0:1], v[34:35], v[108:109], v[0:1]
	v_max_f32_e32 v210, 0, v226
	v_max_f32_e32 v211, 0, v227
	v_pk_fma_f32 v[0:1], v[36:37], v[210:211], v[0:1]
	v_add_f32_e32 v0, v0, v1
	v_ashrrev_i32_e32 v1, 31, v0
	v_mfma_f32_32x32x16_bf16 v[6:21], v[98:101], v[196:199], v[6:21]
	s_waitcnt vmcnt(10)
	v_add_u32_e32 v228, 0x10000, v5
	ds_read_b128 v[38:41], v228 offset:43264
	v_add_u32_e32 v228, 0x10000, v52
	ds_read_b128 v[42:45], v228 offset:43264
	v_add_u32_e32 v228, 0x10000, v55
	ds_read_b128 v[46:49], v228 offset:43264
	v_add_u32_e32 v228, 0x10000, v56
	ds_read_b128 v[196:199], v228 offset:43264
	v_or_b32_e32 v1, 0x80000000, v1
	s_cmpk_gt_i32 s11, 496
	s_cselect_b64 vcc, -1, 0
	v_xor_b32_e32 v0, v1, v0
	v_cndmask_b32_e32 v4, v123, v0, vcc
	s_nop 3
	s_waitcnt lgkmcnt(3)
	v_mfma_f32_32x32x16_bf16 v[212:227], v[70:73], v[38:41], 0
	v_max_f32_e32 v108, 0, v6
	v_max_f32_e32 v109, 0, v7
	v_pk_mul_f32 v[50:51], v[244:245], v[108:109]
	v_max_f32_e32 v210, 0, v8
	v_max_f32_e32 v211, 0, v9
	v_pk_fma_f32 v[50:51], v[246:247], v[210:211], v[50:51]
	v_max_f32_e32 v108, 0, v10
	v_max_f32_e32 v109, 0, v11
	v_pk_fma_f32 v[50:51], v[248:249], v[108:109], v[50:51]
	s_waitcnt lgkmcnt(2)
	v_mfma_f32_32x32x16_bf16 v[212:227], v[74:77], v[42:45], v[212:227]
	v_max_f32_e32 v210, 0, v12
	v_max_f32_e32 v211, 0, v13
	v_pk_fma_f32 v[50:51], v[250:251], v[210:211], v[50:51]
	v_max_f32_e32 v108, 0, v14
	v_max_f32_e32 v109, 0, v15
	v_pk_fma_f32 v[50:51], v[252:253], v[108:109], v[50:51]
	v_max_f32_e32 v210, 0, v16
	v_max_f32_e32 v211, 0, v17
	v_pk_fma_f32 v[50:51], v[254:255], v[210:211], v[50:51]
	s_waitcnt lgkmcnt(1)
	v_mfma_f32_32x32x16_bf16 v[212:227], v[78:81], v[46:49], v[212:227]
	v_max_f32_e32 v108, 0, v18
	v_max_f32_e32 v109, 0, v19
	v_pk_fma_f32 v[50:51], v[200:201], v[108:109], v[50:51]
	v_max_f32_e32 v210, 0, v20
	v_max_f32_e32 v211, 0, v21
	v_pk_fma_f32 v[50:51], v[202:203], v[210:211], v[50:51]
	v_add_f32_e32 v50, v50, v51
	v_ashrrev_i32_e32 v51, 31, v50
	s_waitcnt lgkmcnt(0)
	v_mfma_f32_32x32x16_bf16 v[212:227], v[82:85], v[196:199], v[212:227]
	v_or_b32_e32 v51, 0x80000000, v51
	s_cmpk_gt_i32 s11, 496
	s_cselect_b64 vcc, -1, 0
	v_xor_b32_e32 v50, v51, v50
	v_cndmask_b32_e32 v50, v123, v50, vcc
	global_store_dword v243, v50, s[8:9]
	v_mfma_f32_32x32x16_bf16 v[6:21], v[86:89], v[38:41], 0
	s_add_i32 m0, s10, 65536
	s_nop 0
	global_load_lds_dwordx4 v102, s[6:7]
	s_add_i32 m0, s10, 66560
	s_nop 0
	global_load_lds_dwordx4 v110, s[6:7]
	s_add_i32 m0, s10, 67584
	s_nop 0
	global_load_lds_dwordx4 v112, s[6:7]
	s_add_i32 m0, s10, 68608
	s_nop 0
	global_load_lds_dwordx4 v193, s[6:7]
	s_add_u32 s6, s6, 0x8000
	s_addc_u32 s7, s7, 0
	v_max_f32_e32 v108, 0, v212
	v_max_f32_e32 v109, 0, v213
	v_pk_mul_f32 v[0:1], v[22:23], v[108:109]
	v_max_f32_e32 v210, 0, v214
	v_max_f32_e32 v211, 0, v215
	v_pk_fma_f32 v[0:1], v[24:25], v[210:211], v[0:1]
	v_max_f32_e32 v108, 0, v216
	v_max_f32_e32 v109, 0, v217
	v_pk_fma_f32 v[0:1], v[26:27], v[108:109], v[0:1]
	v_mfma_f32_32x32x16_bf16 v[6:21], v[90:93], v[42:45], v[6:21]
	v_max_f32_e32 v210, 0, v218
	v_max_f32_e32 v211, 0, v219
	v_pk_fma_f32 v[0:1], v[28:29], v[210:211], v[0:1]
	v_max_f32_e32 v108, 0, v220
	v_max_f32_e32 v109, 0, v221
	v_pk_fma_f32 v[0:1], v[30:31], v[108:109], v[0:1]
	v_max_f32_e32 v210, 0, v222
	v_max_f32_e32 v211, 0, v223
	v_pk_fma_f32 v[0:1], v[32:33], v[210:211], v[0:1]
	v_mfma_f32_32x32x16_bf16 v[6:21], v[94:97], v[46:49], v[6:21]
	v_max_f32_e32 v108, 0, v224
	v_max_f32_e32 v109, 0, v225
	v_pk_fma_f32 v[0:1], v[34:35], v[108:109], v[0:1]
	v_max_f32_e32 v210, 0, v226
	v_max_f32_e32 v211, 0, v227
	v_pk_fma_f32 v[0:1], v[36:37], v[210:211], v[0:1]
	v_add_f32_e32 v0, v0, v1
	v_ashrrev_i32_e32 v1, 31, v0
	v_mfma_f32_32x32x16_bf16 v[6:21], v[98:101], v[196:199], v[6:21]
	s_waitcnt vmcnt(10)
	ds_read_b128 v[38:41], v5 offset:10496
	ds_read_b128 v[42:45], v52 offset:10496
	ds_read_b128 v[46:49], v55 offset:10496
	ds_read_b128 v[196:199], v56 offset:10496
	v_or_b32_e32 v1, 0x80000000, v1
	s_cmpk_gt_i32 s11, 504
	s_cselect_b64 vcc, -1, 0
	v_xor_b32_e32 v0, v1, v0
	v_cndmask_b32_e32 v185, v123, v0, vcc
	s_nop 3
	v_max_f32_e32 v108, 0, v6
	v_max_f32_e32 v109, 0, v7
	v_pk_mul_f32 v[50:51], v[244:245], v[108:109]
	v_max_f32_e32 v210, 0, v8
	v_max_f32_e32 v211, 0, v9
	v_pk_fma_f32 v[50:51], v[246:247], v[210:211], v[50:51]
	v_max_f32_e32 v108, 0, v10
	v_max_f32_e32 v109, 0, v11
	v_pk_fma_f32 v[50:51], v[248:249], v[108:109], v[50:51]
	v_max_f32_e32 v210, 0, v12
	v_max_f32_e32 v211, 0, v13
	v_pk_fma_f32 v[50:51], v[250:251], v[210:211], v[50:51]
	v_max_f32_e32 v108, 0, v14
	v_max_f32_e32 v109, 0, v15
	v_pk_fma_f32 v[50:51], v[252:253], v[108:109], v[50:51]
	v_max_f32_e32 v210, 0, v16
	v_max_f32_e32 v211, 0, v17
	v_pk_fma_f32 v[50:51], v[254:255], v[210:211], v[50:51]
	v_max_f32_e32 v108, 0, v18
	v_max_f32_e32 v109, 0, v19
	v_pk_fma_f32 v[50:51], v[200:201], v[108:109], v[50:51]
	v_max_f32_e32 v210, 0, v20
	v_max_f32_e32 v211, 0, v21
	v_pk_fma_f32 v[50:51], v[202:203], v[210:211], v[50:51]
	v_add_f32_e32 v50, v50, v51
	v_ashrrev_i32_e32 v51, 31, v50
	v_or_b32_e32 v51, 0x80000000, v51
	s_cmpk_gt_i32 s11, 504
	s_cselect_b64 vcc, -1, 0
	v_xor_b32_e32 v50, v51, v50
	v_cndmask_b32_e32 v50, v123, v50, vcc
	global_store_dword v243, v50, s[8:9] offset:2048
	s_add_u32 s8, s8, 0x1000
	s_addc_u32 s9, s9, 0
	s_branch .Lix_done

.Lix_reload:
	s_cmp_eq_u32 s100, 1
	s_cbranch_scc1 .Lix_pre_done
	global_load_dword v133, v243, s[8:9] sc1
	global_load_dword v132, v243, s[8:9] offset:2048 sc1
	s_add_u32 s8, s8, 0x1000
	s_addc_u32 s9, s9, 0
	global_load_dword v135, v243, s[8:9] sc1
	global_load_dword v134, v243, s[8:9] offset:2048 sc1
	s_add_u32 s8, s8, 0x1000
	s_addc_u32 s9, s9, 0
	global_load_dword v138, v243, s[8:9] sc1
	global_load_dword v137, v243, s[8:9] offset:2048 sc1
	s_add_u32 s8, s8, 0x1000
	s_addc_u32 s9, s9, 0
	global_load_dword v140, v243, s[8:9] sc1
	global_load_dword v139, v243, s[8:9] offset:2048 sc1
	s_add_u32 s8, s8, 0x1000
	s_addc_u32 s9, s9, 0
	s_cmpk_gt_i32 s81, 8
	s_cbranch_scc0 .Lix_rfill_1
	global_load_dword v142, v243, s[8:9] sc1
	global_load_dword v141, v243, s[8:9] offset:2048 sc1
	s_add_u32 s8, s8, 0x1000
	s_addc_u32 s9, s9, 0
	global_load_dword v144, v243, s[8:9] sc1
	global_load_dword v143, v243, s[8:9] offset:2048 sc1
	s_add_u32 s8, s8, 0x1000
	s_addc_u32 s9, s9, 0
	global_load_dword v146, v243, s[8:9] sc1
	global_load_dword v145, v243, s[8:9] offset:2048 sc1
	s_add_u32 s8, s8, 0x1000
	s_addc_u32 s9, s9, 0
	global_load_dword v147, v243, s[8:9] sc1
	global_load_dword v136, v243, s[8:9] offset:2048 sc1
	s_add_u32 s8, s8, 0x1000
	s_addc_u32 s9, s9, 0
	s_cmpk_gt_i32 s81, 16
	s_cbranch_scc0 .Lix_rfill_2
	global_load_dword v149, v243, s[8:9] sc1
	global_load_dword v148, v243, s[8:9] offset:2048 sc1
	s_add_u32 s8, s8, 0x1000
	s_addc_u32 s9, s9, 0
	global_load_dword v151, v243, s[8:9] sc1
	global_load_dword v150, v243, s[8:9] offset:2048 sc1
	s_add_u32 s8, s8, 0x1000
	s_addc_u32 s9, s9, 0
	global_load_dword v154, v243, s[8:9] sc1
	global_load_dword v153, v243, s[8:9] offset:2048 sc1
	s_add_u32 s8, s8, 0x1000
	s_addc_u32 s9, s9, 0
	global_load_dword v156, v243, s[8:9] sc1
	global_load_dword v155, v243, s[8:9] offset:2048 sc1
	s_add_u32 s8, s8, 0x1000
	s_addc_u32 s9, s9, 0
	s_cmpk_gt_i32 s81, 24
	s_cbranch_scc0 .Lix_rfill_3
	global_load_dword v158, v243, s[8:9] sc1
	global_load_dword v157, v243, s[8:9] offset:2048 sc1
	s_add_u32 s8, s8, 0x1000
	s_addc_u32 s9, s9, 0
	global_load_dword v160, v243, s[8:9] sc1
	global_load_dword v159, v243, s[8:9] offset:2048 sc1
	s_add_u32 s8, s8, 0x1000
	s_addc_u32 s9, s9, 0
	global_load_dword v162, v243, s[8:9] sc1
	global_load_dword v161, v243, s[8:9] offset:2048 sc1
	s_add_u32 s8, s8, 0x1000
	s_addc_u32 s9, s9, 0
	global_load_dword v163, v243, s[8:9] sc1
	global_load_dword v152, v243, s[8:9] offset:2048 sc1
	s_add_u32 s8, s8, 0x1000
	s_addc_u32 s9, s9, 0
	s_cmpk_gt_i32 s81, 32
	s_cbranch_scc0 .Lix_rfill_4
	global_load_dword v165, v243, s[8:9] sc1
	global_load_dword v164, v243, s[8:9] offset:2048 sc1
	s_add_u32 s8, s8, 0x1000
	s_addc_u32 s9, s9, 0
	global_load_dword v167, v243, s[8:9] sc1
	global_load_dword v166, v243, s[8:9] offset:2048 sc1
	s_add_u32 s8, s8, 0x1000
	s_addc_u32 s9, s9, 0
	global_load_dword v170, v243, s[8:9] sc1
	global_load_dword v169, v243, s[8:9] offset:2048 sc1
	s_add_u32 s8, s8, 0x1000
	s_addc_u32 s9, s9, 0
	global_load_dword v172, v243, s[8:9] sc1
	global_load_dword v171, v243, s[8:9] offset:2048 sc1
	s_add_u32 s8, s8, 0x1000
	s_addc_u32 s9, s9, 0
	s_cmpk_gt_i32 s81, 40
	s_cbranch_scc0 .Lix_rfill_5
	global_load_dword v174, v243, s[8:9] sc1
	global_load_dword v173, v243, s[8:9] offset:2048 sc1
	s_add_u32 s8, s8, 0x1000
	s_addc_u32 s9, s9, 0
	global_load_dword v176, v243, s[8:9] sc1
	global_load_dword v175, v243, s[8:9] offset:2048 sc1
	s_add_u32 s8, s8, 0x1000
	s_addc_u32 s9, s9, 0
	global_load_dword v178, v243, s[8:9] sc1
	global_load_dword v177, v243, s[8:9] offset:2048 sc1
	s_add_u32 s8, s8, 0x1000
	s_addc_u32 s9, s9, 0
	global_load_dword v179, v243, s[8:9] sc1
	global_load_dword v168, v243, s[8:9] offset:2048 sc1
	s_add_u32 s8, s8, 0x1000
	s_addc_u32 s9, s9, 0
	s_cmpk_gt_i32 s81, 48
	s_cbranch_scc0 .Lix_rfill_6
	global_load_dword v182, v243, s[8:9] sc1
	global_load_dword v181, v243, s[8:9] offset:2048 sc1
	s_add_u32 s8, s8, 0x1000
	s_addc_u32 s9, s9, 0
	global_load_dword v184, v243, s[8:9] sc1
	global_load_dword v183, v243, s[8:9] offset:2048 sc1
	s_add_u32 s8, s8, 0x1000
	s_addc_u32 s9, s9, 0
	global_load_dword v187, v243, s[8:9] sc1
	global_load_dword v186, v243, s[8:9] offset:2048 sc1
	s_add_u32 s8, s8, 0x1000
	s_addc_u32 s9, s9, 0
	global_load_dword v189, v243, s[8:9] sc1
	global_load_dword v188, v243, s[8:9] offset:2048 sc1
	s_add_u32 s8, s8, 0x1000
	s_addc_u32 s9, s9, 0
	s_cmpk_gt_i32 s81, 56
	s_cbranch_scc0 .Lix_rfill_7
	global_load_dword v190, v243, s[8:9] sc1
	global_load_dword v53, v243, s[8:9] offset:2048 sc1
	s_add_u32 s8, s8, 0x1000
	s_addc_u32 s9, s9, 0
	global_load_dword v192, v243, s[8:9] sc1
	global_load_dword v191, v243, s[8:9] offset:2048 sc1
	s_add_u32 s8, s8, 0x1000
	s_addc_u32 s9, s9, 0
	global_load_dword v3, v243, s[8:9] sc1
	global_load_dword v2, v243, s[8:9] offset:2048 sc1
	s_add_u32 s8, s8, 0x1000
	s_addc_u32 s9, s9, 0
	global_load_dword v4, v243, s[8:9] sc1
	global_load_dword v185, v243, s[8:9] offset:2048 sc1
	s_add_u32 s8, s8, 0x1000
	s_addc_u32 s9, s9, 0
	s_branch .Lix_rdone

.Lix_rfill_7:
	v_mov_b32_e32 v190, v123
	v_mov_b32_e32 v53, v123
	v_mov_b32_e32 v192, v123
	v_mov_b32_e32 v191, v123
	v_mov_b32_e32 v3, v123
	v_mov_b32_e32 v2, v123
	v_mov_b32_e32 v4, v123
	v_mov_b32_e32 v185, v123
.Lix_rdone:
	s_branch .Lix_done
.Lix_pre_done:
	s_cmpk_gt_i32 s81, 8
	s_cbranch_scc0 .Lix_rfill_1
	s_cmpk_gt_i32 s81, 16
	s_cbranch_scc0 .Lix_rfill_2
	s_cmpk_gt_i32 s81, 24
	s_cbranch_scc0 .Lix_rfill_3
	s_cmpk_gt_i32 s81, 32
	s_cbranch_scc0 .Lix_rfill_4
	s_cmpk_gt_i32 s81, 40
	s_cbranch_scc0 .Lix_rfill_5
	s_cmpk_gt_i32 s81, 48
	s_cbranch_scc0 .Lix_rfill_6
	s_cmpk_gt_i32 s81, 56
	s_cbranch_scc0 .Lix_rfill_7
	s_waitcnt vmcnt(0)
	v_mov_b32_e32 v3, v244
	v_mov_b32_e32 v2, v245
	v_mov_b32_e32 v4, v246

.LBB0_1337:
	s_or_b64 exec, exec, s[0:1]
	s_ashr_i32 s85, s83, 8
	s_cmpk_lt_u32 s83, 0x100
	s_cselect_b64 vcc, -1, 0
	s_lshl_b32 s0, s85, 13
	v_and_b32_e32 v9, 0xff, v129
	v_cndmask_b32_e32 v1, v105, v104, vcc
	s_add_i32 s0, s0, 0
	v_cmp_lt_i32_e32 vcc, v9, v1
	v_mov_b32_e32 v16, 0
	v_lshl_add_u32 v0, v9, 2, s0
	v_mov_b32_e32 v17, 0
	s_waitcnt vmcnt(0) lgkmcnt(0)
	s_barrier
	s_cmp_lg_u32 s82, 0
	s_cbranch_scc1 .Lpf_skip
	s_lshl_b32 s90, s2, 17
	s_lshl_b32 s91, s84, 8
	s_add_u32 s90, s90, s91
	s_add_u32 s90, s28, s90
	s_addc_u32 s91, s29, 0
	global_load_dword v133, v243, s[90:91] sc1
	global_load_dword v132, v243, s[90:91] offset:2048 sc1
	s_add_u32 s90, s90, 0x1000
	s_addc_u32 s91, s91, 0
	global_load_dword v135, v243, s[90:91] sc1
	global_load_dword v134, v243, s[90:91] offset:2048 sc1
	s_add_u32 s90, s90, 0x1000
	s_addc_u32 s91, s91, 0
	global_load_dword v138, v243, s[90:91] sc1
	global_load_dword v137, v243, s[90:91] offset:2048 sc1
	s_add_u32 s90, s90, 0x1000
	s_addc_u32 s91, s91, 0
	global_load_dword v140, v243, s[90:91] sc1
	global_load_dword v139, v243, s[90:91] offset:2048 sc1
	s_add_u32 s90, s90, 0x1000
	s_addc_u32 s91, s91, 0
	s_cmpk_gt_i32 s81, 8
	s_cbranch_scc0 .Lpf_end
	global_load_dword v142, v243, s[90:91] sc1
	global_load_dword v141, v243, s[90:91] offset:2048 sc1
	s_add_u32 s90, s90, 0x1000
	s_addc_u32 s91, s91, 0
	global_load_dword v144, v243, s[90:91] sc1
	global_load_dword v143, v243, s[90:91] offset:2048 sc1
	s_add_u32 s90, s90, 0x1000
	s_addc_u32 s91, s91, 0
	global_load_dword v146, v243, s[90:91] sc1
	global_load_dword v145, v243, s[90:91] offset:2048 sc1
	s_add_u32 s90, s90, 0x1000
	s_addc_u32 s91, s91, 0
	global_load_dword v147, v243, s[90:91] sc1
	global_load_dword v136, v243, s[90:91] offset:2048 sc1
	s_add_u32 s90, s90, 0x1000
	s_addc_u32 s91, s91, 0
	s_cmpk_gt_i32 s81, 16
	s_cbranch_scc0 .Lpf_end
	global_load_dword v149, v243, s[90:91] sc1
	global_load_dword v148, v243, s[90:91] offset:2048 sc1
	s_add_u32 s90, s90, 0x1000
	s_addc_u32 s91, s91, 0
	global_load_dword v151, v243, s[90:91] sc1
	global_load_dword v150, v243, s[90:91] offset:2048 sc1
	s_add_u32 s90, s90, 0x1000
	s_addc_u32 s91, s91, 0
	global_load_dword v154, v243, s[90:91] sc1
	global_load_dword v153, v243, s[90:91] offset:2048 sc1
	s_add_u32 s90, s90, 0x1000
	s_addc_u32 s91, s91, 0
	global_load_dword v156, v243, s[90:91] sc1
	global_load_dword v155, v243, s[90:91] offset:2048 sc1
	s_add_u32 s90, s90, 0x1000
	s_addc_u32 s91, s91, 0
	s_cmpk_gt_i32 s81, 24
	s_cbranch_scc0 .Lpf_end
	global_load_dword v158, v243, s[90:91] sc1
	global_load_dword v157, v243, s[90:91] offset:2048 sc1
	s_add_u32 s90, s90, 0x1000
	s_addc_u32 s91, s91, 0
	global_load_dword v160, v243, s[90:91] sc1
	global_load_dword v159, v243, s[90:91] offset:2048 sc1
	s_add_u32 s90, s90, 0x1000
	s_addc_u32 s91, s91, 0
	global_load_dword v162, v243, s[90:91] sc1
	global_load_dword v161, v243, s[90:91] offset:2048 sc1
	s_add_u32 s90, s90, 0x1000
	s_addc_u32 s91, s91, 0
	global_load_dword v163, v243, s[90:91] sc1
	global_load_dword v152, v243, s[90:91] offset:2048 sc1
	s_add_u32 s90, s90, 0x1000
	s_addc_u32 s91, s91, 0
	s_cmpk_gt_i32 s81, 32
	s_cbranch_scc0 .Lpf_end
	global_load_dword v165, v243, s[90:91] sc1
	global_load_dword v164, v243, s[90:91] offset:2048 sc1
	s_add_u32 s90, s90, 0x1000
	s_addc_u32 s91, s91, 0
	global_load_dword v167, v243, s[90:91] sc1
	global_load_dword v166, v243, s[90:91] offset:2048 sc1
	s_add_u32 s90, s90, 0x1000
	s_addc_u32 s91, s91, 0
	global_load_dword v170, v243, s[90:91] sc1
	global_load_dword v169, v243, s[90:91] offset:2048 sc1
	s_add_u32 s90, s90, 0x1000
	s_addc_u32 s91, s91, 0
	global_load_dword v172, v243, s[90:91] sc1
	global_load_dword v171, v243, s[90:91] offset:2048 sc1
	s_add_u32 s90, s90, 0x1000
	s_addc_u32 s91, s91, 0
	s_cmpk_gt_i32 s81, 40
	s_cbranch_scc0 .Lpf_end
	global_load_dword v174, v243, s[90:91] sc1
	global_load_dword v173, v243, s[90:91] offset:2048 sc1
	s_add_u32 s90, s90, 0x1000
	s_addc_u32 s91, s91, 0
	global_load_dword v176, v243, s[90:91] sc1
	global_load_dword v175, v243, s[90:91] offset:2048 sc1
	s_add_u32 s90, s90, 0x1000
	s_addc_u32 s91, s91, 0
	global_load_dword v178, v243, s[90:91] sc1
	global_load_dword v177, v243, s[90:91] offset:2048 sc1
	s_add_u32 s90, s90, 0x1000
	s_addc_u32 s91, s91, 0
	global_load_dword v179, v243, s[90:91] sc1
	global_load_dword v168, v243, s[90:91] offset:2048 sc1
	s_add_u32 s90, s90, 0x1000
	s_addc_u32 s91, s91, 0
	s_cmpk_gt_i32 s81, 48
	s_cbranch_scc0 .Lpf_end
	global_load_dword v182, v243, s[90:91] sc1
	global_load_dword v181, v243, s[90:91] offset:2048 sc1
	s_add_u32 s90, s90, 0x1000
	s_addc_u32 s91, s91, 0
	global_load_dword v184, v243, s[90:91] sc1
	global_load_dword v183, v243, s[90:91] offset:2048 sc1
	s_add_u32 s90, s90, 0x1000
	s_addc_u32 s91, s91, 0
	global_load_dword v187, v243, s[90:91] sc1
	global_load_dword v186, v243, s[90:91] offset:2048 sc1
	s_add_u32 s90, s90, 0x1000
	s_addc_u32 s91, s91, 0
	global_load_dword v189, v243, s[90:91] sc1
	global_load_dword v188, v243, s[90:91] offset:2048 sc1
	s_add_u32 s90, s90, 0x1000
	s_addc_u32 s91, s91, 0
	s_cmpk_gt_i32 s81, 56
	s_cbranch_scc0 .Lpf_end
	global_load_dword v190, v243, s[90:91] sc1
	global_load_dword v53, v243, s[90:91] offset:2048 sc1
	s_add_u32 s90, s90, 0x1000
	s_addc_u32 s91, s91, 0
	global_load_dword v192, v243, s[90:91] sc1
	global_load_dword v191, v243, s[90:91] offset:2048 sc1
	s_add_u32 s90, s90, 0x1000
	s_addc_u32 s91, s91, 0
	global_load_dword v244, v243, s[90:91] sc1
	global_load_dword v245, v243, s[90:91] offset:2048 sc1
	s_add_u32 s90, s90, 0x1000
	s_addc_u32 s91, s91, 0
	global_load_dword v246, v243, s[90:91] sc1
	global_load_dword v185, v243, s[90:91] offset:2048 sc1
	s_add_u32 s90, s90, 0x1000
	s_addc_u32 s91, s91, 0
.Lpf_end:
	s_mov_b32 s100, 1
.Lpf_skip:
	s_and_saveexec_b64 s[0:1], vcc
	ds_read_b32 v17, v0 offset:10496
	s_or_b64 exec, exec, s[0:1]
	v_or_b32_e32 v2, 0x100, v9
	v_cmp_lt_i32_e32 vcc, v2, v1
	s_and_saveexec_b64 s[0:1], vcc
	ds_read_b32 v16, v0 offset:11520
	s_or_b64 exec, exec, s[0:1]
	v_or_b32_e32 v2, 0x200, v9
	v_cmp_lt_i32_e32 vcc, v2, v1
	v_mov_b32_e32 v14, 0
	v_mov_b32_e32 v15, 0
	s_and_saveexec_b64 s[0:1], vcc
	ds_read_b32 v15, v0 offset:12544
	s_or_b64 exec, exec, s[0:1]
	v_or_b32_e32 v2, 0x300, v9
	v_cmp_lt_i32_e32 vcc, v2, v1
	s_and_saveexec_b64 s[0:1], vcc
	ds_read_b32 v14, v0 offset:13568
	s_or_b64 exec, exec, s[0:1]
	v_or_b32_e32 v2, 0x400, v9
	v_cmp_lt_i32_e32 vcc, v2, v1
	v_mov_b32_e32 v12, 0
	v_mov_b32_e32 v13, 0
	s_and_saveexec_b64 s[0:1], vcc
	ds_read_b32 v13, v0 offset:14592
	s_or_b64 exec, exec, s[0:1]
	v_or_b32_e32 v2, 0x500, v9
	v_cmp_lt_i32_e32 vcc, v2, v1
	s_and_saveexec_b64 s[0:1], vcc
	ds_read_b32 v12, v0 offset:15616
	s_or_b64 exec, exec, s[0:1]
	v_or_b32_e32 v2, 0x600, v9
	v_cmp_lt_i32_e32 vcc, v2, v1
	v_mov_b32_e32 v10, 0
	v_mov_b32_e32 v11, 0
	s_and_saveexec_b64 s[0:1], vcc
	ds_read_b32 v11, v0 offset:16640
	s_or_b64 exec, exec, s[0:1]
	v_or_b32_e32 v2, 0x700, v9
	v_cmp_lt_i32_e32 vcc, v2, v1
	s_and_saveexec_b64 s[0:1], vcc
	ds_read_b32 v10, v0 offset:17664
	s_or_b64 exec, exec, s[0:1]
	s_cmp_gt_i32 s84, 1
	s_cbranch_scc1 .LBB0_1436
	s_lshl_b32 s86, s84, 2
	v_mov_b32_e32 v0, s86
	v_add_u32_e32 v20, 0x1800, v0
	ds_read2_b32 v[0:1], v20 offset1:2
	ds_read2_b32 v[2:3], v20 offset0:4 offset1:6
	ds_read2_b32 v[4:5], v20 offset0:8 offset1:10
	ds_read2_b32 v[6:7], v20 offset0:12 offset1:14
	ds_read2_b32 v[18:19], v20 offset0:16 offset1:18
	ds_read2_b32 v[20:21], v20 offset0:20 offset1:22
	ds_read2_b32 v[22:23], v20 offset0:24 offset1:26
	ds_read2_b32 v[24:25], v20 offset0:28 offset1:30
	s_cmp_lt_u32 s83, 64
	s_cselect_b64 vcc, -1, 0
	v_cndmask_b32_e32 v32, v105, v104, vcc
	s_lshl_b32 s0, s84, 13
	v_lshl_add_u32 v50, v8, 2, s0
	v_readfirstlane_b32 s1, v32
	s_waitcnt lgkmcnt(0)
	v_min_u32_e32 v0, v0, v1
	v_min3_u32 v0, v0, v2, v3
	v_min3_u32 v0, v0, v4, v5
	v_min3_u32 v0, v0, v6, v7
	v_max_u32_e32 v1, v18, v19
	v_max3_u32 v1, v1, v20, v21
	v_max3_u32 v1, v1, v22, v23
	v_max3_u32 v1, v1, v24, v25
	s_add_i32 s20, s1, 63
	s_lshr_b32 s20, s20, 6
	v_readfirstlane_b32 s87, v0
	v_readfirstlane_b32 s0, v1
	s_nop 0
	s_sub_u32 s90, s0, s87
	ds_read_b32 v18, v50 offset:10496
	ds_read_b32 v19, v50 offset:10752
	ds_read_b32 v20, v50 offset:11008
	ds_read_b32 v21, v50 offset:11264
	ds_read_b32 v22, v50 offset:11520
	ds_read_b32 v23, v50 offset:11776
	ds_read_b32 v24, v50 offset:12032
	ds_read_b32 v25, v50 offset:12288
	s_cmp_gt_u32 s20, 8
	s_cbranch_scc0 .Lbs_ld_done
	ds_read_b32 v26, v50 offset:12544
	ds_read_b32 v27, v50 offset:12800
	ds_read_b32 v28, v50 offset:13056
	ds_read_b32 v29, v50 offset:13312
	ds_read_b32 v30, v50 offset:13568
	ds_read_b32 v31, v50 offset:13824
	ds_read_b32 v32, v50 offset:14080
	ds_read_b32 v33, v50 offset:14336
	s_cmp_gt_u32 s20, 16
	s_cbranch_scc0 .Lbs_ld_done
	ds_read_b32 v34, v50 offset:14592
	ds_read_b32 v35, v50 offset:14848
	ds_read_b32 v36, v50 offset:15104
	ds_read_b32 v37, v50 offset:15360
	ds_read_b32 v38, v50 offset:15616
	ds_read_b32 v39, v50 offset:15872
	ds_read_b32 v40, v50 offset:16128
	ds_read_b32 v41, v50 offset:16384
	s_cmp_gt_u32 s20, 24
	s_cbranch_scc0 .Lbs_ld_done
	ds_read_b32 v42, v50 offset:16640
	ds_read_b32 v43, v50 offset:16896
	ds_read_b32 v44, v50 offset:17152
	ds_read_b32 v45, v50 offset:17408
	ds_read_b32 v46, v50 offset:17664
	ds_read_b32 v47, v50 offset:17920
	ds_read_b32 v48, v50 offset:18176
	ds_read_b32 v49, v50 offset:18432
